# row pass prefetches next row; Params pointer reloads in epilogue store ladders via s_load + v_mov, no vmcnt drain between stores
# speedup vs baseline: 1.1503x; 1.0085x over previous
; template <int NT, class VF, class RP>
; __device__ __forceinline__ void epi_staged_bf16(f32x4 (&acc)[4][NT], int r0, int c0, unsigned char* smem, VF vf, RP rowptr) {
;     ...
;   for (int i = 0; i < CPR / 2; ++i) {
;     const int c = t + 256 * i, row = c / CPR, ch = c % CPR;
;     u16* d = rowptr(row);
;     if (d) *(u32x4*)(d + ch * 8) = *(const u32x4*)(Ts + row * PITCH + ch * 8);
;   }
; __device__ __forceinline__ void phase_in_gemm(const Params& p, int l, unsigned char* smem) {
;     ...
;       auto rp = [&](int r) -> u16* {
;         const int row = row_base + r;
;         if (nt < 4) return p.PX + (size_t)row * 1024 + nt * 128;
;         if (nt >= 8) return p.PX + (size_t)row * 1024 + 512 + (nt - 8) * 128;
;         const int ri = (nt - 4) >> 1, jx = ((nt - 4) & 1) * 128;
;         if (row < T_LAT) return p.GD + ((size_t)((row >> 13) * 2 + ri) * SEQ + (row & (SEQ - 1))) * 256 + jx;
;         const int rc = row - T_LAT;
;         return p.GDc + ((size_t)((rc >> 8) * 2 + ri) * CTX + (rc & 255)) * 256 + jx;
;       };
.LBB0_315:
	v_cvt_pk_bf16_f32 v2, v5, s0
	ds_write_b16 v0, v2 offset:13968
	v_ashrrev_i32_e32 v0, 31, v66
	v_lshrrev_b32_e32 v0, 28, v0
	v_add_u32_e32 v0, v66, v0
	v_ashrrev_i32_e32 v6, 4, v0
	v_add_u32_e32 v2, s42, v6
	s_mov_b64 s[0:1], -1
	s_and_b64 vcc, exec, s[46:47]
	s_waitcnt lgkmcnt(0)
	s_barrier
	s_cbranch_vccz .LBB0_468
	s_cmp_lt_u32 s40, 8
	s_cbranch_scc0 .LBB0_322
	s_add_i32 s0, s40, -4
	s_lshr_b32 s19, s0, 1
	s_lshl_b32 s0, s40, 7
	s_and_b32 s18, s0, 0x80
	s_movk_i32 s0, 0x3fff
	v_cmp_lt_i32_e32 vcc, s0, v2
	v_lshlrev_b32_e32 v3, 9, v2
	s_and_saveexec_b64 s[0:1], vcc
	s_xor_b64 s[0:1], exec, s[0:1]
	s_cbranch_execz .LBB0_319
	v_mov_b64_e32 v[4:5], s[4:5]
	s_load_dwordx2 s[100:101], s[4:5], 0x138
	s_waitcnt lgkmcnt(0)
	v_mov_b32_e32 v4, s100
	v_mov_b32_e32 v5, s101
	v_add_u32_e32 v0, 0xffffc000, v2
	v_lshrrev_b32_e32 v0, 7, v0
	v_and_b32_e32 v0, 0x1fffffe, v0
	v_add_u32_e32 v0, s19, v0
	v_lshlrev_b64 v[8:9], 17, v[0:1]
	v_and_b32_e32 v0, 0x1fe00, v3
	s_lshl_b32 s94, s18, 1
	s_waitcnt lgkmcnt(0)
	v_lshl_add_u64 v[4:5], v[4:5], 0, v[8:9]
	v_lshl_add_u64 v[4:5], v[4:5], 0, v[0:1]
	v_lshl_add_u64 v[4:5], v[4:5], 0, s[94:95]
.LBB0_319:
	s_andn2_saveexec_b64 s[0:1], s[0:1]
	s_cbranch_execz .LBB0_321
	v_mov_b64_e32 v[4:5], s[4:5]
	s_load_dwordx2 s[100:101], s[4:5], 0x130
	s_waitcnt lgkmcnt(0)
	v_mov_b32_e32 v4, s100
	v_mov_b32_e32 v5, s101
	v_ashrrev_i32_e32 v7, 12, v2
	v_and_b32_e32 v0, 0x3ffe00, v3
	v_and_b32_e32 v3, -2, v7
	v_add_u32_e32 v8, s19, v3
	v_ashrrev_i32_e32 v9, 31, v8
	v_lshlrev_b64 v[8:9], 22, v[8:9]
	s_lshl_b32 s94, s18, 1
	s_waitcnt lgkmcnt(0)
	v_lshl_add_u64 v[4:5], v[4:5], 0, v[8:9]
	v_lshl_add_u64 v[4:5], v[4:5], 0, v[0:1]
	v_lshl_add_u64 v[4:5], v[4:5], 0, s[94:95]

; template <int NT, class VF, class RP>
; __device__ __forceinline__ void epi_staged_bf16(f32x4 (&acc)[4][NT], int r0, int c0, unsigned char* smem, VF vf, RP rowptr) {
;     ...
;   for (int i = 0; i < CPR / 2; ++i) {
;     const int c = t + 256 * i, row = c / CPR, ch = c % CPR;
;     u16* d = rowptr(row);
;     if (d) *(u32x4*)(d + ch * 8) = *(const u32x4*)(Ts + row * PITCH + ch * 8);
;   }
; __device__ __forceinline__ void phase_in_gemm(const Params& p, int l, unsigned char* smem) {
;     ...
;         if (nt >= 8) return p.PX + (size_t)row * 1024 + 512 + (nt - 8) * 128;
.LBB0_322:
	s_andn2_b64 vcc, exec, s[0:1]
	s_cbranch_vccnz .LBB0_324
	v_mov_b64_e32 v[4:5], s[4:5]
	s_load_dwordx2 s[100:101], s[4:5], 0x120
	s_waitcnt lgkmcnt(0)
	v_mov_b32_e32 v4, s100
	v_mov_b32_e32 v5, s101
	v_ashrrev_i32_e32 v3, 31, v2
	v_lshlrev_b64 v[8:9], 11, v[2:3]
	s_lshl_b32 s94, s40, 8
	s_movk_i32 s0, 0xfc00
	s_mov_b32 s1, -1
	s_waitcnt lgkmcnt(0)
	v_lshl_add_u64 v[4:5], v[4:5], 0, v[8:9]
	v_lshl_add_u64 v[4:5], v[4:5], 0, s[94:95]
	v_lshl_add_u64 v[4:5], v[4:5], 0, s[0:1]

; template <int NT, class VF, class RP>
; __device__ __forceinline__ void epi_staged_bf16(f32x4 (&acc)[4][NT], int r0, int c0, unsigned char* smem, VF vf, RP rowptr) {
;     ...
;   for (int i = 0; i < CPR / 2; ++i) {
;     const int c = t + 256 * i, row = c / CPR, ch = c % CPR;
;     u16* d = rowptr(row);
;     if (d) *(u32x4*)(d + ch * 8) = *(const u32x4*)(Ts + row * PITCH + ch * 8);
;   }
; __device__ __forceinline__ void phase_in_gemm(const Params& p, int l, unsigned char* smem) {
;     ...
;       auto rp = [&](int r) -> u16* {
;         const int row = row_base + r;
;         if (nt < 4) return p.PX + (size_t)row * 1024 + nt * 128;
;         if (nt >= 8) return p.PX + (size_t)row * 1024 + 512 + (nt - 8) * 128;
;         const int ri = (nt - 4) >> 1, jx = ((nt - 4) & 1) * 128;
;         if (row < T_LAT) return p.GD + ((size_t)((row >> 13) * 2 + ri) * SEQ + (row & (SEQ - 1))) * 256 + jx;
;         const int rc = row - T_LAT;
;         return p.GDc + ((size_t)((rc >> 8) * 2 + ri) * CTX + (rc & 255)) * 256 + jx;
;       };
.LBB0_327:
	s_or_b64 exec, exec, s[0:1]
	s_nop 0
	v_add_u32_e32 v6, 0x100, v66
	v_ashrrev_i32_e32 v0, 31, v6
	v_lshrrev_b32_e32 v0, 28, v0
	v_add_u32_e32 v0, v6, v0
	v_ashrrev_i32_e32 v7, 4, v0
	v_cndmask_b32_e64 v0, 0, 1, s[46:47]
	v_add_u32_e32 v2, s42, v7
	v_cmp_ne_u32_e64 s[38:39], 1, v0
	s_andn2_b64 vcc, exec, s[46:47]
	s_mov_b64 s[0:1], -1
	s_cbranch_vccnz .LBB0_470
	s_cmp_gt_u32 s40, 7
	s_cbranch_scc1 .LBB0_334
	s_add_i32 s0, s40, -4
	s_lshr_b32 s19, s0, 1
	s_lshl_b32 s0, s40, 7
	s_and_b32 s18, s0, 0x80
	s_movk_i32 s0, 0x3fff
	v_cmp_lt_i32_e32 vcc, s0, v2
	v_lshlrev_b32_e32 v3, 9, v2
	s_and_saveexec_b64 s[0:1], vcc
	s_xor_b64 s[0:1], exec, s[0:1]
	s_cbranch_execz .LBB0_331
	v_mov_b64_e32 v[4:5], s[4:5]
	s_load_dwordx2 s[100:101], s[4:5], 0x138
	s_waitcnt lgkmcnt(0)
	v_mov_b32_e32 v4, s100
	v_mov_b32_e32 v5, s101
	v_add_u32_e32 v0, 0xffffc000, v2
	v_lshrrev_b32_e32 v0, 7, v0
	v_and_b32_e32 v0, 0x1fffffe, v0
	v_add_u32_e32 v0, s19, v0
	v_lshlrev_b64 v[8:9], 17, v[0:1]
	v_and_b32_e32 v0, 0x1fe00, v3
	s_lshl_b32 s94, s18, 1
	s_waitcnt lgkmcnt(0)
	v_lshl_add_u64 v[4:5], v[4:5], 0, v[8:9]
	v_lshl_add_u64 v[4:5], v[4:5], 0, v[0:1]
	v_lshl_add_u64 v[4:5], v[4:5], 0, s[94:95]
.LBB0_331:
	s_andn2_saveexec_b64 s[0:1], s[0:1]
	s_cbranch_execz .LBB0_333
	v_mov_b64_e32 v[4:5], s[4:5]
	s_load_dwordx2 s[100:101], s[4:5], 0x130
	s_waitcnt lgkmcnt(0)
	v_mov_b32_e32 v4, s100
	v_mov_b32_e32 v5, s101
	v_ashrrev_i32_e32 v8, 12, v2
	v_and_b32_e32 v0, 0x3ffe00, v3
	v_and_b32_e32 v3, -2, v8
	v_add_u32_e32 v8, s19, v3
	v_ashrrev_i32_e32 v9, 31, v8
	v_lshlrev_b64 v[8:9], 22, v[8:9]
	s_lshl_b32 s94, s18, 1
	s_waitcnt lgkmcnt(0)
	v_lshl_add_u64 v[4:5], v[4:5], 0, v[8:9]
	v_lshl_add_u64 v[4:5], v[4:5], 0, v[0:1]
	v_lshl_add_u64 v[4:5], v[4:5], 0, s[94:95]

; template <int NT, class VF, class RP>
; __device__ __forceinline__ void epi_staged_bf16(f32x4 (&acc)[4][NT], int r0, int c0, unsigned char* smem, VF vf, RP rowptr) {
;     ...
;   for (int i = 0; i < CPR / 2; ++i) {
;     const int c = t + 256 * i, row = c / CPR, ch = c % CPR;
;     u16* d = rowptr(row);
;     if (d) *(u32x4*)(d + ch * 8) = *(const u32x4*)(Ts + row * PITCH + ch * 8);
;   }
; __device__ __forceinline__ void phase_in_gemm(const Params& p, int l, unsigned char* smem) {
;     ...
;       auto rp = [&](int r) -> u16* {
;         const int row = row_base + r;
;         if (nt < 4) return p.PX + (size_t)row * 1024 + nt * 128;
;         if (nt >= 8) return p.PX + (size_t)row * 1024 + 512 + (nt - 8) * 128;
;         const int ri = (nt - 4) >> 1, jx = ((nt - 4) & 1) * 128;
;         if (row < T_LAT) return p.GD + ((size_t)((row >> 13) * 2 + ri) * SEQ + (row & (SEQ - 1))) * 256 + jx;
;         const int rc = row - T_LAT;
;         return p.GDc + ((size_t)((rc >> 8) * 2 + ri) * CTX + (rc & 255)) * 256 + jx;
;       };
.LBB0_339:
	s_or_b64 exec, exec, s[0:1]
	s_nop 0
	v_add_u32_e32 v6, 0x200, v66
	v_ashrrev_i32_e32 v0, 31, v6
	v_lshrrev_b32_e32 v0, 28, v0
	v_add_u32_e32 v0, v6, v0
	v_ashrrev_i32_e32 v7, 4, v0
	v_add_u32_e32 v2, s42, v7
	s_and_b64 vcc, exec, s[38:39]
	s_mov_b64 s[0:1], -1
	s_cbranch_vccnz .LBB0_472
	s_cmp_gt_u32 s40, 7
	s_cbranch_scc1 .LBB0_346
	s_add_i32 s0, s40, -4
	s_lshr_b32 s19, s0, 1
	s_lshl_b32 s0, s40, 7
	s_and_b32 s18, s0, 0x80
	s_movk_i32 s0, 0x3fff
	v_cmp_lt_i32_e32 vcc, s0, v2
	v_lshlrev_b32_e32 v3, 9, v2
	s_and_saveexec_b64 s[0:1], vcc
	s_xor_b64 s[0:1], exec, s[0:1]
	s_cbranch_execz .LBB0_343
	v_mov_b64_e32 v[4:5], s[4:5]
	s_load_dwordx2 s[100:101], s[4:5], 0x138
	s_waitcnt lgkmcnt(0)
	v_mov_b32_e32 v4, s100
	v_mov_b32_e32 v5, s101
	v_add_u32_e32 v0, 0xffffc000, v2
	v_lshrrev_b32_e32 v0, 7, v0
	v_and_b32_e32 v0, 0x1fffffe, v0
	v_add_u32_e32 v0, s19, v0
	v_lshlrev_b64 v[8:9], 17, v[0:1]
	v_and_b32_e32 v0, 0x1fe00, v3
	s_lshl_b32 s94, s18, 1
	s_waitcnt lgkmcnt(0)
	v_lshl_add_u64 v[4:5], v[4:5], 0, v[8:9]
	v_lshl_add_u64 v[4:5], v[4:5], 0, v[0:1]
	v_lshl_add_u64 v[4:5], v[4:5], 0, s[94:95]

; template <int NT, class VF, class RP>
; __device__ __forceinline__ void epi_staged_bf16(f32x4 (&acc)[4][NT], int r0, int c0, unsigned char* smem, VF vf, RP rowptr) {
;     ...
;   for (int i = 0; i < CPR / 2; ++i) {
;     const int c = t + 256 * i, row = c / CPR, ch = c % CPR;
;     u16* d = rowptr(row);
;     if (d) *(u32x4*)(d + ch * 8) = *(const u32x4*)(Ts + row * PITCH + ch * 8);
;   }
; __device__ __forceinline__ void phase_in_gemm(const Params& p, int l, unsigned char* smem) {
;     ...
;       auto rp = [&](int r) -> u16* {
;         const int row = row_base + r;
;         if (nt < 4) return p.PX + (size_t)row * 1024 + nt * 128;
;         if (nt >= 8) return p.PX + (size_t)row * 1024 + 512 + (nt - 8) * 128;
;         const int ri = (nt - 4) >> 1, jx = ((nt - 4) & 1) * 128;
;         if (row < T_LAT) return p.GD + ((size_t)((row >> 13) * 2 + ri) * SEQ + (row & (SEQ - 1))) * 256 + jx;
;         const int rc = row - T_LAT;
;         return p.GDc + ((size_t)((rc >> 8) * 2 + ri) * CTX + (rc & 255)) * 256 + jx;
;       };
.LBB0_351:
	s_or_b64 exec, exec, s[0:1]
	s_nop 0
	v_add_u32_e32 v6, 0x300, v66
	v_ashrrev_i32_e32 v0, 31, v6
	v_lshrrev_b32_e32 v0, 28, v0
	v_add_u32_e32 v0, v6, v0
	v_ashrrev_i32_e32 v7, 4, v0
	v_add_u32_e32 v2, s42, v7
	s_and_b64 vcc, exec, s[38:39]
	s_mov_b64 s[0:1], -1
	s_cbranch_vccnz .LBB0_474
	s_cmp_gt_u32 s40, 7
	s_cbranch_scc1 .LBB0_358
	s_add_i32 s0, s40, -4
	s_lshr_b32 s19, s0, 1
	s_lshl_b32 s0, s40, 7
	s_and_b32 s18, s0, 0x80
	s_movk_i32 s0, 0x3fff
	v_cmp_lt_i32_e32 vcc, s0, v2
	v_lshlrev_b32_e32 v3, 9, v2
	s_and_saveexec_b64 s[0:1], vcc
	s_xor_b64 s[0:1], exec, s[0:1]
	s_cbranch_execz .LBB0_355
	v_mov_b64_e32 v[4:5], s[4:5]
	s_load_dwordx2 s[100:101], s[4:5], 0x138
	s_waitcnt lgkmcnt(0)
	v_mov_b32_e32 v4, s100
	v_mov_b32_e32 v5, s101
	v_add_u32_e32 v0, 0xffffc000, v2
	v_lshrrev_b32_e32 v0, 7, v0
	v_and_b32_e32 v0, 0x1fffffe, v0
	v_add_u32_e32 v0, s19, v0
	v_lshlrev_b64 v[8:9], 17, v[0:1]
	v_and_b32_e32 v0, 0x1fe00, v3
	s_lshl_b32 s94, s18, 1
	s_waitcnt lgkmcnt(0)
	v_lshl_add_u64 v[4:5], v[4:5], 0, v[8:9]
	v_lshl_add_u64 v[4:5], v[4:5], 0, v[0:1]
	v_lshl_add_u64 v[4:5], v[4:5], 0, s[94:95]

; template <int NT, class VF, class RP>
; __device__ __forceinline__ void epi_staged_bf16(f32x4 (&acc)[4][NT], int r0, int c0, unsigned char* smem, VF vf, RP rowptr) {
;     ...
;   for (int i = 0; i < CPR / 2; ++i) {
;     const int c = t + 256 * i, row = c / CPR, ch = c % CPR;
;     u16* d = rowptr(row);
;     if (d) *(u32x4*)(d + ch * 8) = *(const u32x4*)(Ts + row * PITCH + ch * 8);
;   }
; __device__ __forceinline__ void phase_in_gemm(const Params& p, int l, unsigned char* smem) {
;     ...
;       auto rp = [&](int r) -> u16* {
;         const int row = row_base + r;
;         if (nt < 4) return p.PX + (size_t)row * 1024 + nt * 128;
;         if (nt >= 8) return p.PX + (size_t)row * 1024 + 512 + (nt - 8) * 128;
;         const int ri = (nt - 4) >> 1, jx = ((nt - 4) & 1) * 128;
;         if (row < T_LAT) return p.GD + ((size_t)((row >> 13) * 2 + ri) * SEQ + (row & (SEQ - 1))) * 256 + jx;
;         const int rc = row - T_LAT;
;         return p.GDc + ((size_t)((rc >> 8) * 2 + ri) * CTX + (rc & 255)) * 256 + jx;
;       };
.LBB0_363:
	s_or_b64 exec, exec, s[0:1]
	s_nop 0
	v_add_u32_e32 v6, 0x400, v66
	v_ashrrev_i32_e32 v0, 31, v6
	v_lshrrev_b32_e32 v0, 28, v0
	v_add_u32_e32 v0, v6, v0
	v_ashrrev_i32_e32 v7, 4, v0
	v_add_u32_e32 v2, s42, v7
	s_and_b64 vcc, exec, s[38:39]
	s_mov_b64 s[0:1], -1
	s_cbranch_vccnz .LBB0_476
	s_cmp_gt_u32 s40, 7
	s_cbranch_scc1 .LBB0_370
	s_add_i32 s0, s40, -4
	s_lshr_b32 s19, s0, 1
	s_lshl_b32 s0, s40, 7
	s_and_b32 s18, s0, 0x80
	s_movk_i32 s0, 0x3fff
	v_cmp_lt_i32_e32 vcc, s0, v2
	v_lshlrev_b32_e32 v3, 9, v2
	s_and_saveexec_b64 s[0:1], vcc
	s_xor_b64 s[0:1], exec, s[0:1]
	s_cbranch_execz .LBB0_367
	v_mov_b64_e32 v[4:5], s[4:5]
	s_load_dwordx2 s[100:101], s[4:5], 0x138
	s_waitcnt lgkmcnt(0)
	v_mov_b32_e32 v4, s100
	v_mov_b32_e32 v5, s101
	v_add_u32_e32 v0, 0xffffc000, v2
	v_lshrrev_b32_e32 v0, 7, v0
	v_and_b32_e32 v0, 0x1fffffe, v0
	v_add_u32_e32 v0, s19, v0
	v_lshlrev_b64 v[8:9], 17, v[0:1]
	v_and_b32_e32 v0, 0x1fe00, v3
	s_lshl_b32 s94, s18, 1
	s_waitcnt lgkmcnt(0)
	v_lshl_add_u64 v[4:5], v[4:5], 0, v[8:9]
	v_lshl_add_u64 v[4:5], v[4:5], 0, v[0:1]
	v_lshl_add_u64 v[4:5], v[4:5], 0, s[94:95]

; template <int NT, class VF, class RP>
; __device__ __forceinline__ void epi_staged_bf16(f32x4 (&acc)[4][NT], int r0, int c0, unsigned char* smem, VF vf, RP rowptr) {
;     ...
;   for (int i = 0; i < CPR / 2; ++i) {
;     const int c = t + 256 * i, row = c / CPR, ch = c % CPR;
;     u16* d = rowptr(row);
;     if (d) *(u32x4*)(d + ch * 8) = *(const u32x4*)(Ts + row * PITCH + ch * 8);
;   }
; __device__ __forceinline__ void phase_in_gemm(const Params& p, int l, unsigned char* smem) {
;     ...
;       auto rp = [&](int r) -> u16* {
;         const int row = row_base + r;
;         if (nt < 4) return p.PX + (size_t)row * 1024 + nt * 128;
;         if (nt >= 8) return p.PX + (size_t)row * 1024 + 512 + (nt - 8) * 128;
;         const int ri = (nt - 4) >> 1, jx = ((nt - 4) & 1) * 128;
;         if (row < T_LAT) return p.GD + ((size_t)((row >> 13) * 2 + ri) * SEQ + (row & (SEQ - 1))) * 256 + jx;
;         const int rc = row - T_LAT;
;         return p.GDc + ((size_t)((rc >> 8) * 2 + ri) * CTX + (rc & 255)) * 256 + jx;
;       };
.LBB0_375:
	s_or_b64 exec, exec, s[0:1]
	s_nop 0
	v_add_u32_e32 v6, 0x500, v66
	v_ashrrev_i32_e32 v0, 31, v6
	v_lshrrev_b32_e32 v0, 28, v0
	v_add_u32_e32 v0, v6, v0
	v_ashrrev_i32_e32 v7, 4, v0
	v_add_u32_e32 v2, s42, v7
	s_and_b64 vcc, exec, s[38:39]
	s_mov_b64 s[0:1], -1
	s_cbranch_vccnz .LBB0_478
	s_cmp_gt_u32 s40, 7
	s_cbranch_scc1 .LBB0_382
	s_add_i32 s0, s40, -4
	s_lshr_b32 s19, s0, 1
	s_lshl_b32 s0, s40, 7
	s_and_b32 s18, s0, 0x80
	s_movk_i32 s0, 0x3fff
	v_cmp_lt_i32_e32 vcc, s0, v2
	v_lshlrev_b32_e32 v3, 9, v2
	s_and_saveexec_b64 s[0:1], vcc
	s_xor_b64 s[0:1], exec, s[0:1]
	s_cbranch_execz .LBB0_379
	v_mov_b64_e32 v[4:5], s[4:5]
	s_load_dwordx2 s[100:101], s[4:5], 0x138
	s_waitcnt lgkmcnt(0)
	v_mov_b32_e32 v4, s100
	v_mov_b32_e32 v5, s101
	v_add_u32_e32 v0, 0xffffc000, v2
	v_lshrrev_b32_e32 v0, 7, v0
	v_and_b32_e32 v0, 0x1fffffe, v0
	v_add_u32_e32 v0, s19, v0
	v_lshlrev_b64 v[8:9], 17, v[0:1]
	v_and_b32_e32 v0, 0x1fe00, v3
	s_lshl_b32 s94, s18, 1
	s_waitcnt lgkmcnt(0)
	v_lshl_add_u64 v[4:5], v[4:5], 0, v[8:9]
	v_lshl_add_u64 v[4:5], v[4:5], 0, v[0:1]
	v_lshl_add_u64 v[4:5], v[4:5], 0, s[94:95]

; template <int NT, class VF, class RP>
; __device__ __forceinline__ void epi_staged_bf16(f32x4 (&acc)[4][NT], int r0, int c0, unsigned char* smem, VF vf, RP rowptr) {
;     ...
;   for (int i = 0; i < CPR / 2; ++i) {
;     const int c = t + 256 * i, row = c / CPR, ch = c % CPR;
;     u16* d = rowptr(row);
;     if (d) *(u32x4*)(d + ch * 8) = *(const u32x4*)(Ts + row * PITCH + ch * 8);
;   }
; __device__ __forceinline__ void phase_in_gemm(const Params& p, int l, unsigned char* smem) {
;     ...
;       auto rp = [&](int r) -> u16* {
;         const int row = row_base + r;
;         if (nt < 4) return p.PX + (size_t)row * 1024 + nt * 128;
;         if (nt >= 8) return p.PX + (size_t)row * 1024 + 512 + (nt - 8) * 128;
;         const int ri = (nt - 4) >> 1, jx = ((nt - 4) & 1) * 128;
;         if (row < T_LAT) return p.GD + ((size_t)((row >> 13) * 2 + ri) * SEQ + (row & (SEQ - 1))) * 256 + jx;
;         const int rc = row - T_LAT;
;         return p.GDc + ((size_t)((rc >> 8) * 2 + ri) * CTX + (rc & 255)) * 256 + jx;
;       };
.LBB0_387:
	s_or_b64 exec, exec, s[0:1]
	s_nop 0
	v_add_u32_e32 v6, 0x600, v66
	v_ashrrev_i32_e32 v0, 31, v6
	v_lshrrev_b32_e32 v0, 28, v0
	v_add_u32_e32 v0, v6, v0
	v_ashrrev_i32_e32 v7, 4, v0
	v_add_u32_e32 v2, s42, v7
	s_and_b64 vcc, exec, s[38:39]
	s_mov_b64 s[0:1], -1
	s_cbranch_vccnz .LBB0_480
	s_cmp_gt_u32 s40, 7
	s_cbranch_scc1 .LBB0_394
	s_add_i32 s0, s40, -4
	s_lshr_b32 s19, s0, 1
	s_lshl_b32 s0, s40, 7
	s_and_b32 s18, s0, 0x80
	s_movk_i32 s0, 0x3fff
	v_cmp_lt_i32_e32 vcc, s0, v2
	v_lshlrev_b32_e32 v3, 9, v2
	s_and_saveexec_b64 s[0:1], vcc
	s_xor_b64 s[0:1], exec, s[0:1]
	s_cbranch_execz .LBB0_391
	v_mov_b64_e32 v[4:5], s[4:5]
	s_load_dwordx2 s[100:101], s[4:5], 0x138
	s_waitcnt lgkmcnt(0)
	v_mov_b32_e32 v4, s100
	v_mov_b32_e32 v5, s101
	v_add_u32_e32 v0, 0xffffc000, v2
	v_lshrrev_b32_e32 v0, 7, v0
	v_and_b32_e32 v0, 0x1fffffe, v0
	v_add_u32_e32 v0, s19, v0
	v_lshlrev_b64 v[8:9], 17, v[0:1]
	v_and_b32_e32 v0, 0x1fe00, v3
	s_lshl_b32 s94, s18, 1
	s_waitcnt lgkmcnt(0)
	v_lshl_add_u64 v[4:5], v[4:5], 0, v[8:9]
	v_lshl_add_u64 v[4:5], v[4:5], 0, v[0:1]
	v_lshl_add_u64 v[4:5], v[4:5], 0, s[94:95]

; template <int NT, class VF, class RP>
; __device__ __forceinline__ void epi_staged_bf16(f32x4 (&acc)[4][NT], int r0, int c0, unsigned char* smem, VF vf, RP rowptr) {
;     ...
;   for (int i = 0; i < CPR / 2; ++i) {
;     const int c = t + 256 * i, row = c / CPR, ch = c % CPR;
;     u16* d = rowptr(row);
;     if (d) *(u32x4*)(d + ch * 8) = *(const u32x4*)(Ts + row * PITCH + ch * 8);
;   }
; __device__ __forceinline__ void phase_in_gemm(const Params& p, int l, unsigned char* smem) {
;     ...
;       auto rp = [&](int r) -> u16* {
;         const int row = row_base + r;
;         if (nt < 4) return p.PX + (size_t)row * 1024 + nt * 128;
;         if (nt >= 8) return p.PX + (size_t)row * 1024 + 512 + (nt - 8) * 128;
;         const int ri = (nt - 4) >> 1, jx = ((nt - 4) & 1) * 128;
;         if (row < T_LAT) return p.GD + ((size_t)((row >> 13) * 2 + ri) * SEQ + (row & (SEQ - 1))) * 256 + jx;
;         const int rc = row - T_LAT;
;         return p.GDc + ((size_t)((rc >> 8) * 2 + ri) * CTX + (rc & 255)) * 256 + jx;
;       };
.LBB0_399:
	s_or_b64 exec, exec, s[0:1]
	s_nop 0
	v_add_u32_e32 v6, 0x700, v66
	v_ashrrev_i32_e32 v0, 31, v6
	v_lshrrev_b32_e32 v0, 28, v0
	v_add_u32_e32 v0, v6, v0
	v_ashrrev_i32_e32 v7, 4, v0
	v_add_u32_e32 v2, s42, v7
	s_and_b64 vcc, exec, s[38:39]
	s_mov_b64 s[0:1], -1
	s_cbranch_vccnz .LBB0_482
	s_cmp_gt_u32 s40, 7
	s_cbranch_scc1 .LBB0_406
	s_add_i32 s0, s40, -4
	s_lshr_b32 s19, s0, 1
	s_lshl_b32 s0, s40, 7
	s_and_b32 s18, s0, 0x80
	s_movk_i32 s0, 0x3fff
	v_cmp_lt_i32_e32 vcc, s0, v2
	v_lshlrev_b32_e32 v3, 9, v2
	s_and_saveexec_b64 s[0:1], vcc
	s_xor_b64 s[0:1], exec, s[0:1]
	s_cbranch_execz .LBB0_403
	v_mov_b64_e32 v[4:5], s[4:5]
	s_load_dwordx2 s[100:101], s[4:5], 0x138
	s_waitcnt lgkmcnt(0)
	v_mov_b32_e32 v4, s100
	v_mov_b32_e32 v5, s101
	v_add_u32_e32 v0, 0xffffc000, v2
	v_lshrrev_b32_e32 v0, 7, v0
	v_and_b32_e32 v0, 0x1fffffe, v0
	v_add_u32_e32 v0, s19, v0
	v_lshlrev_b64 v[8:9], 17, v[0:1]
	v_and_b32_e32 v0, 0x1fe00, v3
	s_lshl_b32 s94, s18, 1
	s_waitcnt lgkmcnt(0)
	v_lshl_add_u64 v[4:5], v[4:5], 0, v[8:9]
	v_lshl_add_u64 v[4:5], v[4:5], 0, v[0:1]
	v_lshl_add_u64 v[4:5], v[4:5], 0, s[94:95]

; template <int NT, class VF, class RP>
; __device__ __forceinline__ void epi_staged_bf16(f32x4 (&acc)[4][NT], int r0, int c0, unsigned char* smem, VF vf, RP rowptr) {
;     ...
;   for (int i = 0; i < CPR / 2; ++i) {
;     const int c = t + 256 * i, row = c / CPR, ch = c % CPR;
;     u16* d = rowptr(row);
;     if (d) *(u32x4*)(d + ch * 8) = *(const u32x4*)(Ts + row * PITCH + ch * 8);
;   }
; __device__ __forceinline__ void phase_in_gemm(const Params& p, int l, unsigned char* smem) {
;     ...
;         if (nt < 4) return p.PX + (size_t)row * 1024 + nt * 128;
.LBB0_469:
	v_mov_b64_e32 v[4:5], s[4:5]
	s_load_dwordx2 s[100:101], s[4:5], 0x120
	s_waitcnt lgkmcnt(0)
	v_mov_b32_e32 v4, s100
	v_mov_b32_e32 v5, s101
	v_ashrrev_i32_e32 v3, 31, v2
	s_lshl_b32 s0, s40, 7
	v_lshlrev_b64 v[2:3], 11, v[2:3]
	s_ashr_i32 s1, s0, 31
	s_waitcnt lgkmcnt(0)
	v_lshl_add_u64 v[2:3], v[4:5], 0, v[2:3]
	v_lshl_add_u64 v[4:5], s[0:1], 1, v[2:3]
	v_cmp_ne_u64_e32 vcc, 0, v[4:5]
	s_and_saveexec_b64 s[0:1], vcc
	s_cbranch_execnz .LBB0_326
	s_branch .LBB0_327

; template <int NT, class VF, class RP>
; __device__ __forceinline__ void epi_staged_bf16(f32x4 (&acc)[4][NT], int r0, int c0, unsigned char* smem, VF vf, RP rowptr) {
;     ...
;   for (int i = 0; i < CPR / 2; ++i) {
;     const int c = t + 256 * i, row = c / CPR, ch = c % CPR;
;     u16* d = rowptr(row);
;     if (d) *(u32x4*)(d + ch * 8) = *(const u32x4*)(Ts + row * PITCH + ch * 8);
;   }
; __device__ __forceinline__ void phase_in_gemm(const Params& p, int l, unsigned char* smem) {
;     ...
;         if (nt < 4) return p.PX + (size_t)row * 1024 + nt * 128;
.LBB0_483:
	v_mov_b64_e32 v[4:5], s[4:5]
	s_load_dwordx2 s[100:101], s[4:5], 0x120
	s_waitcnt lgkmcnt(0)
	v_mov_b32_e32 v4, s100
	v_mov_b32_e32 v5, s101
	v_ashrrev_i32_e32 v3, 31, v2
	s_lshl_b32 s0, s40, 7
	v_lshlrev_b64 v[2:3], 11, v[2:3]
	s_ashr_i32 s1, s0, 31
	s_waitcnt lgkmcnt(0)
	v_lshl_add_u64 v[2:3], v[4:5], 0, v[2:3]
	v_lshl_add_u64 v[4:5], s[0:1], 1, v[2:3]
	v_cmp_ne_u64_e32 vcc, 0, v[4:5]
	s_and_saveexec_b64 s[0:1], vcc
	s_cbranch_execz .LBB0_242

; template <int NT, bool BKN, bool MASK = false, bool ROWSS = false, class Epi> ...
;     ...
;   for (int kt = 0; kt < nk - 2; kt += 2) {
;     GEMM_COMPUTE(0);
;     GEMM_STORE(ra1, rb1, 1);
;     GEMM_LOAD(ra1, rb1, kt + 3);
;     __syncthreads();
;     GEMM_COMPUTE(1);
;     GEMM_STORE(ra0, rb0, 0);
;     GEMM_LOAD(ra0, rb0, (kt + 4 < nkm1 ? kt + 4 : nkm1));
;     __syncthreads();
;   }
.LBB0_488:
	s_nop 0
	ds_read_b128 v[112:115], v109
	ds_read_b128 v[116:119], v109 offset:2048
	ds_read_b128 v[120:123], v109 offset:4096
	ds_read_b128 v[124:127], v109 offset:6144
	ds_read_b128 v[128:131], v108 offset:16384
	ds_read_b128 v[132:135], v108 offset:18432
	s_mov_b32 s9, 0x2c0000
	s_add_i32 s8, s8, 2
	s_waitcnt lgkmcnt(0)
	v_mfma_f32_16x16x32_bf16 v[78:81], v[112:115], v[128:131], v[78:81]
	s_waitcnt lgkmcnt(0)
	v_mfma_f32_16x16x32_bf16 v[74:77], v[112:115], v[132:135], v[74:77]
	v_mfma_f32_16x16x32_bf16 v[70:73], v[116:119], v[128:131], v[70:73]
	v_mfma_f32_16x16x32_bf16 v[66:69], v[116:119], v[132:135], v[66:69]
	v_mfma_f32_16x16x32_bf16 v[62:65], v[120:123], v[128:131], v[62:65]
	v_mfma_f32_16x16x32_bf16 v[58:61], v[120:123], v[132:135], v[58:61]
	v_mfma_f32_16x16x32_bf16 v[112:115], v[124:127], v[128:131], v[54:57]
	v_mfma_f32_16x16x32_bf16 v[116:119], v[124:127], v[132:135], v[50:53]
	s_nop 2
	ds_read_b128 v[50:53], v107
	ds_read_b128 v[54:57], v107 offset:2048
	ds_read_b128 v[120:123], v107 offset:4096
	ds_read_b128 v[124:127], v107 offset:6144
	ds_read_b128 v[128:131], v106 offset:16384
	ds_read_b128 v[132:135], v106 offset:18432
	s_waitcnt vmcnt(0)
	ds_write_b128 v110, v[2:5] offset:32768
	ds_write_b128 v110, v[10:13] offset:36864
	ds_write_b128 v110, v[14:17] offset:40960
	ds_write_b128 v110, v[18:21] offset:45056
	ds_write_b128 v110, v[6:9] offset:49152
	ds_write_b128 v110, v[22:25] offset:53248
	v_lshl_add_u64 v[6:7], v[100:101], 0, v[0:1]
	v_add_co_u32_e32 v8, vcc, s15, v6
	global_load_dwordx4 v[2:5], v[6:7], off offset:384
	s_nop 0
	v_addc_co_u32_e32 v9, vcc, 0, v7, vcc
	global_load_dwordx4 v[10:13], v[8:9], off offset:384
	v_add_co_u32_e32 v8, vcc, s16, v6
	v_lshl_add_u64 v[22:23], v[98:99], 0, v[0:1]
	s_nop 0
	v_addc_co_u32_e32 v9, vcc, 0, v7, vcc
	v_add_co_u32_e32 v6, vcc, s17, v6
	global_load_dwordx4 v[14:17], v[8:9], off offset:384
	s_nop 0
	v_addc_co_u32_e32 v7, vcc, 0, v7, vcc
	global_load_dwordx4 v[18:21], v[6:7], off offset:384
	v_add_co_u32_e32 v6, vcc, s9, v22
	s_mov_b32 s9, 0x2d0000
	s_nop 0
	v_addc_co_u32_e32 v7, vcc, 0, v23, vcc
	v_add_co_u32_e32 v22, vcc, s9, v22
	s_waitcnt lgkmcnt(0)
	v_mfma_f32_16x16x32_bf16 v[78:81], v[50:53], v[128:131], v[78:81]
	v_addc_co_u32_e32 v23, vcc, 0, v23, vcc
	global_load_dwordx4 v[6:9], v[6:7], off offset:384
	v_mfma_f32_16x16x32_bf16 v[74:77], v[50:53], v[132:135], v[74:77]
	global_load_dwordx4 v[22:25], v[22:23], off offset:384
	s_waitcnt lgkmcnt(0)
	s_barrier
	v_mfma_f32_16x16x32_bf16 v[70:73], v[54:57], v[128:131], v[70:73]
	s_min_u32 s9, s8, 11
	s_lshl_b32 s94, s9, 7
	v_mfma_f32_16x16x32_bf16 v[66:69], v[54:57], v[132:135], v[66:69]
	v_lshl_add_u64 v[98:99], v[98:99], 0, s[6:7]
	v_lshl_add_u64 v[100:101], v[100:101], 0, s[6:7]
	s_cmp_lt_u32 s8, 12
	v_mfma_f32_16x16x32_bf16 v[50:53], v[120:123], v[128:131], v[62:65]
	v_mfma_f32_16x16x32_bf16 v[54:57], v[120:123], v[132:135], v[58:61]
	v_mfma_f32_16x16x32_bf16 v[58:61], v[124:127], v[128:131], v[112:115]
	v_mfma_f32_16x16x32_bf16 v[62:65], v[124:127], v[132:135], v[116:119]
	s_nop 1
	ds_read_b128 v[112:115], v109 offset:32768
	ds_read_b128 v[116:119], v109 offset:34816
	ds_read_b128 v[120:123], v109 offset:36864
	ds_read_b128 v[124:127], v109 offset:38912
	ds_read_b128 v[128:131], v108 offset:49152
	ds_read_b128 v[132:135], v108 offset:51200
	s_waitcnt lgkmcnt(0)
	v_mfma_f32_16x16x32_bf16 v[78:81], v[112:115], v[128:131], v[78:81]
	v_mfma_f32_16x16x32_bf16 v[74:77], v[112:115], v[132:135], v[74:77]
	v_mfma_f32_16x16x32_bf16 v[70:73], v[116:119], v[128:131], v[70:73]
	v_mfma_f32_16x16x32_bf16 v[66:69], v[116:119], v[132:135], v[66:69]
	v_mfma_f32_16x16x32_bf16 v[50:53], v[120:123], v[128:131], v[50:53]
	v_mfma_f32_16x16x32_bf16 v[54:57], v[120:123], v[132:135], v[54:57]
	v_mfma_f32_16x16x32_bf16 v[112:115], v[124:127], v[128:131], v[58:61]
	v_mfma_f32_16x16x32_bf16 v[116:119], v[124:127], v[132:135], v[62:65]
	s_nop 1
	ds_read_b128 v[58:61], v107 offset:32768
	ds_read_b128 v[62:65], v107 offset:34816
	ds_read_b128 v[120:123], v107 offset:36864
	ds_read_b128 v[124:127], v107 offset:38912
	ds_read_b128 v[128:131], v106 offset:49152
	ds_read_b128 v[132:135], v106 offset:51200
	ds_write_b128 v110, v[26:29]
	ds_write_b128 v110, v[34:37] offset:4096
	ds_write_b128 v110, v[38:41] offset:8192
	ds_write_b128 v110, v[42:45] offset:12288
	ds_write_b128 v110, v[30:33] offset:16384
	ds_write_b128 v110, v[46:49] offset:20480
	v_lshl_add_u64 v[26:27], v[90:91], 0, s[94:95]
	v_lshl_add_u64 v[30:31], v[92:93], 0, s[94:95]
	global_load_dwordx4 v[26:29], v[26:27], off offset:512
	v_lshl_add_u64 v[46:47], v[88:89], 0, s[94:95]
	global_load_dwordx4 v[34:37], v[30:31], off offset:512
	v_lshl_add_u64 v[30:31], v[94:95], 0, s[94:95]
	global_load_dwordx4 v[38:41], v[30:31], off offset:512
	v_lshl_add_u64 v[30:31], v[96:97], 0, s[94:95]
	global_load_dwordx4 v[42:45], v[30:31], off offset:512
	v_lshl_add_u64 v[30:31], v[86:87], 0, s[94:95]
	global_load_dwordx4 v[30:33], v[30:31], off offset:512
	s_waitcnt lgkmcnt(0)
	v_mfma_f32_16x16x32_bf16 v[78:81], v[58:61], v[128:131], v[78:81]
	global_load_dwordx4 v[46:49], v[46:47], off offset:512
	s_waitcnt lgkmcnt(0)
	s_barrier
	v_mfma_f32_16x16x32_bf16 v[74:77], v[58:61], v[132:135], v[74:77]
	v_mfma_f32_16x16x32_bf16 v[70:73], v[62:65], v[128:131], v[70:73]
	v_mfma_f32_16x16x32_bf16 v[66:69], v[62:65], v[132:135], v[66:69]
	v_mfma_f32_16x16x32_bf16 v[62:65], v[120:123], v[128:131], v[50:53]
	v_mfma_f32_16x16x32_bf16 v[58:61], v[120:123], v[132:135], v[54:57]
	v_mfma_f32_16x16x32_bf16 v[54:57], v[124:127], v[128:131], v[112:115]
	v_mfma_f32_16x16x32_bf16 v[50:53], v[124:127], v[132:135], v[116:119]
	s_cbranch_scc1 .LBB0_488
; __device__ __forceinline__ u16 f2bf(float f) { return (u16)(pack2(f, 0.f) & 0xffffu); }
; __device__ __forceinline__ int tid_() { int t = threadIdx.x; asm volatile("" : "+v"(t)); return t; }
; template <int NT, bool BKN, bool MASK = false, bool ROWSS = false, class Epi> ...
;     ...
;   GEMM_COMPUTE(0);
;   GEMM_STORE(ra1, rb1, 1);
;   __syncthreads();
;   GEMM_COMPUTE(1);
;     ...
;   epi(acc, wr * 64 + quad * 4, wc * (BN / 2) + l16);
; }
; template <int NT, class VF, class RP>
; __device__ __forceinline__ void epi_staged_bf16(f32x4 (&acc)[4][NT], int r0, int c0, unsigned char* smem, VF vf, RP rowptr) {
;   constexpr int BN = NT * 32, PITCH = BN + 8, CPR = BN / 8;
;   u16* Ts = (u16*)smem;
;   const int t = tid_();
;   __syncthreads();
; #pragma unroll
;   for (int mi = 0; mi < 4; ++mi)
; #pragma unroll
;     for (int ni = 0; ni < NT; ++ni)
; #pragma unroll
;       for (int j = 0; j < 4; ++j) {
;         const int r = r0 + mi * 16 + j, c = c0 + ni * 16;
;         Ts[r * PITCH + c] = f2bf(vf(r, c, acc[mi][ni][j]));
	s_waitcnt vmcnt(0)
	ds_read_b128 v[26:29], v109
	ds_read_b128 v[30:33], v109 offset:2048
	ds_read_b128 v[34:37], v109 offset:4096
	ds_read_b128 v[38:41], v109 offset:6144
	ds_read_b128 v[42:45], v108 offset:16384
	ds_read_b128 v[46:49], v108 offset:18432
	v_lshlrev_b32_e32 v0, 6, v105
	s_add_i32 s1, s1, s3
	s_waitcnt lgkmcnt(1)
	v_mfma_f32_16x16x32_bf16 v[78:81], v[26:29], v[42:45], v[78:81]
	s_waitcnt lgkmcnt(0)
	v_mfma_f32_16x16x32_bf16 v[26:29], v[26:29], v[46:49], v[74:77]
	v_mfma_f32_16x16x32_bf16 v[70:73], v[30:33], v[42:45], v[70:73]
	v_mfma_f32_16x16x32_bf16 v[30:33], v[30:33], v[46:49], v[66:69]
	v_mfma_f32_16x16x32_bf16 v[62:65], v[34:37], v[42:45], v[62:65]
	v_mfma_f32_16x16x32_bf16 v[34:37], v[34:37], v[46:49], v[58:61]
	v_mfma_f32_16x16x32_bf16 v[42:45], v[38:41], v[42:45], v[54:57]
	v_mfma_f32_16x16x32_bf16 v[38:41], v[38:41], v[46:49], v[50:53]
	ds_read_b128 v[46:49], v107
	s_nop 1
	ds_read_b128 v[50:53], v107 offset:2048
	ds_read_b128 v[54:57], v107 offset:4096
	ds_read_b128 v[58:61], v107 offset:6144
	ds_read_b128 v[66:69], v106 offset:16384
	ds_read_b128 v[74:77], v106 offset:18432
	ds_write_b128 v110, v[2:5] offset:32768
	ds_write_b128 v110, v[10:13] offset:36864
	ds_write_b128 v110, v[14:17] offset:40960
	ds_write_b128 v110, v[18:21] offset:45056
	ds_write_b128 v110, v[6:9] offset:49152
	ds_write_b128 v110, v[22:25] offset:53248
	s_waitcnt lgkmcnt(0)
	s_barrier
	ds_read_b128 v[2:5], v109 offset:32768
	ds_read_b128 v[6:9], v109 offset:34816
	ds_read_b128 v[10:13], v109 offset:36864
	ds_read_b128 v[14:17], v109 offset:38912
	ds_read_b128 v[18:21], v108 offset:49152
	ds_read_b128 v[22:25], v108 offset:51200
	v_mfma_f32_16x16x32_bf16 v[78:81], v[46:49], v[66:69], v[78:81]
	v_mfma_f32_16x16x32_bf16 v[26:29], v[46:49], v[74:77], v[26:29]
	v_mfma_f32_16x16x32_bf16 v[46:49], v[50:53], v[66:69], v[70:73]
	v_mfma_f32_16x16x32_bf16 v[30:33], v[50:53], v[74:77], v[30:33]
	v_mfma_f32_16x16x32_bf16 v[50:53], v[54:57], v[66:69], v[62:65]
	v_mfma_f32_16x16x32_bf16 v[34:37], v[54:57], v[74:77], v[34:37]
	v_mfma_f32_16x16x32_bf16 v[42:45], v[58:61], v[66:69], v[42:45]
	v_mfma_f32_16x16x32_bf16 v[38:41], v[58:61], v[74:77], v[38:41]
	s_waitcnt lgkmcnt(1)
	v_mfma_f32_16x16x32_bf16 v[54:57], v[2:5], v[18:21], v[78:81]
	s_waitcnt lgkmcnt(0)
	v_mfma_f32_16x16x32_bf16 v[2:5], v[2:5], v[22:25], v[26:29]
	v_mfma_f32_16x16x32_bf16 v[26:29], v[6:9], v[18:21], v[46:49]
	v_mfma_f32_16x16x32_bf16 v[6:9], v[6:9], v[22:25], v[30:33]
	v_mfma_f32_16x16x32_bf16 v[30:33], v[10:13], v[18:21], v[50:53]
	v_mfma_f32_16x16x32_bf16 v[10:13], v[10:13], v[22:25], v[34:37]
	v_mfma_f32_16x16x32_bf16 v[18:21], v[14:17], v[18:21], v[42:45]
	v_mfma_f32_16x16x32_bf16 v[14:17], v[14:17], v[22:25], v[38:41]
	ds_read_b128 v[22:25], v107 offset:32768
	ds_read_b128 v[34:37], v107 offset:34816
	s_nop 0
	ds_read_b128 v[38:41], v107 offset:36864
	ds_read_b128 v[42:45], v107 offset:38912
	ds_read_b128 v[46:49], v106 offset:49152
	ds_read_b128 v[50:53], v106 offset:51200
	s_waitcnt lgkmcnt(1)
	v_mfma_f32_16x16x32_bf16 v[54:57], v[22:25], v[46:49], v[54:57]
	s_waitcnt lgkmcnt(0)
	v_mfma_f32_16x16x32_bf16 v[2:5], v[22:25], v[50:53], v[2:5]
	v_mfma_f32_16x16x32_bf16 v[22:25], v[34:37], v[46:49], v[26:29]
	v_mfma_f32_16x16x32_bf16 v[26:29], v[38:41], v[46:49], v[30:33]
	s_nop 2
	v_lshl_or_b32 v30, v104, 2, v0
	v_lshlrev_b32_e32 v0, 1, v103
	v_lshl_or_b32 v0, v102, 6, v0
	v_mov_b32_e32 v32, v187
	v_mad_u64_u32 v[30:31], s[8:9], v30, s96, v[0:1]
	v_cvt_pk_bf16_f32 v0, v55, s0
	s_barrier
; __device__ __forceinline__ u16 f2bf(float f) { return (u16)(pack2(f, 0.f) & 0xffffu); }
; template <int NT, class VF, class RP>
; __device__ __forceinline__ void epi_staged_bf16(f32x4 (&acc)[4][NT], int r0, int c0, unsigned char* smem, VF vf, RP rowptr) {
;     ...
;   __syncthreads();
; #pragma unroll
;   for (int mi = 0; mi < 4; ++mi)
; #pragma unroll
;     for (int ni = 0; ni < NT; ++ni)
; #pragma unroll
;       for (int j = 0; j < 4; ++j) {
;         const int r = r0 + mi * 16 + j, c = c0 + ni * 16;
;         Ts[r * PITCH + c] = f2bf(vf(r, c, acc[mi][ni][j]));
;       }
;   __syncthreads();
; #pragma unroll
;   for (int i = 0; i < CPR / 2; ++i) {
;     const int c = t + 256 * i, row = c / CPR, ch = c % CPR;
;     u16* d = rowptr(row);
;     if (d) *(u32x4*)(d + ch * 8) = *(const u32x4*)(Ts + row * PITCH + ch * 8);
;   }
; __device__ __forceinline__ void phase_in_gemm(const Params& p, int l, unsigned char* smem) {
;     ...
;       auto rp = [&](int r) -> u16* { return p.PX + (size_t)(row_base + r) * 1024 + 896; };
;       epi_staged_bf16<2>(acc, r0, c0, smem, vf, rp);
	ds_write_b16 v30, v0 offset:144
	v_cvt_pk_bf16_f32 v0, v56, s0
	ds_write_b16 v30, v0 offset:288
	v_cvt_pk_bf16_f32 v0, v57, s0
	ds_write_b16 v30, v0 offset:432
	v_cvt_pk_bf16_f32 v0, v2, s0
	ds_write_b16 v30, v0 offset:32
	v_cvt_pk_bf16_f32 v0, v3, s0
	ds_write_b16 v30, v0 offset:176
	v_cvt_pk_bf16_f32 v0, v4, s0
	ds_write_b16 v30, v0 offset:320
	v_cvt_pk_bf16_f32 v0, v5, s0
	v_mfma_f32_16x16x32_bf16 v[6:9], v[34:37], v[50:53], v[6:9]
	ds_write_b16 v30, v0 offset:464
	v_cvt_pk_bf16_f32 v0, v22, s0
	ds_write_b16 v30, v0 offset:2304
	v_cvt_pk_bf16_f32 v0, v23, s0
	ds_write_b16 v30, v0 offset:2448
	v_cvt_pk_bf16_f32 v0, v24, s0
	ds_write_b16 v30, v0 offset:2592
	v_cvt_pk_bf16_f32 v0, v25, s0
	ds_write_b16 v30, v0 offset:2736
	v_cvt_pk_bf16_f32 v0, v6, s0
	ds_write_b16 v30, v0 offset:2336
	v_cvt_pk_bf16_f32 v0, v7, s0
	ds_write_b16 v30, v0 offset:2480
	v_cvt_pk_bf16_f32 v0, v8, s0
	ds_write_b16 v30, v0 offset:2624
	v_cvt_pk_bf16_f32 v0, v9, s0
	v_mfma_f32_16x16x32_bf16 v[10:13], v[38:41], v[50:53], v[10:13]
	ds_write_b16 v30, v0 offset:2768
	v_cvt_pk_bf16_f32 v0, v26, s0
	ds_write_b16 v30, v0 offset:4608
	v_cvt_pk_bf16_f32 v0, v27, s0
	ds_write_b16 v30, v0 offset:4752
	v_cvt_pk_bf16_f32 v0, v28, s0
	ds_write_b16 v30, v0 offset:4896
	v_cvt_pk_bf16_f32 v0, v29, s0
	v_mfma_f32_16x16x32_bf16 v[18:21], v[42:45], v[46:49], v[18:21]
	ds_write_b16 v30, v0 offset:5040
	v_cvt_pk_bf16_f32 v0, v10, s0
	ds_write_b16 v30, v0 offset:4640
	v_cvt_pk_bf16_f32 v0, v11, s0
	ds_write_b16 v30, v0 offset:4784
	v_cvt_pk_bf16_f32 v0, v12, s0
	ds_write_b16 v30, v0 offset:4928
	v_cvt_pk_bf16_f32 v0, v13, s0
	v_mfma_f32_16x16x32_bf16 v[14:17], v[42:45], v[50:53], v[14:17]
	ds_write_b16 v30, v0 offset:5072
	v_cvt_pk_bf16_f32 v0, v18, s0
	ds_write_b16 v30, v0 offset:6912
	v_cvt_pk_bf16_f32 v0, v19, s0
	ds_write_b16 v30, v0 offset:7056
	v_cvt_pk_bf16_f32 v0, v20, s0
	ds_write_b16 v30, v0 offset:7200
	v_cvt_pk_bf16_f32 v0, v21, s0
	ds_write_b16 v30, v0 offset:7344
	v_cvt_pk_bf16_f32 v0, v14, s0
	ds_write_b16 v30, v0 offset:6944
	v_cvt_pk_bf16_f32 v0, v15, s0
	ds_write_b16 v30, v0 offset:7088
	v_cvt_pk_bf16_f32 v0, v16, s0
	v_cvt_pk_bf16_f32 v33, v54, s0
	ds_write_b16 v30, v0 offset:7232
	v_cvt_pk_bf16_f32 v0, v17, s0
	v_mov_b64_e32 v[2:3], s[4:5]
	ds_write_b16 v30, v33
	ds_write_b16 v30, v0 offset:7376
	s_waitcnt lgkmcnt(0)
	s_barrier
	s_load_dwordx2 s[100:101], s[4:5], 0x120
	s_waitcnt lgkmcnt(0)
	v_mov_b32_e32 v4, s100
	v_mov_b32_e32 v5, s101
	v_ashrrev_i32_e32 v0, 31, v32
	v_lshrrev_b32_e32 v0, 29, v0
	v_add_u32_e32 v0, v32, v0
	v_ashrrev_i32_e32 v10, 3, v0
	v_add_u32_e32 v6, s40, v10
	v_ashrrev_i32_e32 v7, 31, v6
	v_lshlrev_b64 v[6:7], 11, v[6:7]
	v_and_b32_e32 v0, -8, v0
	v_sub_u32_e32 v0, v32, v0
	v_readlane_b32 s8, v254, 44
	s_add_i32 s38, s38, s8
	s_cmp_lt_i32 s1, s0
	s_waitcnt lgkmcnt(0)
	v_lshl_add_u64 v[8:9], v[4:5], 0, v[6:7]
	v_mul_lo_u32 v4, v10, s96
	v_lshlrev_b32_e32 v10, 3, v0
	v_lshl_add_u32 v0, v0, 4, v4
	ds_read_b128 v[4:7], v0
	v_ashrrev_i32_e32 v11, 31, v10
	v_lshl_add_u64 v[8:9], v[10:11], 1, v[8:9]
	v_add_u32_e32 v0, 0x100, v32
	s_waitcnt lgkmcnt(0)
	global_store_dwordx4 v[8:9], v[4:7], off offset:1792
	s_nop 1
	v_ashrrev_i32_e32 v4, 31, v0
	v_lshrrev_b32_e32 v4, 29, v4
	v_add_u32_e32 v10, v0, v4
	s_load_dwordx2 s[100:101], s[4:5], 0x120
	s_waitcnt lgkmcnt(0)
	v_mov_b32_e32 v4, s100
	v_mov_b32_e32 v5, s101
	v_ashrrev_i32_e32 v11, 3, v10
	v_add_u32_e32 v6, s40, v11
	v_ashrrev_i32_e32 v7, 31, v6
	v_lshlrev_b64 v[6:7], 11, v[6:7]
	s_waitcnt lgkmcnt(0)
	v_lshl_add_u64 v[8:9], v[4:5], 0, v[6:7]
	v_and_b32_e32 v4, -8, v10
	v_sub_u32_e32 v0, v0, v4
	v_mul_lo_u32 v4, v11, s96
	v_lshlrev_b32_e32 v10, 3, v0
	v_lshl_add_u32 v0, v0, 4, v4
	ds_read_b128 v[4:7], v0
	v_ashrrev_i32_e32 v11, 31, v10
	v_lshl_add_u64 v[8:9], v[10:11], 1, v[8:9]
	v_add_u32_e32 v0, 0x200, v32
	s_waitcnt lgkmcnt(0)
	global_store_dwordx4 v[8:9], v[4:7], off offset:1792
	s_nop 1
	v_ashrrev_i32_e32 v4, 31, v0
	v_lshrrev_b32_e32 v4, 29, v4
	v_add_u32_e32 v10, v0, v4
	s_load_dwordx2 s[100:101], s[4:5], 0x120
	s_waitcnt lgkmcnt(0)
	v_mov_b32_e32 v4, s100
	v_mov_b32_e32 v5, s101
	v_ashrrev_i32_e32 v11, 3, v10
	v_add_u32_e32 v6, s40, v11
	v_ashrrev_i32_e32 v7, 31, v6
	v_lshlrev_b64 v[6:7], 11, v[6:7]
	s_waitcnt lgkmcnt(0)
	v_lshl_add_u64 v[8:9], v[4:5], 0, v[6:7]
	v_and_b32_e32 v4, -8, v10
	v_sub_u32_e32 v0, v0, v4
	v_mul_lo_u32 v4, v11, s96
	v_lshlrev_b32_e32 v10, 3, v0
	v_lshl_add_u32 v0, v0, 4, v4
	ds_read_b128 v[4:7], v0
	v_ashrrev_i32_e32 v11, 31, v10
	v_lshl_add_u64 v[8:9], v[10:11], 1, v[8:9]
	v_add_u32_e32 v0, 0x300, v32
	s_waitcnt lgkmcnt(0)
	global_store_dwordx4 v[8:9], v[4:7], off offset:1792
	global_load_dwordx2 v[2:3], v[2:3], off offset:288
	s_nop 0
	v_ashrrev_i32_e32 v4, 31, v0
	v_lshrrev_b32_e32 v4, 29, v4
	v_add_u32_e32 v8, v0, v4
	v_ashrrev_i32_e32 v9, 3, v8
	v_add_u32_e32 v4, s40, v9
	v_ashrrev_i32_e32 v5, 31, v4
	v_lshlrev_b64 v[4:5], 11, v[4:5]
	s_waitcnt vmcnt(0) lgkmcnt(0)
	v_lshl_add_u64 v[6:7], v[2:3], 0, v[4:5]
	v_and_b32_e32 v2, -8, v8
	v_sub_u32_e32 v0, v0, v2
	v_mul_lo_u32 v2, v9, s96
	v_lshlrev_b32_e32 v8, 3, v0
	v_lshl_add_u32 v0, v0, 4, v2
	ds_read_b128 v[2:5], v0
	v_ashrrev_i32_e32 v9, 31, v8
	v_lshl_add_u64 v[6:7], v[8:9], 1, v[6:7]
	s_waitcnt lgkmcnt(0)
	global_store_dwordx4 v[6:7], v[2:5], off offset:1792
	s_cbranch_scc1 .LBB0_487

; __device__ __forceinline__ u16 f2bf(float f) { return (u16)(pack2(f, 0.f) & 0xffffu); }
; template <int NT, class VF, class RP>
; __device__ __forceinline__ void epi_staged_bf16(f32x4 (&acc)[4][NT], int r0, int c0, unsigned char* smem, VF vf, RP rowptr) {
;     ...
;   __syncthreads();
; #pragma unroll
;   for (int mi = 0; mi < 4; ++mi)
; #pragma unroll
;     for (int ni = 0; ni < NT; ++ni)
; #pragma unroll
;       for (int j = 0; j < 4; ++j) {
;         const int r = r0 + mi * 16 + j, c = c0 + ni * 16;
;         Ts[r * PITCH + c] = f2bf(vf(r, c, acc[mi][ni][j]));
;       }
;   __syncthreads();
; __device__ __forceinline__ void phase_mix_a(const Params& p, int l, bool last, unsigned char* smem) {
;     ...
;       auto epi = [&](f32x4(&acc)[4][4], int r0, int c0) {
;         const float* rs = (const float*)(smem + 65536);
;         auto vf = [&](int r, int, float v) { return v * rs[r]; };
;         auto rp = [&](int r) -> u16* { return p.QR + (size_t)(row_base + r) * 768 + nt * 128; };
;         epi_staged_bf16<4>(acc, r0, c0, smem, vf, rp);
;       };
;       gemm_tile<4, false, false, true>(p.PX + (size_t)row_base * 1024 + 512, 1024, nullptr, 128, W + (size_t)nt * 128 * 256, 256, 256, smem, epi);
.LBB0_553:
	s_or_b64 exec, exec, s[0:1]
	v_lshlrev_b32_e32 v0, 6, v0
	s_waitcnt lgkmcnt(0)
	v_lshl_or_b32 v3, v137, 2, v0
	v_mov_b32_e32 v0, v187
	v_lshl_add_u32 v4, v3, 2, v213
	s_barrier
	s_barrier
	ds_read_b128 v[6:9], v4
	s_mulk_i32 s19, 0xfd00
	s_waitcnt lgkmcnt(0)
	v_mul_f32_e32 v2, v98, v6
	v_cvt_pk_bf16_f32 v5, v2, s0
	v_lshlrev_b32_e32 v2, 1, v145
	v_lshl_or_b32 v2, v144, 7, v2
	v_mad_u64_u32 v[10:11], s[0:1], v3, s23, v[2:3]
	ds_write_b16 v10, v5
	v_or_b32_e32 v3, 1, v3
	v_mul_f32_e32 v5, v99, v7
	v_cvt_pk_bf16_f32 v5, v5, s0
	v_mad_u64_u32 v[2:3], s[0:1], v3, s23, v[2:3]
	v_mul_f32_e32 v3, v100, v8
	s_nop 0
	v_cvt_pk_bf16_f32 v3, v3, s0
	ds_write_b16 v2, v3 offset:272
	v_mul_f32_e32 v3, v101, v9
	v_cvt_pk_bf16_f32 v3, v3, s0
	ds_write_b16 v2, v3 offset:544
	v_mul_f32_e32 v3, v102, v6
	v_cvt_pk_bf16_f32 v3, v3, s0
	ds_write_b16 v10, v3 offset:32
	v_mul_f32_e32 v3, v103, v7
	v_cvt_pk_bf16_f32 v3, v3, s0
	ds_write_b16 v2, v3 offset:32
	v_mul_f32_e32 v3, v104, v8
	v_cvt_pk_bf16_f32 v3, v3, s0
	ds_write_b16 v2, v3 offset:304
	v_mul_f32_e32 v3, v105, v9
	v_cvt_pk_bf16_f32 v3, v3, s0
	ds_write_b16 v2, v3 offset:576
	v_mul_f32_e32 v3, v106, v6
	v_cvt_pk_bf16_f32 v3, v3, s0
	ds_write_b16 v10, v3 offset:64
	v_mul_f32_e32 v3, v107, v7
	v_cvt_pk_bf16_f32 v3, v3, s0
	ds_write_b16 v2, v3 offset:64
	v_mul_f32_e32 v3, v108, v8
	v_cvt_pk_bf16_f32 v3, v3, s0
	ds_write_b16 v2, v3 offset:336
	v_mul_f32_e32 v3, v109, v9
	v_cvt_pk_bf16_f32 v3, v3, s0
	ds_write_b16 v2, v3 offset:608
	v_mul_f32_e32 v3, v110, v6
	v_cvt_pk_bf16_f32 v3, v3, s0
	ds_write_b16 v10, v3 offset:96
	v_mul_f32_e32 v3, v111, v7
	v_cvt_pk_bf16_f32 v3, v3, s0
	ds_write_b16 v2, v3 offset:96
	v_mul_f32_e32 v3, v112, v8
	v_cvt_pk_bf16_f32 v3, v3, s0
	ds_write_b16 v2, v3 offset:368
	v_mul_f32_e32 v3, v113, v9
	ds_read_b128 v[6:9], v4 offset:64
	v_cvt_pk_bf16_f32 v3, v3, s0
	ds_write_b16 v2, v3 offset:640
	ds_write_b16 v2, v5
	s_waitcnt lgkmcnt(2)
	v_mul_f32_e32 v3, v82, v6
	v_cvt_pk_bf16_f32 v3, v3, s0
	ds_write_b16 v2, v3 offset:4080
	v_mul_f32_e32 v3, v83, v7
	v_cvt_pk_bf16_f32 v3, v3, s0
	ds_write_b16 v2, v3 offset:4352
	v_mul_f32_e32 v3, v84, v8
	v_cvt_pk_bf16_f32 v3, v3, s0
	ds_write_b16 v2, v3 offset:4624
	v_mul_f32_e32 v3, v85, v9
	v_cvt_pk_bf16_f32 v3, v3, s0
	ds_write_b16 v2, v3 offset:4896
	v_mul_f32_e32 v3, v86, v6
	v_cvt_pk_bf16_f32 v3, v3, s0
	ds_write_b16 v2, v3 offset:4112
	v_mul_f32_e32 v3, v87, v7
	v_cvt_pk_bf16_f32 v3, v3, s0
	ds_write_b16 v2, v3 offset:4384
	v_mul_f32_e32 v3, v88, v8
	v_cvt_pk_bf16_f32 v3, v3, s0
	ds_write_b16 v2, v3 offset:4656
	v_mul_f32_e32 v3, v89, v9
	v_cvt_pk_bf16_f32 v3, v3, s0
	ds_write_b16 v2, v3 offset:4928
	v_mul_f32_e32 v3, v90, v6
	v_cvt_pk_bf16_f32 v3, v3, s0
	ds_write_b16 v2, v3 offset:4144
	v_mul_f32_e32 v3, v91, v7
	v_cvt_pk_bf16_f32 v3, v3, s0
	ds_write_b16 v2, v3 offset:4416
	v_mul_f32_e32 v3, v92, v8
	v_cvt_pk_bf16_f32 v3, v3, s0
	ds_write_b16 v2, v3 offset:4688
	v_mul_f32_e32 v3, v93, v9
	v_cvt_pk_bf16_f32 v3, v3, s0
	ds_write_b16 v2, v3 offset:4960
	v_mul_f32_e32 v3, v94, v6
	v_cvt_pk_bf16_f32 v3, v3, s0
	ds_write_b16 v2, v3 offset:4176
	v_mul_f32_e32 v3, v95, v7
	v_cvt_pk_bf16_f32 v3, v3, s0
	ds_write_b16 v2, v3 offset:4448
	v_mul_f32_e32 v3, v96, v8
	v_cvt_pk_bf16_f32 v3, v3, s0
	ds_write_b16 v2, v3 offset:4720
	v_mul_f32_e32 v3, v97, v9
	ds_read_b128 v[6:9], v4 offset:128
	v_cvt_pk_bf16_f32 v3, v3, s0
	ds_write_b16 v2, v3 offset:4992
	s_waitcnt lgkmcnt(1)
	v_mul_f32_e32 v3, v70, v6
	v_cvt_pk_bf16_f32 v3, v3, s0
	ds_write_b16 v2, v3 offset:8432
	v_mul_f32_e32 v3, v71, v7
	v_cvt_pk_bf16_f32 v3, v3, s0
	ds_write_b16 v2, v3 offset:8704
	v_mul_f32_e32 v3, v72, v8
	v_cvt_pk_bf16_f32 v3, v3, s0
	ds_write_b16 v2, v3 offset:8976
	v_mul_f32_e32 v3, v73, v9
	v_cvt_pk_bf16_f32 v3, v3, s0
	ds_write_b16 v2, v3 offset:9248
	v_mul_f32_e32 v3, v74, v6
	v_cvt_pk_bf16_f32 v3, v3, s0
	ds_write_b16 v2, v3 offset:8464
	v_mul_f32_e32 v3, v75, v7
	v_cvt_pk_bf16_f32 v3, v3, s0
	ds_write_b16 v2, v3 offset:8736
	v_mul_f32_e32 v3, v76, v8
	v_cvt_pk_bf16_f32 v3, v3, s0
	ds_write_b16 v2, v3 offset:9008
	v_mul_f32_e32 v3, v77, v9
	v_cvt_pk_bf16_f32 v3, v3, s0
	ds_write_b16 v2, v3 offset:9280
	v_mul_f32_e32 v3, v78, v6
	v_cvt_pk_bf16_f32 v3, v3, s0
	ds_write_b16 v2, v3 offset:8496
	v_mul_f32_e32 v3, v79, v7
	v_cvt_pk_bf16_f32 v3, v3, s0
	ds_write_b16 v2, v3 offset:8768
	v_mul_f32_e32 v3, v80, v8
	v_cvt_pk_bf16_f32 v3, v3, s0
	ds_write_b16 v2, v3 offset:9040
	v_mul_f32_e32 v3, v81, v9
	v_cvt_pk_bf16_f32 v3, v3, s0
	ds_write_b16 v2, v3 offset:9312
	v_mul_f32_e32 v3, v66, v6
	v_cvt_pk_bf16_f32 v3, v3, s0
	ds_write_b16 v2, v3 offset:8528
	v_mul_f32_e32 v3, v67, v7
	v_cvt_pk_bf16_f32 v3, v3, s0
	ds_read_b128 v[4:7], v4 offset:192
	ds_write_b16 v2, v3 offset:8800
	v_mul_f32_e32 v3, v68, v8
	v_cvt_pk_bf16_f32 v3, v3, s0
	ds_write_b16 v2, v3 offset:9072
	v_mul_f32_e32 v3, v69, v9
	v_cvt_pk_bf16_f32 v3, v3, s0
	ds_write_b16 v2, v3 offset:9344
	s_waitcnt lgkmcnt(3)
	v_mul_f32_e32 v3, v58, v4
	v_cvt_pk_bf16_f32 v3, v3, s0
	ds_write_b16 v2, v3 offset:12784
	v_mul_f32_e32 v3, v59, v5
	v_cvt_pk_bf16_f32 v3, v3, s0
	ds_write_b16 v2, v3 offset:13056
	v_mul_f32_e32 v3, v60, v6
	v_cvt_pk_bf16_f32 v3, v3, s0
	ds_write_b16 v2, v3 offset:13328
	v_mul_f32_e32 v3, v61, v7
	v_cvt_pk_bf16_f32 v3, v3, s0
	ds_write_b16 v2, v3 offset:13600
	v_mul_f32_e32 v3, v54, v4
	v_cvt_pk_bf16_f32 v3, v3, s0
	ds_write_b16 v2, v3 offset:12816
	v_mul_f32_e32 v3, v55, v5
	v_cvt_pk_bf16_f32 v3, v3, s0
	ds_write_b16 v2, v3 offset:13088
	v_mul_f32_e32 v3, v56, v6
	v_cvt_pk_bf16_f32 v3, v3, s0
	ds_write_b16 v2, v3 offset:13360
	v_mul_f32_e32 v3, v57, v7
	v_cvt_pk_bf16_f32 v3, v3, s0
	ds_write_b16 v2, v3 offset:13632
	v_mul_f32_e32 v3, v50, v4
	v_cvt_pk_bf16_f32 v3, v3, s0
	ds_write_b16 v2, v3 offset:12848
	v_mul_f32_e32 v3, v51, v5
	v_cvt_pk_bf16_f32 v3, v3, s0
	ds_write_b16 v2, v3 offset:13120
	v_mul_f32_e32 v3, v52, v6
	v_cvt_pk_bf16_f32 v3, v3, s0
	ds_write_b16 v2, v3 offset:13392
	v_mul_f32_e32 v3, v53, v7
	v_cvt_pk_bf16_f32 v3, v3, s0
	ds_write_b16 v2, v3 offset:13664
	v_mul_f32_e32 v3, v46, v4
	v_cvt_pk_bf16_f32 v3, v3, s0
	ds_write_b16 v2, v3 offset:12880
	v_mul_f32_e32 v3, v47, v5
	v_cvt_pk_bf16_f32 v3, v3, s0
	ds_write_b16 v2, v3 offset:13152
	v_mul_f32_e32 v3, v48, v6
	v_cvt_pk_bf16_f32 v3, v3, s0
	ds_write_b16 v2, v3 offset:13424
	v_mul_f32_e32 v3, v49, v7
	v_cvt_pk_bf16_f32 v3, v3, s0
	ds_write_b16 v2, v3 offset:13696
	v_mov_b64_e32 v[2:3], s[40:41]
	s_waitcnt lgkmcnt(0)
	s_barrier
; template <int NT, class VF, class RP>
; __device__ __forceinline__ void epi_staged_bf16(f32x4 (&acc)[4][NT], int r0, int c0, unsigned char* smem, VF vf, RP rowptr) {
;     ...
;   for (int i = 0; i < CPR / 2; ++i) {
;     const int c = t + 256 * i, row = c / CPR, ch = c % CPR;
;     u16* d = rowptr(row);
;     if (d) *(u32x4*)(d + ch * 8) = *(const u32x4*)(Ts + row * PITCH + ch * 8);
;   }
; __device__ __forceinline__ void phase_mix_a(const Params& p, int l, bool last, unsigned char* smem) {
;     ...
;         auto rp = [&](int r) -> u16* { return p.QR + (size_t)(row_base + r) * 768 + nt * 128; };
	s_load_dwordx2 s[100:101], s[40:41], 0x148
	s_waitcnt lgkmcnt(0)
	v_mov_b32_e32 v6, s100
	v_mov_b32_e32 v7, s101
	v_mov_b64_e32 v[2:3], 0
	v_mov_b64_e32 v[4:5], 0
	s_waitcnt lgkmcnt(0)
	v_cmp_ne_u64_e32 vcc, 0, v[6:7]
	s_and_saveexec_b64 s[0:1], vcc
	s_xor_b64 s[0:1], exec, s[0:1]
	s_cbranch_execz .LBB0_555
	v_ashrrev_i32_e32 v4, 31, v0
	v_lshrrev_b32_e32 v4, 28, v4
	v_add_u32_e32 v4, v0, v4
	v_ashrrev_i32_e32 v5, 4, v4
	v_and_b32_e32 v4, -16, v4
	v_sub_u32_e32 v10, v0, v4
	v_mul_lo_u32 v4, v5, s23
	v_add_u32_e32 v8, s4, v5
	s_movk_i32 s5, 0x600
	v_lshl_add_u32 v4, v10, 4, v4
	v_mad_i64_i32 v[8:9], s[34:35], v8, s5, v[6:7]
	ds_read_b128 v[4:7], v4
	s_add_i32 s34, s18, s19
	s_ashr_i32 s35, s34, 31
	v_lshlrev_b32_e32 v10, 3, v10
	v_lshl_add_u64 v[8:9], s[34:35], 1, v[8:9]
	v_ashrrev_i32_e32 v11, 31, v10
	v_lshl_add_u64 v[8:9], v[10:11], 1, v[8:9]
	s_waitcnt lgkmcnt(0)
	global_store_dwordx4 v[8:9], v[4:7], off
	s_nop 1
	v_mov_b64_e32 v[4:5], s[40:41]
	s_load_dwordx2 s[100:101], s[40:41], 0x148
	s_waitcnt lgkmcnt(0)
	v_mov_b32_e32 v4, s100
	v_mov_b32_e32 v5, s101
.LBB0_555:
	s_or_b64 exec, exec, s[0:1]
	s_waitcnt lgkmcnt(0)
	v_cmp_ne_u64_e32 vcc, 0, v[4:5]
	s_and_saveexec_b64 s[0:1], vcc
	s_cbranch_execz .LBB0_557
	v_add_u32_e32 v2, 0x100, v0
	v_ashrrev_i32_e32 v3, 31, v2
	v_lshrrev_b32_e32 v3, 28, v3
	v_add_u32_e32 v3, v2, v3
	v_ashrrev_i32_e32 v8, 4, v3
	v_and_b32_e32 v3, -16, v3
	v_sub_u32_e32 v9, v2, v3
	v_mul_lo_u32 v2, v8, s23
	v_add_u32_e32 v6, s4, v8
	s_movk_i32 s5, 0x600
	v_lshl_add_u32 v2, v9, 4, v2
	v_mad_i64_i32 v[6:7], s[34:35], v6, s5, v[4:5]
	ds_read_b128 v[2:5], v2
	s_add_i32 s34, s18, s19
	s_ashr_i32 s35, s34, 31
	v_lshlrev_b32_e32 v8, 3, v9
	v_lshl_add_u64 v[6:7], s[34:35], 1, v[6:7]
	v_ashrrev_i32_e32 v9, 31, v8
	v_lshl_add_u64 v[6:7], v[8:9], 1, v[6:7]
	s_waitcnt lgkmcnt(0)
	global_store_dwordx4 v[6:7], v[2:5], off
	s_nop 1
	v_mov_b64_e32 v[2:3], s[40:41]
	s_load_dwordx2 s[100:101], s[40:41], 0x148
	s_waitcnt lgkmcnt(0)
	v_mov_b32_e32 v2, s100
	v_mov_b32_e32 v3, s101
.LBB0_557:
	s_or_b64 exec, exec, s[0:1]
	v_mov_b64_e32 v[4:5], 0
	s_waitcnt lgkmcnt(0)
	v_cmp_ne_u64_e32 vcc, 0, v[2:3]
	v_mov_b64_e32 v[6:7], 0
	s_and_saveexec_b64 s[0:1], vcc
	s_cbranch_execz .LBB0_559
	v_add_u32_e32 v6, 0x200, v0
	v_ashrrev_i32_e32 v7, 31, v6
	v_lshrrev_b32_e32 v7, 28, v7
	v_add_u32_e32 v7, v6, v7
	v_ashrrev_i32_e32 v8, 4, v7
	v_and_b32_e32 v7, -16, v7
	v_sub_u32_e32 v10, v6, v7
	v_mul_lo_u32 v6, v8, s23
	v_add_u32_e32 v9, s4, v8
	s_movk_i32 s5, 0x600
	v_lshl_add_u32 v6, v10, 4, v6
	v_mad_i64_i32 v[2:3], s[34:35], v9, s5, v[2:3]
	ds_read_b128 v[6:9], v6
	s_add_i32 s34, s18, s19
	s_ashr_i32 s35, s34, 31
	v_lshlrev_b32_e32 v10, 3, v10
	v_lshl_add_u64 v[2:3], s[34:35], 1, v[2:3]
	v_ashrrev_i32_e32 v11, 31, v10
	v_lshl_add_u64 v[2:3], v[10:11], 1, v[2:3]
	s_waitcnt lgkmcnt(0)
	global_store_dwordx4 v[2:3], v[6:9], off
	v_mov_b64_e32 v[2:3], s[40:41]
	s_load_dwordx2 s[100:101], s[40:41], 0x148
	s_waitcnt lgkmcnt(0)
	v_mov_b32_e32 v6, s100
	v_mov_b32_e32 v7, s101
.LBB0_559:
	s_or_b64 exec, exec, s[0:1]
	s_waitcnt lgkmcnt(0)
	v_cmp_ne_u64_e32 vcc, 0, v[6:7]
	s_and_saveexec_b64 s[0:1], vcc
	s_cbranch_execz .LBB0_561
	v_add_u32_e32 v2, 0x300, v0
	v_ashrrev_i32_e32 v3, 31, v2
	v_lshrrev_b32_e32 v3, 28, v3
	v_add_u32_e32 v3, v2, v3
	v_ashrrev_i32_e32 v4, 4, v3
	v_and_b32_e32 v3, -16, v3
	v_sub_u32_e32 v8, v2, v3
	v_mul_lo_u32 v2, v4, s23
	v_add_u32_e32 v5, s4, v4
	s_movk_i32 s5, 0x600
	v_lshl_add_u32 v2, v8, 4, v2
	v_mad_i64_i32 v[6:7], s[34:35], v5, s5, v[6:7]
	ds_read_b128 v[2:5], v2
	s_add_i32 s34, s18, s19
	s_ashr_i32 s35, s34, 31
	v_lshlrev_b32_e32 v8, 3, v8
	v_lshl_add_u64 v[6:7], s[34:35], 1, v[6:7]
	v_ashrrev_i32_e32 v9, 31, v8
	v_lshl_add_u64 v[6:7], v[8:9], 1, v[6:7]
	s_waitcnt lgkmcnt(0)
	global_store_dwordx4 v[6:7], v[2:5], off
	s_nop 1
	v_mov_b64_e32 v[2:3], s[40:41]
	s_load_dwordx2 s[100:101], s[40:41], 0x148
	s_waitcnt lgkmcnt(0)
	v_mov_b32_e32 v4, s100
	v_mov_b32_e32 v5, s101
; template <int NT, class VF, class RP>
; __device__ __forceinline__ void epi_staged_bf16(f32x4 (&acc)[4][NT], int r0, int c0, unsigned char* smem, VF vf, RP rowptr) {
;     ...
;   for (int i = 0; i < CPR / 2; ++i) {
;     const int c = t + 256 * i, row = c / CPR, ch = c % CPR;
;     u16* d = rowptr(row);
;     if (d) *(u32x4*)(d + ch * 8) = *(const u32x4*)(Ts + row * PITCH + ch * 8);
;   }
; __device__ __forceinline__ void phase_mix_a(const Params& p, int l, bool last, unsigned char* smem) {
;     ...
;         auto rp = [&](int r) -> u16* { return p.QR + (size_t)(row_base + r) * 768 + nt * 128; };
.LBB0_561:
	s_or_b64 exec, exec, s[0:1]
	v_mov_b64_e32 v[2:3], 0
	s_waitcnt lgkmcnt(0)
	v_cmp_ne_u64_e32 vcc, 0, v[4:5]
	v_mov_b64_e32 v[6:7], 0
	s_and_saveexec_b64 s[0:1], vcc
	s_cbranch_execz .LBB0_563
	v_add_u32_e32 v6, 0x400, v0
	v_ashrrev_i32_e32 v7, 31, v6
	v_lshrrev_b32_e32 v7, 28, v7
	v_add_u32_e32 v7, v6, v7
	v_ashrrev_i32_e32 v10, 4, v7
	v_add_u32_e32 v8, s4, v10
	s_movk_i32 s5, 0x600
	v_mad_i64_i32 v[8:9], s[34:35], v8, s5, v[4:5]
	v_and_b32_e32 v4, -16, v7
	v_sub_u32_e32 v11, v6, v4
	v_mul_lo_u32 v4, v10, s23
	v_lshl_add_u32 v4, v11, 4, v4
	ds_read_b128 v[4:7], v4
	s_add_i32 s34, s18, s19
	s_ashr_i32 s35, s34, 31
	v_lshlrev_b32_e32 v10, 3, v11
	v_lshl_add_u64 v[8:9], s[34:35], 1, v[8:9]
	v_ashrrev_i32_e32 v11, 31, v10
	v_lshl_add_u64 v[8:9], v[10:11], 1, v[8:9]
	s_waitcnt lgkmcnt(0)
	global_store_dwordx4 v[8:9], v[4:7], off
	s_nop 1
	v_mov_b64_e32 v[4:5], s[40:41]
	s_load_dwordx2 s[100:101], s[40:41], 0x148
	s_waitcnt lgkmcnt(0)
	v_mov_b32_e32 v6, s100
	v_mov_b32_e32 v7, s101
.LBB0_563:
	s_or_b64 exec, exec, s[0:1]
	s_waitcnt lgkmcnt(0)
	v_cmp_ne_u64_e32 vcc, 0, v[6:7]
	s_and_saveexec_b64 s[0:1], vcc
	s_cbranch_execz .LBB0_565
	v_add_u32_e32 v2, 0x500, v0
	v_ashrrev_i32_e32 v3, 31, v2
	v_lshrrev_b32_e32 v3, 28, v3
	v_add_u32_e32 v3, v2, v3
	v_ashrrev_i32_e32 v4, 4, v3
	v_and_b32_e32 v3, -16, v3
	v_sub_u32_e32 v8, v2, v3
	v_mul_lo_u32 v2, v4, s23
	v_add_u32_e32 v5, s4, v4
	s_movk_i32 s5, 0x600
	v_lshl_add_u32 v2, v8, 4, v2
	v_mad_i64_i32 v[6:7], s[34:35], v5, s5, v[6:7]
	ds_read_b128 v[2:5], v2
	s_add_i32 s34, s18, s19
	s_ashr_i32 s35, s34, 31
	v_lshlrev_b32_e32 v8, 3, v8
	v_lshl_add_u64 v[6:7], s[34:35], 1, v[6:7]
	v_ashrrev_i32_e32 v9, 31, v8
	v_lshl_add_u64 v[6:7], v[8:9], 1, v[6:7]
	s_waitcnt lgkmcnt(0)
	global_store_dwordx4 v[6:7], v[2:5], off
	s_nop 1
	v_mov_b64_e32 v[2:3], s[40:41]
	s_load_dwordx2 s[100:101], s[40:41], 0x148
	s_waitcnt lgkmcnt(0)
	v_mov_b32_e32 v2, s100
	v_mov_b32_e32 v3, s101
.LBB0_565:
	s_or_b64 exec, exec, s[0:1]
	v_mov_b64_e32 v[4:5], 0
	s_waitcnt lgkmcnt(0)
	v_cmp_ne_u64_e32 vcc, 0, v[2:3]
	s_and_saveexec_b64 s[0:1], vcc
	s_cbranch_execz .LBB0_567
	v_add_u32_e32 v4, 0x600, v0
	v_ashrrev_i32_e32 v5, 31, v4
	v_lshrrev_b32_e32 v5, 28, v5
	v_add_u32_e32 v5, v4, v5
	v_ashrrev_i32_e32 v8, 4, v5
	v_add_u32_e32 v6, s4, v8
	s_movk_i32 s5, 0x600
	v_mad_i64_i32 v[6:7], s[34:35], v6, s5, v[2:3]
	v_and_b32_e32 v2, -16, v5
	v_sub_u32_e32 v9, v4, v2
	v_mul_lo_u32 v2, v8, s23
	v_lshl_add_u32 v2, v9, 4, v2
	ds_read_b128 v[2:5], v2
	s_add_i32 s34, s18, s19
	s_ashr_i32 s35, s34, 31
	v_lshlrev_b32_e32 v8, 3, v9
	v_lshl_add_u64 v[6:7], s[34:35], 1, v[6:7]
	v_ashrrev_i32_e32 v9, 31, v8
	v_lshl_add_u64 v[6:7], v[8:9], 1, v[6:7]
	s_waitcnt lgkmcnt(0)
	global_store_dwordx4 v[6:7], v[2:5], off
	s_nop 1
	v_mov_b64_e32 v[2:3], s[40:41]
	s_load_dwordx2 s[100:101], s[40:41], 0x148
	s_waitcnt lgkmcnt(0)
	v_mov_b32_e32 v4, s100
	v_mov_b32_e32 v5, s101
.LBB0_567:
	s_or_b64 exec, exec, s[0:1]
	s_waitcnt lgkmcnt(0)
	v_cmp_ne_u64_e32 vcc, 0, v[4:5]
	s_and_saveexec_b64 s[0:1], vcc
	s_cbranch_execz .LBB0_544
	v_add_u32_e32 v0, 0x700, v0
	v_ashrrev_i32_e32 v2, 31, v0
	v_lshrrev_b32_e32 v2, 28, v2
	v_add_u32_e32 v2, v0, v2
	v_ashrrev_i32_e32 v3, 4, v2
	v_and_b32_e32 v2, -16, v2
	v_sub_u32_e32 v0, v0, v2
	v_mul_lo_u32 v2, v3, s23
	v_add_u32_e32 v6, s4, v3
	s_movk_i32 s4, 0x600
	v_lshl_add_u32 v2, v0, 4, v2
	v_mad_i64_i32 v[6:7], s[4:5], v6, s4, v[4:5]
	ds_read_b128 v[2:5], v2
	s_add_i32 s4, s18, s19
	s_ashr_i32 s5, s4, 31
	v_lshlrev_b32_e32 v8, 3, v0
	v_lshl_add_u64 v[6:7], s[4:5], 1, v[6:7]
	v_ashrrev_i32_e32 v9, 31, v8
	v_lshl_add_u64 v[6:7], v[8:9], 1, v[6:7]
	s_waitcnt lgkmcnt(0)
	global_store_dwordx4 v[6:7], v[2:5], off
	s_branch .LBB0_544

; template <class RP>
; __device__ __forceinline__ void epi_staged_bf16_T(f32x4 (&acc)[4][4], int r0, int c0, unsigned char* smem, RP colptr) {
;     ...
;   __syncthreads();
; #pragma unroll
;   for (int mi = 0; mi < 4; ++mi)
; #pragma unroll
;     for (int ni = 0; ni < 4; ++ni) {
;       u32x2 pk;
;       pk.x = pack2(acc[mi][ni][0], acc[mi][ni][1]);
;       pk.y = pack2(acc[mi][ni][2], acc[mi][ni][3]);
;       *(u32x2*)(Ts + (c0 + ni * 16) * PITCH + r0 + mi * 16) = pk;
;     }
;   __syncthreads();
; __device__ __forceinline__ void phase_mix_a(const Params& p, int l, bool last, unsigned char* smem) {
;     ...
; #pragma unroll
;           for (int mi = 0; mi < 4; ++mi)
; #pragma unroll
;             for (int j = 0; j < 4; ++j) {
;               const float sc = rs[r0 + mi * 16 + j];
; #pragma unroll
;               for (int ni = 0; ni < 4; ++ni) acc[mi][ni][j] *= sc;
;             }
;           auto cp = [&](int c) -> u16* { return p.Vt + ((size_t)(b * 4 + h) * 128 + c) * NPOS + pos_base; };
;           epi_staged_bf16_T(acc, r0, c0, smem, cp);
.LBB0_581:
	s_or_b64 exec, exec, s[0:1]
	s_lshr_b32 s5, s19, 1
	v_lshlrev_b32_e32 v0, 6, v0
	s_bitcmp1_b32 s9, 0
	v_lshl_or_b32 v18, v93, 2, v0
	s_cselect_b64 s[34:35], -1, 0
	s_waitcnt lgkmcnt(0)
	v_lshl_or_b32 v19, v100, 6, v101
	s_mov_b64 s[0:1], -1
	s_and_b64 vcc, exec, s[34:35]
	v_lshl_add_u32 v20, v18, 2, v213
	s_barrier
	s_cbranch_vccz .LBB0_583
	ds_read_b128 v[22:25], v20
	ds_read_b128 v[26:29], v20 offset:64
	v_mul_u32_u24_e32 v0, 0x88, v19
	v_lshlrev_b32_e32 v0, 1, v0
	v_mov_b32_e32 v21, v187
	s_waitcnt lgkmcnt(1)
	v_pk_mul_f32 v[30:31], v[86:87], v[22:23]
	v_pk_mul_f32 v[32:33], v[74:75], v[22:23]
	v_pk_mul_f32 v[50:51], v[78:79], v[22:23]
	v_pk_mul_f32 v[52:53], v[82:83], v[22:23]
	v_pk_mul_f32 v[70:71], v[88:89], v[24:25]
	v_pk_mul_f32 v[72:73], v[76:77], v[24:25]
	v_pk_mul_f32 v[92:93], v[80:81], v[24:25]
	v_pk_mul_f32 v[94:95], v[84:85], v[24:25]
	s_waitcnt lgkmcnt(0)
	v_pk_mul_f32 v[96:97], v[66:67], v[26:27]
	v_pk_mul_f32 v[98:99], v[54:55], v[26:27]
	v_pk_mul_f32 v[100:101], v[58:59], v[26:27]
	v_pk_mul_f32 v[102:103], v[62:63], v[26:27]
	v_pk_mul_f32 v[104:105], v[68:69], v[28:29]
	ds_read_b128 v[22:25], v20 offset:128
	v_pk_mul_f32 v[106:107], v[56:57], v[28:29]
	v_pk_mul_f32 v[108:109], v[60:61], v[28:29]
	v_pk_mul_f32 v[110:111], v[64:65], v[28:29]
	ds_read_b128 v[26:29], v20 offset:192
	v_cvt_pk_bf16_f32 v32, v32, v33
	v_cvt_pk_bf16_f32 v33, v72, v73
	v_lshl_add_u32 v0, v18, 1, v0
	v_cvt_pk_bf16_f32 v30, v30, v31
	v_cvt_pk_bf16_f32 v31, v70, v71
	v_cvt_pk_bf16_f32 v70, v98, v99
	v_cvt_pk_bf16_f32 v71, v106, v107
	s_waitcnt lgkmcnt(0)
	s_barrier
	v_cvt_pk_bf16_f32 v50, v50, v51
	v_cvt_pk_bf16_f32 v51, v92, v93
	ds_write2_b64 v0, v[32:33], v[70:71] offset1:4
	v_cvt_pk_bf16_f32 v32, v100, v101
	v_cvt_pk_bf16_f32 v33, v108, v109
	v_add_u32_e32 v70, 0x1000, v0
	v_cvt_pk_bf16_f32 v52, v52, v53
	v_cvt_pk_bf16_f32 v53, v94, v95
	ds_write2_b64 v70, v[50:51], v[32:33] offset0:32 offset1:36
	v_cvt_pk_bf16_f32 v32, v102, v103
	v_cvt_pk_bf16_f32 v33, v110, v111
	v_add_u32_e32 v71, 0x2000, v0
	v_pk_mul_f32 v[112:113], v[34:35], v[22:23]
	v_pk_mul_f32 v[114:115], v[38:39], v[22:23]
	v_pk_mul_f32 v[116:117], v[42:43], v[22:23]
	v_pk_mul_f32 v[22:23], v[46:47], v[22:23]
	v_pk_mul_f32 v[118:119], v[36:37], v[24:25]
	v_pk_mul_f32 v[120:121], v[40:41], v[24:25]
	v_pk_mul_f32 v[122:123], v[44:45], v[24:25]
	v_pk_mul_f32 v[24:25], v[48:49], v[24:25]
	v_pk_mul_f32 v[124:125], v[2:3], v[26:27]
	v_pk_mul_f32 v[126:127], v[14:15], v[26:27]
	v_pk_mul_f32 v[128:129], v[10:11], v[26:27]
	v_pk_mul_f32 v[26:27], v[6:7], v[26:27]
	v_pk_mul_f32 v[130:131], v[4:5], v[28:29]
	v_pk_mul_f32 v[132:133], v[16:17], v[28:29]
	v_pk_mul_f32 v[134:135], v[12:13], v[28:29]
	v_pk_mul_f32 v[28:29], v[8:9], v[28:29]
	ds_write2_b64 v71, v[52:53], v[32:33] offset0:64 offset1:68
	v_cvt_pk_bf16_f32 v32, v96, v97
	v_cvt_pk_bf16_f32 v33, v104, v105
	v_add_u32_e32 v52, 0x3000, v0
	ds_write2_b64 v52, v[30:31], v[32:33] offset0:96 offset1:100
	v_cvt_pk_bf16_f32 v30, v114, v115
	v_cvt_pk_bf16_f32 v31, v120, v121
	v_cvt_pk_bf16_f32 v22, v22, v23
	v_cvt_pk_bf16_f32 v23, v24, v25
	v_cvt_pk_bf16_f32 v50, v126, v127
	v_cvt_pk_bf16_f32 v51, v132, v133
	v_cvt_pk_bf16_f32 v26, v26, v27
	v_cvt_pk_bf16_f32 v27, v28, v29
	v_cvt_pk_bf16_f32 v32, v116, v117
	v_cvt_pk_bf16_f32 v33, v122, v123
	v_cvt_pk_bf16_f32 v24, v112, v113
	v_cvt_pk_bf16_f32 v25, v118, v119
	ds_write2_b64 v0, v[30:31], v[50:51] offset0:8 offset1:12
	v_cvt_pk_bf16_f32 v30, v128, v129
	v_cvt_pk_bf16_f32 v31, v134, v135
	ds_write2_b64 v71, v[22:23], v[26:27] offset0:72 offset1:76
	v_cvt_pk_bf16_f32 v22, v124, v125
	v_cvt_pk_bf16_f32 v23, v130, v131
	v_mov_b64_e32 v[26:27], s[40:41]
	ds_write2_b64 v70, v[32:33], v[30:31] offset0:40 offset1:44
	ds_write2_b64 v52, v[24:25], v[22:23] offset0:104 offset1:108
	s_waitcnt lgkmcnt(0)
	s_barrier
; template <class RP>
; __device__ __forceinline__ void epi_staged_bf16_T(f32x4 (&acc)[4][4], int r0, int c0, unsigned char* smem, RP colptr) {
;     ...
; #pragma unroll
;   for (int i = 0; i < 8; ++i) {
;     const int c = t + 256 * i, col = c >> 4, ch = c & 15;
;     *(u32x4*)(colptr(col) + ch * 8) = *(const u32x4*)(Ts + col * PITCH + ch * 8);
;   }
; __device__ __forceinline__ void phase_mix_a(const Params& p, int l, bool last, unsigned char* smem) {
;     ...
;           auto cp = [&](int c) -> u16* { return p.Vt + ((size_t)(b * 4 + h) * 128 + c) * NPOS + pos_base; };
	global_load_dwordx2 v[28:29], v[26:27], off offset:344
	s_add_i32 s1, s18, 0xffffc000
	s_and_b32 s19, s18, 0x1f80
	s_ashr_i32 s0, s9, 9
	s_lshr_b32 s1, s1, 8
	s_addk_i32 s19, 0x100
	s_and_b32 s34, s18, 0x80
	v_lshlrev_b32_e32 v0, 4, v21
	s_cmpk_lt_i32 s4, 0x4000
	v_and_b32_e32 v0, 0xf0, v0
	v_ashrrev_i32_e32 v30, 4, v21
	s_cselect_b32 s35, s0, s1
	v_mad_u64_u32 v[22:23], s[0:1], v30, s23, v[0:1]
	s_cselect_b32 s19, s19, s34
	s_lshl_b32 s0, s35, 2
	s_or_b32 s0, s0, s5
	s_ashr_i32 s1, s0, 31
	s_lshl_b64 s[0:1], s[0:1], 7
	v_ashrrev_i32_e32 v31, 31, v30
	ds_read_b128 v[22:25], v22
	v_lshl_add_u64 v[30:31], s[0:1], 0, v[30:31]
	s_lshl_b32 s94, s19, 1
	s_waitcnt vmcnt(0) lgkmcnt(0)
	v_mad_u64_u32 v[28:29], s[34:35], v30, s68, v[28:29]
	v_mad_i32_i24 v29, v31, s68, v29
	v_lshl_add_u64 v[28:29], v[28:29], 0, s[94:95]
	v_lshl_add_u64 v[28:29], v[28:29], 0, v[0:1]
	global_store_dwordx4 v[28:29], v[22:25], off
	s_load_dwordx2 s[100:101], s[40:41], 0x158
	s_waitcnt lgkmcnt(0)
	v_mov_b32_e32 v28, s100
	v_mov_b32_e32 v29, s101
	s_nop 0
	v_add_u32_e32 v22, 0x100, v21
	v_ashrrev_i32_e32 v22, 4, v22
	v_mad_u64_u32 v[24:25], s[34:35], v22, s23, v[0:1]
	v_ashrrev_i32_e32 v23, 31, v22
	v_lshl_add_u64 v[30:31], s[0:1], 0, v[22:23]
	ds_read_b128 v[22:25], v24
	s_waitcnt lgkmcnt(0)
	v_mad_u64_u32 v[28:29], s[34:35], v30, s68, v[28:29]
	v_mad_i32_i24 v29, v31, s68, v29
	v_lshl_add_u64 v[28:29], v[28:29], 0, s[94:95]
	v_lshl_add_u64 v[28:29], v[28:29], 0, v[0:1]
	global_store_dwordx4 v[28:29], v[22:25], off
	s_load_dwordx2 s[100:101], s[40:41], 0x158
	s_waitcnt lgkmcnt(0)
	v_mov_b32_e32 v28, s100
	v_mov_b32_e32 v29, s101
	s_nop 0
	v_add_u32_e32 v22, 0x200, v21
	v_ashrrev_i32_e32 v22, 4, v22
	v_mad_u64_u32 v[24:25], s[34:35], v22, s23, v[0:1]
	v_ashrrev_i32_e32 v23, 31, v22
	v_lshl_add_u64 v[30:31], s[0:1], 0, v[22:23]
	ds_read_b128 v[22:25], v24
	s_waitcnt lgkmcnt(0)
	v_mad_u64_u32 v[28:29], s[34:35], v30, s68, v[28:29]
	v_mad_i32_i24 v29, v31, s68, v29
	v_lshl_add_u64 v[28:29], v[28:29], 0, s[94:95]
	v_lshl_add_u64 v[28:29], v[28:29], 0, v[0:1]
	global_store_dwordx4 v[28:29], v[22:25], off
	global_load_dwordx2 v[28:29], v[26:27], off offset:344
	s_nop 0
	v_add_u32_e32 v22, 0x300, v21
	v_ashrrev_i32_e32 v22, 4, v22
	v_mad_u64_u32 v[24:25], s[34:35], v22, s23, v[0:1]
	v_ashrrev_i32_e32 v23, 31, v22
	v_lshl_add_u64 v[30:31], s[0:1], 0, v[22:23]
	ds_read_b128 v[22:25], v24
	s_waitcnt vmcnt(0) lgkmcnt(0)
	v_mad_u64_u32 v[28:29], s[34:35], v30, s68, v[28:29]
	v_mad_i32_i24 v29, v31, s68, v29
	v_lshl_add_u64 v[28:29], v[28:29], 0, s[94:95]
	v_lshl_add_u64 v[28:29], v[28:29], 0, v[0:1]
	global_store_dwordx4 v[28:29], v[22:25], off
	global_load_dwordx2 v[28:29], v[26:27], off offset:344
	s_nop 0
	v_add_u32_e32 v22, 0x400, v21
	v_ashrrev_i32_e32 v22, 4, v22
	v_mad_u64_u32 v[24:25], s[34:35], v22, s23, v[0:1]
	v_ashrrev_i32_e32 v23, 31, v22
	v_lshl_add_u64 v[30:31], s[0:1], 0, v[22:23]
	ds_read_b128 v[22:25], v24
	s_waitcnt vmcnt(0) lgkmcnt(0)
	v_mad_u64_u32 v[28:29], s[34:35], v30, s68, v[28:29]
	v_mad_i32_i24 v29, v31, s68, v29
	v_lshl_add_u64 v[28:29], v[28:29], 0, s[94:95]
	v_lshl_add_u64 v[28:29], v[28:29], 0, v[0:1]
	global_store_dwordx4 v[28:29], v[22:25], off
	global_load_dwordx2 v[28:29], v[26:27], off offset:344
	s_nop 0
	v_add_u32_e32 v22, 0x500, v21
	v_ashrrev_i32_e32 v22, 4, v22
	v_mad_u64_u32 v[24:25], s[34:35], v22, s23, v[0:1]
	v_ashrrev_i32_e32 v23, 31, v22
	v_lshl_add_u64 v[30:31], s[0:1], 0, v[22:23]
	ds_read_b128 v[22:25], v24
	s_waitcnt vmcnt(0) lgkmcnt(0)
	v_mad_u64_u32 v[28:29], s[34:35], v30, s68, v[28:29]
	v_mad_i32_i24 v29, v31, s68, v29
	v_lshl_add_u64 v[28:29], v[28:29], 0, s[94:95]
	v_lshl_add_u64 v[28:29], v[28:29], 0, v[0:1]
	global_store_dwordx4 v[28:29], v[22:25], off
	global_load_dwordx2 v[28:29], v[26:27], off offset:344
	s_nop 0
	v_add_u32_e32 v22, 0x600, v21
	v_ashrrev_i32_e32 v22, 4, v22
	v_mad_u64_u32 v[24:25], s[34:35], v22, s23, v[0:1]
	v_ashrrev_i32_e32 v23, 31, v22
	v_lshl_add_u64 v[30:31], s[0:1], 0, v[22:23]
	ds_read_b128 v[22:25], v24
	v_add_u32_e32 v21, 0x700, v21
	s_waitcnt vmcnt(0) lgkmcnt(0)
	v_mad_u64_u32 v[28:29], s[34:35], v30, s68, v[28:29]
	v_mad_i32_i24 v29, v31, s68, v29
	v_lshl_add_u64 v[28:29], v[28:29], 0, s[94:95]
	v_lshl_add_u64 v[28:29], v[28:29], 0, v[0:1]
	global_store_dwordx4 v[28:29], v[22:25], off
	global_load_dwordx2 v[26:27], v[26:27], off offset:344
	s_nop 0
	v_ashrrev_i32_e32 v22, 4, v21
	v_mad_u64_u32 v[24:25], s[34:35], v22, s23, v[0:1]
	v_ashrrev_i32_e32 v23, 31, v22
	v_lshl_add_u64 v[28:29], s[0:1], 0, v[22:23]
	ds_read_b128 v[22:25], v24
	s_waitcnt vmcnt(0) lgkmcnt(0)
	v_mad_u64_u32 v[26:27], s[0:1], v28, s68, v[26:27]
	v_mad_i32_i24 v27, v29, s68, v27
	v_lshl_add_u64 v[26:27], v[26:27], 0, s[94:95]
	v_lshl_add_u64 v[26:27], v[26:27], 0, v[0:1]
	global_store_dwordx4 v[26:27], v[22:25], off
	s_cbranch_execnz .LBB0_572
	s_branch .LBB0_584

; __device__ __forceinline__ u16 f2bf(float f) { return (u16)(pack2(f, 0.f) & 0xffffu); }
; template <int NT, class VF, class RP>
; __device__ __forceinline__ void epi_staged_bf16(f32x4 (&acc)[4][NT], int r0, int c0, unsigned char* smem, VF vf, RP rowptr) {
;     ...
;   __syncthreads();
; #pragma unroll
;   for (int mi = 0; mi < 4; ++mi)
; #pragma unroll
;     for (int ni = 0; ni < NT; ++ni)
; #pragma unroll
;       for (int j = 0; j < 4; ++j) {
;         const int r = r0 + mi * 16 + j, c = c0 + ni * 16;
;         Ts[r * PITCH + c] = f2bf(vf(r, c, acc[mi][ni][j]));
;       }
;   __syncthreads();
; __device__ __forceinline__ void phase_mix_a(const Params& p, int l, bool last, unsigned char* smem) {
;     ...
;         if ((nt & 1) == 0) {
;           auto vf = [&](int r, int, float v) { return v * rs[r]; };
;           auto rp = [&](int r) -> u16* { return p.KN + (size_t)(row_base + r) * 512 + h * 128; };
;           epi_staged_bf16<4>(acc, r0, c0, smem, vf, rp);
.LBB0_584:
	v_mov_b32_e32 v0, v187
	s_waitcnt lgkmcnt(0)
	s_barrier
	ds_read_b128 v[22:25], v20
	v_lshlrev_b32_e32 v26, 1, v19
	s_waitcnt lgkmcnt(0)
	v_mul_f32_e32 v21, v74, v22
	v_cvt_pk_bf16_f32 v21, v21, s0
	v_mad_u64_u32 v[28:29], s[0:1], v18, s23, v[26:27]
	v_or_b32_e32 v18, 1, v18
	v_mul_f32_e32 v19, v75, v23
	ds_write_b16 v28, v21
	v_cvt_pk_bf16_f32 v21, v19, s0
	v_mad_u64_u32 v[18:19], s[0:1], v18, s23, v[26:27]
	v_mul_f32_e32 v19, v76, v24
	s_nop 0
	v_cvt_pk_bf16_f32 v19, v19, s0
	ds_write_b16 v18, v19 offset:272
	v_mul_f32_e32 v19, v77, v25
	v_cvt_pk_bf16_f32 v19, v19, s0
	ds_write_b16 v18, v19 offset:544
	v_mul_f32_e32 v19, v78, v22
	v_cvt_pk_bf16_f32 v19, v19, s0
	ds_write_b16 v28, v19 offset:32
	v_mul_f32_e32 v19, v79, v23
	v_cvt_pk_bf16_f32 v19, v19, s0
	ds_write_b16 v18, v19 offset:32
	v_mul_f32_e32 v19, v80, v24
	v_cvt_pk_bf16_f32 v19, v19, s0
	ds_write_b16 v18, v19 offset:304
	v_mul_f32_e32 v19, v81, v25
	v_cvt_pk_bf16_f32 v19, v19, s0
	ds_write_b16 v18, v19 offset:576
	v_mul_f32_e32 v19, v82, v22
	v_cvt_pk_bf16_f32 v19, v19, s0
	ds_write_b16 v28, v19 offset:64
	v_mul_f32_e32 v19, v83, v23
	v_cvt_pk_bf16_f32 v19, v19, s0
	ds_write_b16 v18, v19 offset:64
	v_mul_f32_e32 v19, v84, v24
	v_cvt_pk_bf16_f32 v19, v19, s0
	ds_write_b16 v18, v19 offset:336
	v_mul_f32_e32 v19, v85, v25
	v_cvt_pk_bf16_f32 v19, v19, s0
	ds_write_b16 v18, v19 offset:608
	v_mul_f32_e32 v19, v86, v22
	v_cvt_pk_bf16_f32 v19, v19, s0
	ds_write_b16 v28, v19 offset:96
	v_mul_f32_e32 v19, v87, v23
	v_cvt_pk_bf16_f32 v19, v19, s0
	ds_write_b16 v18, v19 offset:96
	v_mul_f32_e32 v19, v88, v24
	v_cvt_pk_bf16_f32 v19, v19, s0
	ds_write_b16 v18, v19 offset:368
	v_mul_f32_e32 v19, v89, v25
	ds_read_b128 v[22:25], v20 offset:64
	v_cvt_pk_bf16_f32 v19, v19, s0
	ds_write_b16 v18, v19 offset:640
	ds_write_b16 v18, v21
	s_waitcnt lgkmcnt(0)
	v_mul_f32_e32 v19, v54, v22
	v_cvt_pk_bf16_f32 v19, v19, s0
	ds_write_b16 v18, v19 offset:4080
	v_mul_f32_e32 v19, v55, v23
	v_cvt_pk_bf16_f32 v19, v19, s0
	ds_write_b16 v18, v19 offset:4352
	v_mul_f32_e32 v19, v56, v24
	v_cvt_pk_bf16_f32 v19, v19, s0
	ds_write_b16 v18, v19 offset:4624
	v_mul_f32_e32 v19, v57, v25
	v_cvt_pk_bf16_f32 v19, v19, s0
	ds_write_b16 v18, v19 offset:4896
	v_mul_f32_e32 v19, v58, v22
	v_cvt_pk_bf16_f32 v19, v19, s0
	ds_write_b16 v18, v19 offset:4112
	v_mul_f32_e32 v19, v59, v23
	v_cvt_pk_bf16_f32 v19, v19, s0
	ds_write_b16 v18, v19 offset:4384
	v_mul_f32_e32 v19, v60, v24
	v_cvt_pk_bf16_f32 v19, v19, s0
	ds_write_b16 v18, v19 offset:4656
	v_mul_f32_e32 v19, v61, v25
	v_cvt_pk_bf16_f32 v19, v19, s0
	ds_write_b16 v18, v19 offset:4928
	v_mul_f32_e32 v19, v62, v22
	v_cvt_pk_bf16_f32 v19, v19, s0
	ds_write_b16 v18, v19 offset:4144
	v_mul_f32_e32 v19, v63, v23
	v_cvt_pk_bf16_f32 v19, v19, s0
	ds_write_b16 v18, v19 offset:4416
	v_mul_f32_e32 v19, v64, v24
	v_cvt_pk_bf16_f32 v19, v19, s0
	ds_write_b16 v18, v19 offset:4688
	v_mul_f32_e32 v19, v65, v25
	v_cvt_pk_bf16_f32 v19, v19, s0
	ds_write_b16 v18, v19 offset:4960
	v_mul_f32_e32 v19, v66, v22
	v_cvt_pk_bf16_f32 v19, v19, s0
	ds_write_b16 v18, v19 offset:4176
	v_mul_f32_e32 v19, v67, v23
	v_cvt_pk_bf16_f32 v19, v19, s0
	ds_write_b16 v18, v19 offset:4448
	v_mul_f32_e32 v19, v68, v24
	v_cvt_pk_bf16_f32 v19, v19, s0
	ds_write_b16 v18, v19 offset:4720
	v_mul_f32_e32 v19, v69, v25
	ds_read_b128 v[22:25], v20 offset:128
	v_cvt_pk_bf16_f32 v19, v19, s0
	ds_write_b16 v18, v19 offset:4992
	s_waitcnt lgkmcnt(0)
	v_mul_f32_e32 v19, v38, v22
	v_cvt_pk_bf16_f32 v19, v19, s0
	ds_write_b16 v18, v19 offset:8432
	v_mul_f32_e32 v19, v39, v23
	v_cvt_pk_bf16_f32 v19, v19, s0
	ds_write_b16 v18, v19 offset:8704
	v_mul_f32_e32 v19, v40, v24
	v_cvt_pk_bf16_f32 v19, v19, s0
	ds_write_b16 v18, v19 offset:8976
	v_mul_f32_e32 v19, v41, v25
	v_cvt_pk_bf16_f32 v19, v19, s0
	ds_write_b16 v18, v19 offset:9248
	v_mul_f32_e32 v19, v42, v22
	v_cvt_pk_bf16_f32 v19, v19, s0
	ds_write_b16 v18, v19 offset:8464
	v_mul_f32_e32 v19, v43, v23
	v_cvt_pk_bf16_f32 v19, v19, s0
	ds_write_b16 v18, v19 offset:8736
	v_mul_f32_e32 v19, v44, v24
	v_cvt_pk_bf16_f32 v19, v19, s0
	ds_write_b16 v18, v19 offset:9008
	v_mul_f32_e32 v19, v45, v25
	v_cvt_pk_bf16_f32 v19, v19, s0
	ds_write_b16 v18, v19 offset:9280
	v_mul_f32_e32 v19, v46, v22
	v_cvt_pk_bf16_f32 v19, v19, s0
	ds_write_b16 v18, v19 offset:8496
	v_mul_f32_e32 v19, v47, v23
	v_cvt_pk_bf16_f32 v19, v19, s0
	ds_write_b16 v18, v19 offset:8768
	v_mul_f32_e32 v19, v48, v24
	v_cvt_pk_bf16_f32 v19, v19, s0
	ds_write_b16 v18, v19 offset:9040
	v_mul_f32_e32 v19, v49, v25
	v_cvt_pk_bf16_f32 v19, v19, s0
	ds_write_b16 v18, v19 offset:9312
	v_mul_f32_e32 v19, v34, v22
	v_cvt_pk_bf16_f32 v19, v19, s0
	ds_write_b16 v18, v19 offset:8528
	v_mul_f32_e32 v19, v35, v23
	ds_read_b128 v[20:23], v20 offset:192
	v_cvt_pk_bf16_f32 v19, v19, s0
	ds_write_b16 v18, v19 offset:8800
	v_mul_f32_e32 v19, v36, v24
	v_cvt_pk_bf16_f32 v19, v19, s0
	s_waitcnt lgkmcnt(0)
	v_mul_f32_e32 v2, v2, v20
	v_mul_f32_e32 v14, v14, v20
	v_mul_f32_e32 v10, v10, v20
	v_mul_f32_e32 v6, v6, v20
	v_cvt_pk_bf16_f32 v2, v2, s0
	v_cvt_pk_bf16_f32 v14, v14, s0
	v_cvt_pk_bf16_f32 v10, v10, s0
	v_cvt_pk_bf16_f32 v6, v6, s0
	ds_write_b16 v18, v2 offset:12880
	v_mul_f32_e32 v2, v3, v21
	ds_write_b16 v18, v14 offset:12784
	v_mul_f32_e32 v14, v15, v21
	ds_write_b16 v18, v10 offset:12816
	v_mul_f32_e32 v10, v11, v21
	ds_write_b16 v18, v6 offset:12848
	v_mul_f32_e32 v6, v7, v21
	v_cvt_pk_bf16_f32 v2, v2, s0
	v_cvt_pk_bf16_f32 v14, v14, s0
	v_cvt_pk_bf16_f32 v10, v10, s0
	v_cvt_pk_bf16_f32 v6, v6, s0
	ds_write_b16 v18, v2 offset:13152
	v_mul_f32_e32 v2, v4, v22
	ds_write_b16 v18, v14 offset:13056
	v_mul_f32_e32 v14, v16, v22
	ds_write_b16 v18, v10 offset:13088
	v_mul_f32_e32 v10, v12, v22
	ds_write_b16 v18, v6 offset:13120
	v_mul_f32_e32 v6, v8, v22
	v_cvt_pk_bf16_f32 v2, v2, s0
	v_cvt_pk_bf16_f32 v14, v14, s0
	v_cvt_pk_bf16_f32 v10, v10, s0
	v_cvt_pk_bf16_f32 v6, v6, s0
	ds_write_b16 v18, v2 offset:13424
	v_mul_f32_e32 v2, v5, v23
	ds_write_b16 v18, v19 offset:9072
	v_mul_f32_e32 v19, v37, v25
	ds_write_b16 v18, v14 offset:13328
	v_mul_f32_e32 v14, v17, v23
	ds_write_b16 v18, v10 offset:13360
	v_mul_f32_e32 v10, v13, v23
	ds_write_b16 v18, v6 offset:13392
	v_mul_f32_e32 v6, v9, v23
	v_cvt_pk_bf16_f32 v2, v2, s0
	v_cvt_pk_bf16_f32 v19, v19, s0
	v_cvt_pk_bf16_f32 v14, v14, s0
	v_cvt_pk_bf16_f32 v10, v10, s0
	v_cvt_pk_bf16_f32 v6, v6, s0
	ds_write_b16 v18, v2 offset:13696
	v_mov_b64_e32 v[2:3], s[40:41]
	ds_write_b16 v18, v19 offset:9344
	ds_write_b16 v18, v14 offset:13600
	ds_write_b16 v18, v10 offset:13632
	ds_write_b16 v18, v6 offset:13664
	s_waitcnt lgkmcnt(0)
	s_barrier
; template <int NT, class VF, class RP>
; __device__ __forceinline__ void epi_staged_bf16(f32x4 (&acc)[4][NT], int r0, int c0, unsigned char* smem, VF vf, RP rowptr) {
;     ...
;   for (int i = 0; i < CPR / 2; ++i) {
;     const int c = t + 256 * i, row = c / CPR, ch = c % CPR;
;     u16* d = rowptr(row);
;     if (d) *(u32x4*)(d + ch * 8) = *(const u32x4*)(Ts + row * PITCH + ch * 8);
;   }
; __device__ __forceinline__ void phase_mix_a(const Params& p, int l, bool last, unsigned char* smem) {
;     ...
;           auto rp = [&](int r) -> u16* { return p.KN + (size_t)(row_base + r) * 512 + h * 128; };
	s_load_dwordx2 s[100:101], s[40:41], 0x150
	s_waitcnt lgkmcnt(0)
	v_mov_b32_e32 v6, s100
	v_mov_b32_e32 v7, s101
	v_mov_b64_e32 v[2:3], 0
	v_mov_b64_e32 v[4:5], 0
	s_waitcnt lgkmcnt(0)
	v_cmp_ne_u64_e32 vcc, 0, v[6:7]
	s_and_saveexec_b64 s[0:1], vcc
	s_cbranch_execz .LBB0_586
	v_ashrrev_i32_e32 v4, 31, v0
	v_lshrrev_b32_e32 v4, 28, v4
	v_add_u32_e32 v10, v0, v4
	v_ashrrev_i32_e32 v11, 4, v10
	v_add_u32_e32 v4, s4, v11
	v_ashrrev_i32_e32 v5, 31, v4
	v_lshlrev_b64 v[4:5], 10, v[4:5]
	v_lshl_add_u64 v[8:9], v[6:7], 0, v[4:5]
	v_and_b32_e32 v4, -16, v10
	v_sub_u32_e32 v10, v0, v4
	v_mul_lo_u32 v4, v11, s23
	v_lshl_add_u32 v4, v10, 4, v4
	ds_read_b128 v[4:7], v4
	s_lshl_b32 s94, s5, 8
	v_lshlrev_b32_e32 v10, 3, v10
	v_lshl_add_u64 v[8:9], v[8:9], 0, s[94:95]
	v_ashrrev_i32_e32 v11, 31, v10
	v_lshl_add_u64 v[8:9], v[10:11], 1, v[8:9]
	s_waitcnt lgkmcnt(0)
	global_store_dwordx4 v[8:9], v[4:7], off
	s_nop 1
	v_mov_b64_e32 v[4:5], s[40:41]
	s_load_dwordx2 s[100:101], s[40:41], 0x150
	s_waitcnt lgkmcnt(0)
	v_mov_b32_e32 v4, s100
	v_mov_b32_e32 v5, s101
.LBB0_586:
	s_or_b64 exec, exec, s[0:1]
	s_waitcnt lgkmcnt(0)
	v_cmp_ne_u64_e32 vcc, 0, v[4:5]
	s_and_saveexec_b64 s[0:1], vcc
	s_cbranch_execz .LBB0_588
	v_add_u32_e32 v8, 0x100, v0
	v_ashrrev_i32_e32 v2, 31, v8
	v_lshrrev_b32_e32 v2, 28, v2
	v_add_u32_e32 v9, v8, v2
	v_ashrrev_i32_e32 v10, 4, v9
	v_add_u32_e32 v2, s4, v10
	v_ashrrev_i32_e32 v3, 31, v2
	v_lshlrev_b64 v[2:3], 10, v[2:3]
	v_lshl_add_u64 v[6:7], v[4:5], 0, v[2:3]
	v_and_b32_e32 v2, -16, v9
	v_sub_u32_e32 v8, v8, v2
	v_mul_lo_u32 v2, v10, s23
	v_lshl_add_u32 v2, v8, 4, v2
	ds_read_b128 v[2:5], v2
	s_lshl_b32 s94, s5, 8
	v_lshlrev_b32_e32 v8, 3, v8
	v_lshl_add_u64 v[6:7], v[6:7], 0, s[94:95]
	v_ashrrev_i32_e32 v9, 31, v8
	v_lshl_add_u64 v[6:7], v[8:9], 1, v[6:7]
	s_waitcnt lgkmcnt(0)
	global_store_dwordx4 v[6:7], v[2:5], off
	s_nop 1
	v_mov_b64_e32 v[2:3], s[40:41]
	s_load_dwordx2 s[100:101], s[40:41], 0x150
	s_waitcnt lgkmcnt(0)
	v_mov_b32_e32 v2, s100
	v_mov_b32_e32 v3, s101
.LBB0_588:
	s_or_b64 exec, exec, s[0:1]
	v_mov_b64_e32 v[4:5], 0
	s_waitcnt lgkmcnt(0)
	v_cmp_ne_u64_e32 vcc, 0, v[2:3]
	v_mov_b64_e32 v[6:7], 0
	s_and_saveexec_b64 s[0:1], vcc
	s_cbranch_execz .LBB0_590
	v_add_u32_e32 v8, 0x200, v0
	v_ashrrev_i32_e32 v6, 31, v8
	v_lshrrev_b32_e32 v6, 28, v6
	v_add_u32_e32 v9, v8, v6
	v_ashrrev_i32_e32 v10, 4, v9
	v_add_u32_e32 v6, s4, v10
	v_ashrrev_i32_e32 v7, 31, v6
	v_lshlrev_b64 v[6:7], 10, v[6:7]
	v_lshl_add_u64 v[2:3], v[2:3], 0, v[6:7]
	v_and_b32_e32 v6, -16, v9
	v_sub_u32_e32 v11, v8, v6
	v_mul_lo_u32 v6, v10, s23
	v_lshl_add_u32 v6, v11, 4, v6
	ds_read_b128 v[6:9], v6
	s_lshl_b32 s94, s5, 8
	v_lshlrev_b32_e32 v10, 3, v11
	v_lshl_add_u64 v[2:3], v[2:3], 0, s[94:95]
	v_ashrrev_i32_e32 v11, 31, v10
	v_lshl_add_u64 v[2:3], v[10:11], 1, v[2:3]
	s_waitcnt lgkmcnt(0)
	global_store_dwordx4 v[2:3], v[6:9], off
	v_mov_b64_e32 v[2:3], s[40:41]
	s_load_dwordx2 s[100:101], s[40:41], 0x150
	s_waitcnt lgkmcnt(0)
	v_mov_b32_e32 v6, s100
	v_mov_b32_e32 v7, s101
.LBB0_590:
	s_or_b64 exec, exec, s[0:1]
	s_waitcnt lgkmcnt(0)
	v_cmp_ne_u64_e32 vcc, 0, v[6:7]
	s_and_saveexec_b64 s[0:1], vcc
	s_cbranch_execz .LBB0_592
	v_add_u32_e32 v4, 0x300, v0
	v_ashrrev_i32_e32 v2, 31, v4
	v_lshrrev_b32_e32 v2, 28, v2
	v_add_u32_e32 v5, v4, v2
	v_ashrrev_i32_e32 v8, 4, v5
	v_add_u32_e32 v2, s4, v8
	v_ashrrev_i32_e32 v3, 31, v2
	v_lshlrev_b64 v[2:3], 10, v[2:3]
	v_lshl_add_u64 v[6:7], v[6:7], 0, v[2:3]
	v_and_b32_e32 v2, -16, v5
	v_sub_u32_e32 v9, v4, v2
	v_mul_lo_u32 v2, v8, s23
	v_lshl_add_u32 v2, v9, 4, v2
	ds_read_b128 v[2:5], v2
	s_lshl_b32 s94, s5, 8
	v_lshlrev_b32_e32 v8, 3, v9
	v_lshl_add_u64 v[6:7], v[6:7], 0, s[94:95]
	v_ashrrev_i32_e32 v9, 31, v8
	v_lshl_add_u64 v[6:7], v[8:9], 1, v[6:7]
	s_waitcnt lgkmcnt(0)
	global_store_dwordx4 v[6:7], v[2:5], off
	s_nop 1
	v_mov_b64_e32 v[2:3], s[40:41]
	s_load_dwordx2 s[100:101], s[40:41], 0x150
	s_waitcnt lgkmcnt(0)
	v_mov_b32_e32 v4, s100
	v_mov_b32_e32 v5, s101
; template <int NT, class VF, class RP>
; __device__ __forceinline__ void epi_staged_bf16(f32x4 (&acc)[4][NT], int r0, int c0, unsigned char* smem, VF vf, RP rowptr) {
;     ...
;   for (int i = 0; i < CPR / 2; ++i) {
;     const int c = t + 256 * i, row = c / CPR, ch = c % CPR;
;     u16* d = rowptr(row);
;     if (d) *(u32x4*)(d + ch * 8) = *(const u32x4*)(Ts + row * PITCH + ch * 8);
;   }
; __device__ __forceinline__ void phase_mix_a(const Params& p, int l, bool last, unsigned char* smem) {
;     ...
;           auto rp = [&](int r) -> u16* { return p.KN + (size_t)(row_base + r) * 512 + h * 128; };
.LBB0_592:
	s_or_b64 exec, exec, s[0:1]
	v_mov_b64_e32 v[2:3], 0
	s_waitcnt lgkmcnt(0)
	v_cmp_ne_u64_e32 vcc, 0, v[4:5]
	v_mov_b64_e32 v[6:7], 0
	s_and_saveexec_b64 s[0:1], vcc
	s_cbranch_execz .LBB0_594
	v_add_u32_e32 v10, 0x400, v0
	v_ashrrev_i32_e32 v6, 31, v10
	v_lshrrev_b32_e32 v6, 28, v6
	v_add_u32_e32 v11, v10, v6
	v_ashrrev_i32_e32 v12, 4, v11
	v_add_u32_e32 v6, s4, v12
	v_ashrrev_i32_e32 v7, 31, v6
	v_lshlrev_b64 v[6:7], 10, v[6:7]
	v_lshl_add_u64 v[8:9], v[4:5], 0, v[6:7]
	v_and_b32_e32 v4, -16, v11
	v_sub_u32_e32 v10, v10, v4
	v_mul_lo_u32 v4, v12, s23
	v_lshl_add_u32 v4, v10, 4, v4
	ds_read_b128 v[4:7], v4
	s_lshl_b32 s94, s5, 8
	v_lshlrev_b32_e32 v10, 3, v10
	v_lshl_add_u64 v[8:9], v[8:9], 0, s[94:95]
	v_ashrrev_i32_e32 v11, 31, v10
	v_lshl_add_u64 v[8:9], v[10:11], 1, v[8:9]
	s_waitcnt lgkmcnt(0)
	global_store_dwordx4 v[8:9], v[4:7], off
	s_nop 1
	v_mov_b64_e32 v[4:5], s[40:41]
	s_load_dwordx2 s[100:101], s[40:41], 0x150
	s_waitcnt lgkmcnt(0)
	v_mov_b32_e32 v6, s100
	v_mov_b32_e32 v7, s101
.LBB0_594:
	s_or_b64 exec, exec, s[0:1]
	s_waitcnt lgkmcnt(0)
	v_cmp_ne_u64_e32 vcc, 0, v[6:7]
	s_and_saveexec_b64 s[0:1], vcc
	s_cbranch_execz .LBB0_596
	v_add_u32_e32 v4, 0x500, v0
	v_ashrrev_i32_e32 v2, 31, v4
	v_lshrrev_b32_e32 v2, 28, v2
	v_add_u32_e32 v5, v4, v2
	v_ashrrev_i32_e32 v8, 4, v5
	v_add_u32_e32 v2, s4, v8
	v_ashrrev_i32_e32 v3, 31, v2
	v_lshlrev_b64 v[2:3], 10, v[2:3]
	v_lshl_add_u64 v[6:7], v[6:7], 0, v[2:3]
	v_and_b32_e32 v2, -16, v5
	v_sub_u32_e32 v9, v4, v2
	v_mul_lo_u32 v2, v8, s23
	v_lshl_add_u32 v2, v9, 4, v2
	ds_read_b128 v[2:5], v2
	s_lshl_b32 s94, s5, 8
	v_lshlrev_b32_e32 v8, 3, v9
	v_lshl_add_u64 v[6:7], v[6:7], 0, s[94:95]
	v_ashrrev_i32_e32 v9, 31, v8
	v_lshl_add_u64 v[6:7], v[8:9], 1, v[6:7]
	s_waitcnt lgkmcnt(0)
	global_store_dwordx4 v[6:7], v[2:5], off
	s_nop 1
	v_mov_b64_e32 v[2:3], s[40:41]
	s_load_dwordx2 s[100:101], s[40:41], 0x150
	s_waitcnt lgkmcnt(0)
	v_mov_b32_e32 v2, s100
	v_mov_b32_e32 v3, s101
.LBB0_596:
	s_or_b64 exec, exec, s[0:1]
	v_mov_b64_e32 v[4:5], 0
	s_waitcnt lgkmcnt(0)
	v_cmp_ne_u64_e32 vcc, 0, v[2:3]
	s_and_saveexec_b64 s[0:1], vcc
	s_cbranch_execz .LBB0_598
	v_add_u32_e32 v8, 0x600, v0
	v_ashrrev_i32_e32 v4, 31, v8
	v_lshrrev_b32_e32 v4, 28, v4
	v_add_u32_e32 v9, v8, v4
	v_ashrrev_i32_e32 v10, 4, v9
	v_add_u32_e32 v4, s4, v10
	v_ashrrev_i32_e32 v5, 31, v4
	v_lshlrev_b64 v[4:5], 10, v[4:5]
	v_lshl_add_u64 v[6:7], v[2:3], 0, v[4:5]
	v_and_b32_e32 v2, -16, v9
	v_sub_u32_e32 v8, v8, v2
	v_mul_lo_u32 v2, v10, s23
	v_lshl_add_u32 v2, v8, 4, v2
	ds_read_b128 v[2:5], v2
	s_lshl_b32 s94, s5, 8
	v_lshlrev_b32_e32 v8, 3, v8
	v_lshl_add_u64 v[6:7], v[6:7], 0, s[94:95]
	v_ashrrev_i32_e32 v9, 31, v8
	v_lshl_add_u64 v[6:7], v[8:9], 1, v[6:7]
	s_waitcnt lgkmcnt(0)
	global_store_dwordx4 v[6:7], v[2:5], off
	s_nop 1
	v_mov_b64_e32 v[2:3], s[40:41]
	s_load_dwordx2 s[100:101], s[40:41], 0x150
	s_waitcnt lgkmcnt(0)
	v_mov_b32_e32 v4, s100
	v_mov_b32_e32 v5, s101
.LBB0_598:
	s_or_b64 exec, exec, s[0:1]
	s_waitcnt lgkmcnt(0)
	v_cmp_ne_u64_e32 vcc, 0, v[4:5]
	s_and_saveexec_b64 s[0:1], vcc
	s_cbranch_execz .LBB0_571
	v_add_u32_e32 v0, 0x700, v0
	v_ashrrev_i32_e32 v2, 31, v0
	v_lshrrev_b32_e32 v2, 28, v2
	v_add_u32_e32 v8, v0, v2
	v_ashrrev_i32_e32 v9, 4, v8
	v_add_u32_e32 v2, s4, v9
	v_ashrrev_i32_e32 v3, 31, v2
	v_lshlrev_b64 v[2:3], 10, v[2:3]
	v_lshl_add_u64 v[6:7], v[4:5], 0, v[2:3]
	v_and_b32_e32 v2, -16, v8
	v_sub_u32_e32 v0, v0, v2
	v_mul_lo_u32 v2, v9, s23
	v_lshl_add_u32 v2, v0, 4, v2
	ds_read_b128 v[2:5], v2
	s_lshl_b32 s94, s5, 8
	v_lshlrev_b32_e32 v8, 3, v0
	v_lshl_add_u64 v[6:7], v[6:7], 0, s[94:95]
	v_ashrrev_i32_e32 v9, 31, v8
	v_lshl_add_u64 v[6:7], v[8:9], 1, v[6:7]
	s_waitcnt lgkmcnt(0)
	global_store_dwordx4 v[6:7], v[2:5], off
	s_branch .LBB0_571

; __device__ __forceinline__ int tid_() { int t = threadIdx.x; asm volatile("" : "+v"(t)); return t; }
; #define XCD_FOR(u, T)                                                                                         \
;   for (int _x = bid_() & 7, _gb = gridDim.x >> 3, _hi = (int)(((long)(_x + 1) * (T)) >> 3),                    \
;            u = (int)(((long)_x * (T)) >> 3) + (bid_() >> 3);                                                  \
;        u < _hi; u += _gb)
; template <int NT, bool BKN, bool MASK = false, bool ROWSS = false, class Epi> ...
;     ...
;   const int t = tid_(), lane = t & 63, wid = t >> 6, wr = wid >> 1, wc = wid & 1, l16 = lane & 15, quad = lane >> 4;
;   const u16* ap[4];
;   const u16* bp[NT];
;   unsigned amask = 0u;
; #pragma unroll
;   for (int i = 0; i < 4; ++i) {
;     const int row = (t >> 3) + 32 * i;
;     const bool v = MASK ? (row < mvalid) : true;
;     amask |= v ? (1u << i) : 0u;
;     int r = v ? row : 0;
;     if (arows) r = arows[r];
;     ap[i] = A + (size_t)r * lda + (t & 7) * 8;
;   }
; #pragma unroll
;   for (int i = 0; i < NT; ++i) {
;     if (!BKN) bp[i] = B + (size_t)((t >> 3) + 32 * i) * ldb + (t & 7) * 8;
;     else { const int c = t + 256 * i; bp[i] = B + (size_t)(c / CPR) * ldb + (c % CPR) * 8; }
;   }
;   const size_t bstep = BKN ? (size_t)64 * ldb : (size_t)64;
;   int nmi = 4;
;   if (MASK) { nmi = (mvalid - wr * 64 + 15) >> 4; nmi = nmi < 0 ? 0 : (nmi > 4 ? 4 : nmi); nmi = __builtin_amdgcn_readfirstlane(nmi); }
;   u32x4 ra0[4], rb0[NT], ra1[4], rb1[NT];
; __device__ __forceinline__ void phase_mix_a(const Params& p, int l, bool last, unsigned char* smem) {
;     ...
;     XCD_FOR(t, 512) {
;       const int nh = t & 1, n1 = (t >> 1) & 127, b = t >> 8;
;       auto epi = [&](f32x4(&acc)[4][4], int r0, int c0) {
;         auto vf = [&](int, int, float v) { return v; };
;         auto rp = [&](int m) -> u16* { const int rip = m >> 6, k2 = m & 63; return p.PF + ((size_t)((b * 64 + k2) * 2 + rip) * 128 + n1) * 256 + nh * 128; };
;         epi_staged_bf16<4>(acc, r0, c0, smem, vf, rp);
;       };
;       gemm_tile<4, true>(p.M1 + (size_t)n1 * 16384, 128, nullptr, 128, p.GD + (size_t)b * 2 * SEQ * 256 + (size_t)n1 * 256 + nh * 128, 128 * 256, 128, smem, epi);
.LBB0_608:
	v_mov_b64_e32 v[34:35], s[40:41]
	s_waitcnt vmcnt(0) lgkmcnt(0)
	global_load_dwordx2 v[2:3], v[34:35], off offset:248
	global_load_dwordx2 v[4:5], v[34:35], off offset:304
	v_mov_b32_e32 v46, v187
	s_ashr_i32 s4, s9, 8
	s_bfe_u32 s19, s9, 0x70001
	v_ashrrev_i32_e32 v9, 31, v46
	s_ashr_i32 s5, s4, 31
	v_lshrrev_b32_e32 v9, 28, v9
	s_lshl_b32 s94, s19, 15
	s_lshl_b64 s[34:35], s[4:5], 23
	v_ashrrev_i32_e32 v6, 3, v46
	v_lshlrev_b32_e32 v8, 4, v46
	v_add_u32_e32 v9, v46, v9
	s_and_b32 s0, s18, 0x80
	v_and_b32_e32 v0, 0x70, v8
	v_ashrrev_i32_e32 v7, 31, v6
	v_and_b32_e32 v17, 0xffffff80, v8
	v_ashrrev_i32_e32 v8, 4, v9
	s_mov_b32 s1, s95
	s_lshl_b32 s0, s0, 1
	v_add_u32_e32 v14, 0x100, v46
	v_lshlrev_b64 v[6:7], 8, v[6:7]
	v_and_b32_e32 v18, -16, v9
	v_ashrrev_i32_e32 v9, 31, v8
	v_lshrrev_b32_e32 v47, 4, v46
	v_add_u32_e32 v15, 0x200, v46
	v_ashrrev_i32_e32 v10, 31, v14
	v_and_b32_e32 v86, -8, v8
	v_and_b32_e32 v87, 7, v8
	v_lshlrev_b64 v[8:9], 16, v[8:9]
	v_add_u32_e32 v16, 0x300, v46
	v_ashrrev_i32_e32 v11, 31, v15
	v_xor_b32_e32 v13, v47, v46
	v_lshrrev_b32_e32 v10, 28, v10
	v_ashrrev_i32_e32 v12, 31, v16
	v_lshrrev_b32_e32 v11, 28, v11
	v_lshlrev_b32_e32 v13, 4, v13
	v_add_u32_e32 v10, v14, v10
	v_lshrrev_b32_e32 v12, 28, v12
	v_add_u32_e32 v11, v15, v11
	v_and_or_b32 v128, v13, s14, v17
	v_sub_u32_e32 v17, v46, v18
	v_ashrrev_i32_e32 v80, 4, v10
	v_and_b32_e32 v18, -16, v10
	v_add_u32_e32 v12, v16, v12
	v_ashrrev_i32_e32 v40, 4, v11
	v_and_b32_e32 v19, -16, v11
	s_movk_i32 s5, 0x6000
	v_ashrrev_i32_e32 v36, 4, v12
	v_and_b32_e32 v20, -16, v12
	v_lshlrev_b32_e32 v82, 3, v17
	v_ashrrev_i32_e32 v83, 31, v82
	v_ashrrev_i32_e32 v37, 31, v36
	s_waitcnt lgkmcnt(0)
	s_barrier
	v_ashrrev_i32_e32 v41, 31, v40
	v_sub_u32_e32 v88, v16, v20
	v_ashrrev_i32_e32 v81, 31, v80
	v_lshlrev_b32_e32 v38, 3, v88
	v_ashrrev_i32_e32 v39, 31, v38
	v_and_b32_e32 v44, 15, v46
	v_bfe_u32 v108, v46, 1, 3
	v_ashrrev_i32_e32 v45, 7, v46
	v_bfe_u32 v161, v46, 6, 1
	v_bfe_u32 v163, v46, 4, 2
	v_bitop3_b32 v46, v163, v108, 4 bitop3:0x36
	v_lshlrev_b32_e32 v46, 4, v46
	s_waitcnt vmcnt(0)
	v_lshl_add_u64 v[2:3], v[2:3], 0, s[94:95]
	v_lshl_add_u64 v[4:5], v[4:5], 0, s[34:35]
	s_lshl_b32 s94, s19, 9
	v_lshl_add_u64 v[4:5], v[4:5], 0, s[94:95]
	v_lshl_add_u64 v[2:3], v[2:3], 0, v[0:1]
	v_lshl_add_u64 v[4:5], v[4:5], 0, s[0:1]
	v_lshl_add_u64 v[2:3], v[2:3], 0, v[6:7]
	v_lshl_add_u64 v[6:7], v[4:5], 0, v[8:9]
	v_add_co_u32_e32 v8, vcc, s70, v2
	global_load_dwordx4 v[48:51], v[2:3], off
	s_nop 0
	v_addc_co_u32_e32 v9, vcc, 0, v3, vcc
	v_add_co_u32_e32 v10, vcc, s69, v2
	v_lshl_add_u64 v[6:7], v[82:83], 1, v[6:7]
	s_nop 0
	v_addc_co_u32_e32 v11, vcc, 0, v3, vcc
	v_add_co_u32_e32 v12, vcc, s5, v2
	v_sub_u32_e32 v0, v14, v18
	s_nop 0
	v_addc_co_u32_e32 v13, vcc, 0, v3, vcc
	global_load_dwordx4 v[52:55], v[8:9], off
	global_load_dwordx4 v[56:59], v[10:11], off
	global_load_dwordx4 v[60:63], v[12:13], off
	global_load_dwordx4 v[64:67], v[6:7], off
	v_lshlrev_b64 v[12:13], 16, v[36:37]
	v_or_b32_e32 v37, 4, v82
	v_sub_u32_e32 v83, v15, v19
	v_lshlrev_b32_e32 v14, 9, v17
	v_lshlrev_b32_e32 v15, 5, v17
	v_lshlrev_b64 v[10:11], 16, v[40:41]
	v_lshlrev_b32_e32 v41, 6, v37
	v_lshlrev_b32_e32 v37, 2, v37
	v_bitop3_b32 v15, v15, v86, 32 bitop3:0x6c
	v_or_b32_e32 v16, v87, v14
	v_or_b32_e32 v17, 2, v82
	v_or_b32_e32 v18, 3, v82
	v_and_b32_e32 v37, 48, v37
	v_add_u32_e32 v14, v15, v14
	v_add_lshl_u32 v129, v16, v15, 1
	v_lshlrev_b32_e32 v15, 6, v17
	v_lshlrev_b32_e32 v16, 2, v17
	v_lshlrev_b32_e32 v17, 6, v18
	v_lshlrev_b32_e32 v18, 2, v18
	v_xad_u32 v37, v37, v86, v41
	v_lshlrev_b64 v[8:9], 16, v[80:81]
	v_or_b32_e32 v14, v14, v87
	v_and_b32_e32 v16, 40, v16
	v_and_b32_e32 v18, 40, v18
	v_or_b32_e32 v37, v37, v87
	v_lshlrev_b32_e32 v130, 1, v14
	v_xad_u32 v14, v16, v86, v15
	v_xad_u32 v15, v18, v86, v17
	v_lshl_add_u64 v[8:9], v[4:5], 0, v[8:9]
	v_lshl_add_u64 v[16:17], v[4:5], 0, v[10:11]
	v_lshl_add_u64 v[4:5], v[4:5], 0, v[12:13]
	v_lshlrev_b32_e32 v133, 1, v37
	v_or_b32_e32 v37, 5, v82
	v_lshl_add_u64 v[4:5], v[38:39], 1, v[4:5]
	v_lshlrev_b32_e32 v39, 6, v37
	v_lshlrev_b32_e32 v37, 2, v37
	v_and_b32_e32 v37, 48, v37
	v_xad_u32 v37, v37, v86, v39
	v_or_b32_e32 v37, v37, v87
	v_lshlrev_b32_e32 v134, 1, v37
	v_or_b32_e32 v37, 6, v82
	v_lshlrev_b32_e32 v39, 6, v37
	v_lshlrev_b32_e32 v37, 2, v37
	v_and_b32_e32 v37, 56, v37
	v_xad_u32 v37, v37, v86, v39
	v_or_b32_e32 v37, v37, v87
	v_lshlrev_b32_e32 v135, 1, v37
	v_or_b32_e32 v37, 7, v82
	v_lshlrev_b32_e32 v39, 6, v37
	v_lshlrev_b32_e32 v37, 2, v37
	v_and_b32_e32 v37, 56, v37
	v_xad_u32 v37, v37, v86, v39
	v_or_b32_e32 v37, v37, v87
	v_lshlrev_b32_e32 v84, 3, v0
	v_lshlrev_b32_e32 v42, 3, v83
	v_lshlrev_b32_e32 v136, 1, v37
	v_and_b32_e32 v37, -8, v80
	v_lshlrev_b32_e32 v41, 9, v0
	v_lshlrev_b32_e32 v0, 5, v0
	v_ashrrev_i32_e32 v43, 31, v42
	v_or_b32_e32 v14, v14, v87
	v_or_b32_e32 v15, v15, v87
	s_mov_b64 s[34:35], 0x2000
	v_and_b32_e32 v39, 7, v80
	v_bitop3_b32 v0, v0, v37, 32 bitop3:0x6c
	v_lshlrev_b32_e32 v131, 1, v14
	v_lshlrev_b32_e32 v132, 1, v15
	v_lshl_add_u64 v[14:15], v[2:3], 0, s[34:35]
	v_lshl_add_u64 v[18:19], v[2:3], 0, s[62:63]
	v_lshl_add_u64 v[22:23], v[2:3], 0, s[24:25]
	global_load_dwordx4 v[10:13], v[2:3], off offset:128
	v_lshl_add_u64 v[2:3], v[42:43], 1, v[16:17]
	v_add_u32_e32 v43, v0, v41
	v_or_b32_e32 v41, v39, v41
	v_or_b32_e32 v43, v43, v39
	v_add_lshl_u32 v0, v41, v0, 1
	v_or_b32_e32 v41, 2, v84
	v_lshlrev_b32_e32 v137, 1, v43
	v_lshlrev_b32_e32 v43, 6, v41
	v_lshlrev_b32_e32 v41, 2, v41
	v_and_b32_e32 v41, 40, v41
	v_xad_u32 v41, v41, v37, v43
	v_or_b32_e32 v41, v41, v39
	v_lshlrev_b32_e32 v138, 1, v41
; template <int NT, bool BKN, bool MASK = false, bool ROWSS = false, class Epi> ...
;     ...
;   GEMM_LOAD(ra0, rb0, 0);
;   GEMM_LOAD(ra1, rb1, 1);
;   GEMM_STORE(ra0, rb0, 0);
;   GEMM_LOAD(ra0, rb0, (2 < nkm1 ? 2 : nkm1));
;   __syncthreads();
	v_or_b32_e32 v41, 3, v84
	v_lshlrev_b32_e32 v43, 6, v41
	v_lshlrev_b32_e32 v41, 2, v41
	v_and_b32_e32 v41, 40, v41
	v_xad_u32 v41, v41, v37, v43
	v_or_b32_e32 v41, v41, v39
	v_lshlrev_b32_e32 v139, 1, v41
	v_or_b32_e32 v41, 4, v84
	v_lshlrev_b32_e32 v43, 6, v41
	v_lshlrev_b32_e32 v41, 2, v41
	v_and_b32_e32 v41, 48, v41
	v_xad_u32 v41, v41, v37, v43
	v_or_b32_e32 v41, v41, v39
	v_lshlrev_b32_e32 v140, 1, v41
	v_or_b32_e32 v41, 5, v84
	v_ashrrev_i32_e32 v85, 31, v84
	v_lshlrev_b32_e32 v43, 6, v41
	v_lshlrev_b32_e32 v41, 2, v41
	v_lshl_add_u64 v[8:9], v[84:85], 1, v[8:9]
	v_and_b32_e32 v41, 48, v41
	global_load_dwordx4 v[68:71], v[8:9], off
	s_nop 0
	global_load_dwordx4 v[14:17], v[14:15], off offset:128
	s_nop 0
	global_load_dwordx4 v[18:21], v[18:19], off offset:128
	s_nop 0
	global_load_dwordx4 v[22:25], v[22:23], off offset:128
	s_nop 0
	global_load_dwordx4 v[72:75], v[2:3], off
	global_load_dwordx4 v[76:79], v[4:5], off
	v_xad_u32 v41, v41, v37, v43
	v_or_b32_e32 v41, v41, v39
	v_lshlrev_b32_e32 v141, 1, v41
	v_or_b32_e32 v41, 6, v84
	v_lshlrev_b32_e32 v43, 6, v41
	v_lshlrev_b32_e32 v41, 2, v41
	v_and_b32_e32 v41, 56, v41
	s_mov_b32 s5, 0x400000
	v_xad_u32 v41, v41, v37, v43
	v_add_co_u32_e32 v6, vcc, s5, v6
	v_or_b32_e32 v41, v41, v39
	s_nop 0
	v_addc_co_u32_e32 v7, vcc, 0, v7, vcc
	v_lshlrev_b32_e32 v142, 1, v41
	v_or_b32_e32 v41, 7, v84
	v_add_co_u32_e32 v8, vcc, s5, v8
	v_lshlrev_b32_e32 v43, 6, v41
	v_lshlrev_b32_e32 v41, 2, v41
	v_addc_co_u32_e32 v9, vcc, 0, v9, vcc
	v_and_b32_e32 v41, 56, v41
	v_add_co_u32_e32 v2, vcc, s5, v2
	v_xad_u32 v37, v41, v37, v43
	s_nop 0
	v_addc_co_u32_e32 v3, vcc, 0, v3, vcc
	v_or_b32_e32 v37, v37, v39
	v_add_co_u32_e32 v4, vcc, s5, v4
	v_lshlrev_b32_e32 v143, 1, v37
	v_and_b32_e32 v37, -8, v40
	v_lshlrev_b32_e32 v41, 5, v83
	v_addc_co_u32_e32 v5, vcc, 0, v5, vcc
	v_and_b32_e32 v39, 7, v40
	v_lshlrev_b32_e32 v40, 9, v83
	v_bitop3_b32 v41, v41, v37, 32 bitop3:0x6c
	global_load_dwordx4 v[30:33], v[6:7], off
	global_load_dwordx4 v[26:29], v[8:9], off
	s_nop 0
	global_load_dwordx4 v[6:9], v[2:3], off
	s_nop 0
	global_load_dwordx4 v[2:5], v[4:5], off
	v_add_u32_e32 v43, v41, v40
	v_or_b32_e32 v40, v39, v40
	v_add_lshl_u32 v145, v40, v41, 1
	v_or_b32_e32 v40, 2, v42
	v_lshlrev_b32_e32 v41, 6, v40
	v_lshlrev_b32_e32 v40, 2, v40
	v_and_b32_e32 v40, 40, v40
	v_xad_u32 v40, v40, v37, v41
	v_or_b32_e32 v40, v40, v39
	v_lshlrev_b32_e32 v146, 1, v40
	v_or_b32_e32 v40, 3, v42
	v_lshlrev_b32_e32 v41, 6, v40
	v_lshlrev_b32_e32 v40, 2, v40
	v_and_b32_e32 v40, 40, v40
	v_xad_u32 v40, v40, v37, v41
	v_or_b32_e32 v40, v40, v39
	v_lshlrev_b32_e32 v147, 1, v40
	v_or_b32_e32 v40, 4, v42
	v_lshlrev_b32_e32 v41, 6, v40
	v_lshlrev_b32_e32 v40, 2, v40
	v_and_b32_e32 v40, 48, v40
	v_xad_u32 v40, v40, v37, v41
	v_or_b32_e32 v40, v40, v39
	v_lshlrev_b32_e32 v148, 1, v40
	v_or_b32_e32 v40, 5, v42
	v_lshlrev_b32_e32 v41, 6, v40
	v_lshlrev_b32_e32 v40, 2, v40
	v_and_b32_e32 v40, 48, v40
	v_xad_u32 v40, v40, v37, v41
	v_or_b32_e32 v40, v40, v39
	v_lshlrev_b32_e32 v149, 1, v40
	v_or_b32_e32 v40, 6, v42
	v_lshlrev_b32_e32 v41, 6, v40
	v_lshlrev_b32_e32 v40, 2, v40
	v_and_b32_e32 v40, 56, v40
	v_xad_u32 v40, v40, v37, v41
	v_or_b32_e32 v40, v40, v39
	v_lshlrev_b32_e32 v150, 1, v40
	v_or_b32_e32 v40, 7, v42
	v_lshlrev_b32_e32 v41, 6, v40
	v_lshlrev_b32_e32 v40, 2, v40
	v_and_b32_e32 v40, 56, v40
	v_xad_u32 v37, v40, v37, v41
	v_or_b32_e32 v37, v37, v39
	v_lshlrev_b32_e32 v151, 1, v37
	v_and_b32_e32 v37, -8, v36
	v_lshlrev_b32_e32 v40, 5, v88
	v_or_b32_e32 v43, v43, v39
	v_and_b32_e32 v36, 7, v36
	v_lshlrev_b32_e32 v39, 9, v88
	v_bitop3_b32 v40, v40, v37, 32 bitop3:0x6c
	v_add_u32_e32 v41, v40, v39
	v_or_b32_e32 v39, v36, v39
	v_add_lshl_u32 v153, v39, v40, 1
	v_or_b32_e32 v39, 2, v38
	v_lshlrev_b32_e32 v40, 6, v39
	v_lshlrev_b32_e32 v39, 2, v39
	v_and_b32_e32 v39, 40, v39
	v_xad_u32 v39, v39, v37, v40
	v_or_b32_e32 v39, v39, v36
	v_lshlrev_b32_e32 v154, 1, v39
	v_or_b32_e32 v39, 3, v38
	v_lshlrev_b32_e32 v40, 6, v39
	v_lshlrev_b32_e32 v39, 2, v39
	v_and_b32_e32 v39, 40, v39
	v_xad_u32 v39, v39, v37, v40
	v_or_b32_e32 v39, v39, v36
	v_lshlrev_b32_e32 v155, 1, v39
	v_or_b32_e32 v39, 4, v38
	v_lshlrev_b32_e32 v40, 6, v39
	v_lshlrev_b32_e32 v39, 2, v39
	v_and_b32_e32 v39, 48, v39
	v_xad_u32 v39, v39, v37, v40
	v_or_b32_e32 v39, v39, v36
	v_lshlrev_b32_e32 v156, 1, v39
	v_or_b32_e32 v39, 5, v38
	v_lshlrev_b32_e32 v40, 6, v39
	v_lshlrev_b32_e32 v39, 2, v39
	v_and_b32_e32 v39, 48, v39
	v_xad_u32 v39, v39, v37, v40
	v_or_b32_e32 v39, v39, v36
	v_lshlrev_b32_e32 v157, 1, v39
	v_or_b32_e32 v39, 6, v38
	v_lshlrev_b32_e32 v40, 6, v39
	v_lshlrev_b32_e32 v39, 2, v39
	v_and_b32_e32 v39, 56, v39
	v_xad_u32 v39, v39, v37, v40
	v_or_b32_e32 v39, v39, v36
	v_or_b32_e32 v38, 7, v38
	v_lshlrev_b32_e32 v158, 1, v39
	v_lshlrev_b32_e32 v39, 6, v38
	v_lshlrev_b32_e32 v38, 2, v38
	v_and_b32_e32 v38, 56, v38
	v_xad_u32 v37, v38, v37, v39
	v_or_b32_e32 v41, v41, v36
	v_or_b32_e32 v36, v37, v36
	v_lshlrev_b32_e32 v152, 1, v41
	v_lshlrev_b32_e32 v159, 1, v36
	v_bitop3_b32 v36, v47, v108, 3 bitop3:0x6c
	v_lshlrev_b32_e32 v41, 7, v44
	v_lshlrev_b32_e32 v40, 4, v36
	v_lshl_or_b32 v47, v45, 13, v41
	v_lshlrev_b32_e32 v144, 1, v43
	v_or_b32_e32 v160, v40, v47
	s_waitcnt vmcnt(0) lgkmcnt(0)
	ds_write_b128 v128, v[48:51]
	ds_write_b128 v128, v[52:55] offset:4096
	ds_write_b128 v128, v[56:59] offset:8192
	ds_write_b128 v128, v[60:63] offset:12288
	ds_write_b16 v130, v64 offset:16384
	ds_write_b16_d16_hi v129, v64 offset:16512
	ds_write_b16 v131, v65 offset:16384
	ds_write_b16_d16_hi v132, v65 offset:16384
	ds_write_b16 v133, v66 offset:16384
	ds_write_b16_d16_hi v134, v66 offset:16384
	ds_write_b16 v135, v67 offset:16384
	ds_write_b16_d16_hi v136, v67 offset:16384
	ds_write_b16 v137, v68 offset:16384
	ds_write_b16_d16_hi v0, v68 offset:16512
	ds_write_b16 v138, v69 offset:16384
	ds_write_b16_d16_hi v139, v69 offset:16384
	ds_write_b16 v140, v70 offset:16384
	ds_write_b16_d16_hi v141, v70 offset:16384
	ds_write_b16 v142, v71 offset:16384
	ds_write_b16_d16_hi v143, v71 offset:16384
	ds_write_b16 v144, v72 offset:16384
	ds_write_b16_d16_hi v145, v72 offset:16512
	ds_write_b16 v146, v73 offset:16384
	ds_write_b16_d16_hi v147, v73 offset:16384
	ds_write_b16 v148, v74 offset:16384
	ds_write_b16_d16_hi v149, v74 offset:16384
	ds_write_b16 v150, v75 offset:16384
	ds_write_b16_d16_hi v151, v75 offset:16384
	ds_write_b16 v152, v76 offset:16384
	ds_write_b16_d16_hi v153, v76 offset:16512
	ds_write_b16 v154, v77 offset:16384
	ds_write_b16_d16_hi v155, v77 offset:16384
	ds_write_b16 v156, v78 offset:16384
	ds_write_b16_d16_hi v157, v78 offset:16384
	ds_write_b16 v158, v79 offset:16384
	ds_write_b16_d16_hi v159, v79 offset:16384
	s_waitcnt lgkmcnt(0)
	s_barrier
; template <int NT, bool BKN, bool MASK = false, bool ROWSS = false, class Epi> ...
;     ...
;   GEMM_COMPUTE(0);
;   GEMM_STORE(ra1, rb1, 1);
;   __syncthreads();
;   GEMM_COMPUTE(1);
	ds_read_b128 v[36:39], v160
	v_lshl_or_b32 v112, v161, 13, v41
	v_or_b32_e32 v162, v40, v112
	ds_read_b128 v[40:43], v162 offset:16384
	ds_read_b128 v[48:51], v160 offset:2048
	ds_read_b128 v[52:55], v162 offset:18432
	ds_read_b128 v[64:67], v162 offset:20480
	ds_read_b128 v[68:71], v162 offset:22528
	ds_read_b128 v[88:91], v160 offset:4096
	ds_read_b128 v[92:95], v160 offset:6144
	v_or_b32_e32 v164, v46, v47
	ds_read_b128 v[108:111], v164
	v_or_b32_e32 v165, v46, v112
	s_waitcnt lgkmcnt(7)
	v_mfma_f32_16x16x32_bf16 v[56:59], v[36:39], v[40:43], 0
	s_lshl_b32 s19, s4, 7
	s_waitcnt lgkmcnt(5)
	v_mfma_f32_16x16x32_bf16 v[60:63], v[36:39], v[52:55], 0
	s_waitcnt lgkmcnt(4)
	v_mfma_f32_16x16x32_bf16 v[72:75], v[36:39], v[64:67], 0
	s_waitcnt lgkmcnt(3)
	v_mfma_f32_16x16x32_bf16 v[36:39], v[36:39], v[68:71], 0
	v_mfma_f32_16x16x32_bf16 v[76:79], v[48:51], v[40:43], 0
	v_mfma_f32_16x16x32_bf16 v[80:83], v[48:51], v[52:55], 0
	v_mfma_f32_16x16x32_bf16 v[84:87], v[48:51], v[64:67], 0
	v_mfma_f32_16x16x32_bf16 v[48:51], v[48:51], v[68:71], 0
	s_waitcnt lgkmcnt(2)
	v_mfma_f32_16x16x32_bf16 v[96:99], v[88:91], v[40:43], 0
	v_mfma_f32_16x16x32_bf16 v[100:103], v[88:91], v[52:55], 0
	v_mfma_f32_16x16x32_bf16 v[104:107], v[88:91], v[64:67], 0
	v_mfma_f32_16x16x32_bf16 v[88:91], v[88:91], v[68:71], 0
	s_waitcnt lgkmcnt(1)
	v_mfma_f32_16x16x32_bf16 v[40:43], v[92:95], v[40:43], 0
	v_mfma_f32_16x16x32_bf16 v[52:55], v[92:95], v[52:55], 0
	v_mfma_f32_16x16x32_bf16 v[64:67], v[92:95], v[64:67], 0
	v_mfma_f32_16x16x32_bf16 v[68:71], v[92:95], v[68:71], 0
	ds_read_b128 v[92:95], v165 offset:16384
	ds_read_b128 v[112:115], v164 offset:2048
	ds_read_b128 v[116:119], v165 offset:18432
	ds_read_b128 v[120:123], v165 offset:20480
	ds_read_b128 v[124:127], v165 offset:22528
	s_waitcnt lgkmcnt(4)
	v_mfma_f32_16x16x32_bf16 v[56:59], v[108:111], v[92:95], v[56:59]
	s_waitcnt lgkmcnt(2)
	v_mfma_f32_16x16x32_bf16 v[60:63], v[108:111], v[116:119], v[60:63]
	s_waitcnt lgkmcnt(1)
	v_mfma_f32_16x16x32_bf16 v[72:75], v[108:111], v[120:123], v[72:75]
	s_waitcnt lgkmcnt(0)
	v_mfma_f32_16x16x32_bf16 v[36:39], v[108:111], v[124:127], v[36:39]
	v_mfma_f32_16x16x32_bf16 v[76:79], v[112:115], v[92:95], v[76:79]
	v_mfma_f32_16x16x32_bf16 v[80:83], v[112:115], v[116:119], v[80:83]
	v_mfma_f32_16x16x32_bf16 v[84:87], v[112:115], v[120:123], v[84:87]
	v_mfma_f32_16x16x32_bf16 v[46:49], v[112:115], v[124:127], v[48:51]
	ds_read_b128 v[108:111], v164 offset:4096
	ds_read_b128 v[112:115], v164 offset:6144
	ds_write_b128 v128, v[10:13] offset:32768
	ds_write_b128 v128, v[14:17] offset:36864
	ds_write_b128 v128, v[18:21] offset:40960
	ds_write_b128 v128, v[22:25] offset:45056
	ds_write_b16 v130, v30 offset:49152
	ds_write_b16_d16_hi v129, v30 offset:49280
	ds_write_b16 v131, v31 offset:49152
	ds_write_b16_d16_hi v132, v31 offset:49152
	ds_write_b16 v133, v32 offset:49152
	ds_write_b16_d16_hi v134, v32 offset:49152
	ds_write_b16 v135, v33 offset:49152
	ds_write_b16_d16_hi v136, v33 offset:49152
	ds_write_b16 v137, v26 offset:49152
	ds_write_b16_d16_hi v0, v26 offset:49280
	ds_write_b16 v138, v27 offset:49152
	ds_write_b16_d16_hi v139, v27 offset:49152
	ds_write_b16 v140, v28 offset:49152
	ds_write_b16_d16_hi v141, v28 offset:49152
	ds_write_b16 v142, v29 offset:49152
	ds_write_b16_d16_hi v143, v29 offset:49152
	ds_write_b16 v144, v6 offset:49152
	ds_write_b16_d16_hi v145, v6 offset:49280
	ds_write_b16 v146, v7 offset:49152
	ds_write_b16_d16_hi v147, v7 offset:49152
	ds_write_b16 v148, v8 offset:49152
	ds_write_b16_d16_hi v149, v8 offset:49152
	ds_write_b16 v150, v9 offset:49152
	ds_write_b16_d16_hi v151, v9 offset:49152
	ds_write_b16 v152, v2 offset:49152
	ds_write_b16_d16_hi v153, v2 offset:49280
	ds_write_b16 v154, v3 offset:49152
	ds_write_b16_d16_hi v155, v3 offset:49152
	ds_write_b16 v156, v4 offset:49152
	ds_write_b16_d16_hi v157, v4 offset:49152
	ds_write_b16 v158, v5 offset:49152
	ds_write_b16_d16_hi v159, v5 offset:49152
	s_waitcnt lgkmcnt(0)
	s_barrier
	ds_read_b128 v[2:5], v160 offset:32768
	ds_read_b128 v[10:13], v162 offset:49152
	ds_read_b128 v[14:17], v160 offset:34816
	ds_read_b128 v[18:21], v162 offset:51200
	v_mfma_f32_16x16x32_bf16 v[50:53], v[112:115], v[116:119], v[52:55]
	v_lshlrev_b32_e32 v0, 6, v45
	v_lshl_or_b32 v45, v163, 2, v0
	v_mov_b32_e32 v0, v187
	s_waitcnt lgkmcnt(2)
	v_mfma_f32_16x16x32_bf16 v[22:25], v[2:5], v[10:13], v[56:59]
	ds_read_b128 v[30:33], v162 offset:53248
	s_nop 1
	ds_read_b128 v[54:57], v162 offset:55296
	v_mfma_f32_16x16x32_bf16 v[6:9], v[112:115], v[124:127], v[68:71]
	s_waitcnt lgkmcnt(2)
	v_mfma_f32_16x16x32_bf16 v[26:29], v[2:5], v[18:21], v[60:63]
	s_waitcnt lgkmcnt(1)
	v_mfma_f32_16x16x32_bf16 v[58:61], v[2:5], v[30:33], v[72:75]
	s_waitcnt lgkmcnt(0)
	v_mfma_f32_16x16x32_bf16 v[2:5], v[2:5], v[54:57], v[36:39]
	v_mfma_f32_16x16x32_bf16 v[36:39], v[14:17], v[10:13], v[76:79]
	v_mfma_f32_16x16x32_bf16 v[68:71], v[14:17], v[18:21], v[80:83]
	v_mfma_f32_16x16x32_bf16 v[72:75], v[14:17], v[30:33], v[84:87]
	v_mfma_f32_16x16x32_bf16 v[14:17], v[14:17], v[54:57], v[46:49]
	s_nop 2
	ds_read_b128 v[46:49], v160 offset:36864
	ds_read_b128 v[76:79], v160 offset:38912
	v_mfma_f32_16x16x32_bf16 v[96:99], v[108:111], v[92:95], v[96:99]
	v_mfma_f32_16x16x32_bf16 v[40:43], v[112:115], v[92:95], v[40:43]
	v_mfma_f32_16x16x32_bf16 v[100:103], v[108:111], v[116:119], v[100:103]
	v_mfma_f32_16x16x32_bf16 v[104:107], v[108:111], v[120:123], v[104:107]
	v_mfma_f32_16x16x32_bf16 v[88:91], v[108:111], v[124:127], v[88:91]
	v_mfma_f32_16x16x32_bf16 v[64:67], v[112:115], v[120:123], v[64:67]
	s_waitcnt lgkmcnt(1)
	v_mfma_f32_16x16x32_bf16 v[80:83], v[46:49], v[10:13], v[96:99]
	s_waitcnt lgkmcnt(0)
; __device__ __forceinline__ u16 f2bf(float f) { return (u16)(pack2(f, 0.f) & 0xffffu); }
; template <int NT, class VF, class RP>
; __device__ __forceinline__ void epi_staged_bf16(f32x4 (&acc)[4][NT], int r0, int c0, unsigned char* smem, VF vf, RP rowptr) {
;     ...
;   __syncthreads();
; #pragma unroll
;   for (int mi = 0; mi < 4; ++mi)
; #pragma unroll
;     for (int ni = 0; ni < NT; ++ni)
; #pragma unroll
;       for (int j = 0; j < 4; ++j) {
;         const int r = r0 + mi * 16 + j, c = c0 + ni * 16;
;         Ts[r * PITCH + c] = f2bf(vf(r, c, acc[mi][ni][j]));
;       }
;   __syncthreads();
	v_mfma_f32_16x16x32_bf16 v[10:13], v[76:79], v[10:13], v[40:43]
	s_nop 2
	ds_read_b128 v[40:43], v164 offset:32768
	v_mfma_f32_16x16x32_bf16 v[84:87], v[46:49], v[18:21], v[100:103]
	v_mfma_f32_16x16x32_bf16 v[92:95], v[46:49], v[30:33], v[104:107]
	v_mfma_f32_16x16x32_bf16 v[46:49], v[46:49], v[54:57], v[88:91]
	v_mfma_f32_16x16x32_bf16 v[18:21], v[76:79], v[18:21], v[50:53]
	v_mfma_f32_16x16x32_bf16 v[30:33], v[76:79], v[30:33], v[64:67]
	v_mfma_f32_16x16x32_bf16 v[6:9], v[76:79], v[54:57], v[6:9]
	s_nop 0
	ds_read_b128 v[50:53], v165 offset:49152
	ds_read_b128 v[54:57], v164 offset:34816
	ds_read_b128 v[62:65], v165 offset:51200
	ds_read_b128 v[76:79], v165 offset:53248
	ds_read_b128 v[88:91], v165 offset:55296
	s_waitcnt lgkmcnt(4)
	v_mfma_f32_16x16x32_bf16 v[22:25], v[40:43], v[50:53], v[22:25]
	s_waitcnt lgkmcnt(2)
	v_mfma_f32_16x16x32_bf16 v[26:29], v[40:43], v[62:65], v[26:29]
	s_waitcnt lgkmcnt(1)
	v_mfma_f32_16x16x32_bf16 v[58:61], v[40:43], v[76:79], v[58:61]
	s_waitcnt lgkmcnt(0)
	v_mfma_f32_16x16x32_bf16 v[2:5], v[40:43], v[88:91], v[2:5]
	v_mfma_f32_16x16x32_bf16 v[36:39], v[54:57], v[50:53], v[36:39]
	v_mfma_f32_16x16x32_bf16 v[40:43], v[54:57], v[62:65], v[68:71]
	s_nop 5
	v_cvt_pk_bf16_f32 v2, v2, s0
	v_mfma_f32_16x16x32_bf16 v[66:69], v[54:57], v[76:79], v[72:75]
	v_mfma_f32_16x16x32_bf16 v[14:17], v[54:57], v[88:91], v[14:17]
	ds_read_b128 v[54:57], v164 offset:36864
	s_nop 0
	ds_read_b128 v[70:73], v164 offset:38912
	s_waitcnt lgkmcnt(0)
	v_mfma_f32_16x16x32_bf16 v[80:83], v[54:57], v[50:53], v[80:83]
	s_barrier
	v_mfma_f32_16x16x32_bf16 v[10:13], v[70:73], v[50:53], v[10:13]
	v_cvt_pk_bf16_f32 v50, v22, s0
	v_lshlrev_b32_e32 v22, 1, v44
	v_lshl_or_b32 v22, v161, 7, v22
	v_mad_u64_u32 v[44:45], s[34:35], v45, s23, v[22:23]
	ds_write_b16 v44, v2 offset:96
	v_cvt_pk_bf16_f32 v2, v3, s0
	ds_write_b16 v44, v2 offset:368
	v_cvt_pk_bf16_f32 v2, v4, s0
	ds_write_b16 v44, v2 offset:640
	v_cvt_pk_bf16_f32 v2, v5, s0
	ds_write_b16 v44, v2 offset:912
	v_cvt_pk_bf16_f32 v2, v36, s0
	ds_write_b16 v44, v2 offset:4352
	v_cvt_pk_bf16_f32 v2, v37, s0
	ds_write_b16 v44, v2 offset:4624
	v_cvt_pk_bf16_f32 v2, v38, s0
	ds_write_b16 v44, v2 offset:4896
	v_cvt_pk_bf16_f32 v2, v39, s0
	ds_write_b16 v44, v2 offset:5168
	v_cvt_pk_bf16_f32 v2, v40, s0
	ds_write_b16 v44, v2 offset:4384
	v_cvt_pk_bf16_f32 v2, v41, s0
	ds_write_b16 v44, v2 offset:4656
	v_cvt_pk_bf16_f32 v2, v42, s0
	ds_write_b16 v44, v2 offset:4928
	v_cvt_pk_bf16_f32 v2, v43, s0
	ds_write_b16 v44, v2 offset:5200
	v_cvt_pk_bf16_f32 v2, v66, s0
	ds_write_b16 v44, v2 offset:4416
	v_cvt_pk_bf16_f32 v2, v67, s0
	ds_write_b16 v44, v2 offset:4688
	v_cvt_pk_bf16_f32 v2, v68, s0
	ds_write_b16 v44, v2 offset:4960
	v_cvt_pk_bf16_f32 v2, v69, s0
	ds_write_b16 v44, v2 offset:5232
	v_cvt_pk_bf16_f32 v2, v14, s0
	ds_write_b16 v44, v2 offset:4448
	v_cvt_pk_bf16_f32 v2, v15, s0
	ds_write_b16 v44, v2 offset:4720
	v_cvt_pk_bf16_f32 v2, v16, s0
	ds_write_b16 v44, v2 offset:4992
	v_cvt_pk_bf16_f32 v2, v17, s0
	v_mfma_f32_16x16x32_bf16 v[84:87], v[54:57], v[62:65], v[84:87]
	ds_write_b16 v44, v2 offset:5264
	v_cvt_pk_bf16_f32 v2, v80, s0
	ds_write_b16 v44, v2 offset:8704
	v_cvt_pk_bf16_f32 v2, v81, s0
	ds_write_b16 v44, v2 offset:8976
	v_cvt_pk_bf16_f32 v2, v82, s0
	ds_write_b16 v44, v2 offset:9248
	v_cvt_pk_bf16_f32 v2, v83, s0
	v_mfma_f32_16x16x32_bf16 v[92:95], v[54:57], v[76:79], v[92:95]
	ds_write_b16 v44, v2 offset:9520
	v_cvt_pk_bf16_f32 v2, v84, s0
	ds_write_b16 v44, v2 offset:8736
	v_cvt_pk_bf16_f32 v2, v85, s0
	ds_write_b16 v44, v2 offset:9008
	v_cvt_pk_bf16_f32 v2, v86, s0
	ds_write_b16 v44, v2 offset:9280
	v_cvt_pk_bf16_f32 v2, v87, s0
	v_mfma_f32_16x16x32_bf16 v[46:49], v[54:57], v[88:91], v[46:49]
	ds_write_b16 v44, v2 offset:9552
	v_cvt_pk_bf16_f32 v2, v92, s0
	ds_write_b16 v44, v2 offset:8768
	v_cvt_pk_bf16_f32 v2, v93, s0
	ds_write_b16 v44, v2 offset:9040
	v_cvt_pk_bf16_f32 v2, v94, s0
	ds_write_b16 v44, v2 offset:9312
	v_cvt_pk_bf16_f32 v2, v95, s0
	ds_write_b16 v44, v2 offset:9584
	v_cvt_pk_bf16_f32 v2, v46, s0
	ds_write_b16 v44, v2 offset:8800
	v_cvt_pk_bf16_f32 v2, v47, s0
	ds_write_b16 v44, v2 offset:9072
	v_cvt_pk_bf16_f32 v2, v48, s0
	ds_write_b16 v44, v2 offset:9344
	v_cvt_pk_bf16_f32 v2, v49, s0
	v_mfma_f32_16x16x32_bf16 v[18:21], v[70:73], v[62:65], v[18:21]
	ds_write_b16 v44, v2 offset:9616
	v_cvt_pk_bf16_f32 v2, v10, s0
	ds_write_b16 v44, v2 offset:13056
	v_cvt_pk_bf16_f32 v2, v11, s0
	ds_write_b16 v44, v2 offset:13328
	v_cvt_pk_bf16_f32 v2, v12, s0
	ds_write_b16 v44, v2 offset:13600
	v_cvt_pk_bf16_f32 v2, v13, s0
	v_mfma_f32_16x16x32_bf16 v[30:33], v[70:73], v[76:79], v[30:33]
	ds_write_b16 v44, v2 offset:13872
	v_cvt_pk_bf16_f32 v2, v18, s0
	v_cvt_pk_bf16_f32 v22, v23, s0
	ds_write_b16 v44, v2 offset:13088
	v_cvt_pk_bf16_f32 v2, v19, s0
	ds_write_b16 v44, v22 offset:272
	v_cvt_pk_bf16_f32 v22, v24, s0
	ds_write_b16 v44, v2 offset:13360
	v_cvt_pk_bf16_f32 v2, v20, s0
	ds_write_b16 v44, v22 offset:544
	v_cvt_pk_bf16_f32 v22, v25, s0
	ds_write_b16 v44, v2 offset:13632
	v_cvt_pk_bf16_f32 v2, v21, s0
	v_mfma_f32_16x16x32_bf16 v[6:9], v[70:73], v[88:91], v[6:9]
	ds_write_b16 v44, v22 offset:816
	v_cvt_pk_bf16_f32 v22, v26, s0
	ds_write_b16 v44, v2 offset:13904
	v_cvt_pk_bf16_f32 v2, v30, s0
	ds_write_b16 v44, v22 offset:32
	v_cvt_pk_bf16_f32 v22, v27, s0
	ds_write_b16 v44, v2 offset:13120
	v_cvt_pk_bf16_f32 v2, v31, s0
	ds_write_b16 v44, v22 offset:304
	v_cvt_pk_bf16_f32 v22, v28, s0
	ds_write_b16 v44, v2 offset:13392
	v_cvt_pk_bf16_f32 v2, v32, s0
	ds_write_b16 v44, v22 offset:576
	v_cvt_pk_bf16_f32 v22, v29, s0
	ds_write_b16 v44, v2 offset:13664
	v_cvt_pk_bf16_f32 v2, v33, s0
	ds_write_b16 v44, v22 offset:848
	v_cvt_pk_bf16_f32 v22, v58, s0
	ds_write_b16 v44, v2 offset:13936
	v_cvt_pk_bf16_f32 v2, v6, s0
	ds_write_b16 v44, v22 offset:64
	v_cvt_pk_bf16_f32 v22, v59, s0
	ds_write_b16 v44, v2 offset:13152
	v_cvt_pk_bf16_f32 v2, v7, s0
	ds_write_b16 v44, v22 offset:336
	v_cvt_pk_bf16_f32 v22, v60, s0
	ds_write_b16 v44, v2 offset:13424
	v_cvt_pk_bf16_f32 v2, v8, s0
	ds_write_b16 v44, v22 offset:608
	v_cvt_pk_bf16_f32 v22, v61, s0
	ds_write_b16 v44, v2 offset:13696
	v_cvt_pk_bf16_f32 v2, v9, s0
	ds_write_b16 v44, v50
	ds_write_b16 v44, v22 offset:880
	ds_write_b16 v44, v2 offset:13968
	s_waitcnt lgkmcnt(0)
	s_barrier
; template <int NT, class VF, class RP>
; __device__ __forceinline__ void epi_staged_bf16(f32x4 (&acc)[4][NT], int r0, int c0, unsigned char* smem, VF vf, RP rowptr) {
;     ...
; #pragma unroll
;   for (int i = 0; i < CPR / 2; ++i) {
;     const int c = t + 256 * i, row = c / CPR, ch = c % CPR;
;     u16* d = rowptr(row);
;     if (d) *(u32x4*)(d + ch * 8) = *(const u32x4*)(Ts + row * PITCH + ch * 8);
;   }
; __device__ __forceinline__ void phase_mix_a(const Params& p, int l, bool last, unsigned char* smem) {
;     ...
;         auto rp = [&](int m) -> u16* { const int rip = m >> 6, k2 = m & 63; return p.PF + ((size_t)((b * 64 + k2) * 2 + rip) * 128 + n1) * 256 + nh * 128; };
	global_load_dwordx2 v[2:3], v[34:35], off offset:320
	v_ashrrev_i32_e32 v4, 31, v0
	v_lshrrev_b32_e32 v4, 28, v4
	v_add_u32_e32 v4, v0, v4
	v_ashrrev_i32_e32 v6, 4, v4
	v_lshlrev_b32_e32 v5, 1, v6
	v_ashrrev_i32_e32 v4, 10, v4
	v_and_b32_e32 v5, 0x7e, v5
	v_add3_u32 v4, v4, s19, v5
	v_ashrrev_i32_e32 v5, 31, v4
	v_lshlrev_b64 v[4:5], 16, v[4:5]
	s_waitcnt vmcnt(0) lgkmcnt(0)
	v_lshl_add_u64 v[4:5], v[2:3], 0, v[4:5]
	v_lshl_add_u64 v[4:5], v[4:5], 0, s[94:95]
	v_cmp_ne_u64_e32 vcc, 0, v[4:5]
	s_and_saveexec_b64 s[4:5], vcc
	s_cbranch_execz .LBB0_610
	v_lshlrev_b32_e32 v2, 4, v6
	v_sub_u32_e32 v10, v0, v2
	v_mul_lo_u32 v2, v6, s23
	v_lshl_add_u32 v2, v10, 4, v2
	ds_read_b128 v[6:9], v2
	v_lshl_add_u64 v[2:3], v[4:5], 0, s[0:1]
	v_lshlrev_b32_e32 v4, 3, v10
	v_ashrrev_i32_e32 v5, 31, v4
	v_lshl_add_u64 v[2:3], v[4:5], 1, v[2:3]
	s_waitcnt lgkmcnt(0)
	global_store_dwordx4 v[2:3], v[6:9], off
	v_mov_b64_e32 v[2:3], s[40:41]
	s_load_dwordx2 s[100:101], s[40:41], 0x140
	s_waitcnt lgkmcnt(0)
	v_mov_b32_e32 v2, s100
	v_mov_b32_e32 v3, s101
.LBB0_610:
	s_or_b64 exec, exec, s[4:5]
	v_add_u32_e32 v6, 0x100, v0
	v_ashrrev_i32_e32 v4, 31, v6
	v_lshrrev_b32_e32 v4, 28, v4
	v_add_u32_e32 v4, v6, v4
	v_ashrrev_i32_e32 v7, 4, v4
	v_lshlrev_b32_e32 v5, 1, v7
	v_ashrrev_i32_e32 v4, 10, v4
	v_and_b32_e32 v5, 0x7e, v5
	v_add3_u32 v4, v4, s19, v5
	v_ashrrev_i32_e32 v5, 31, v4
	v_lshlrev_b64 v[4:5], 16, v[4:5]
	s_waitcnt lgkmcnt(0)
	v_lshl_add_u64 v[4:5], v[2:3], 0, v[4:5]
	v_lshl_add_u64 v[4:5], v[4:5], 0, s[94:95]
	v_cmp_ne_u64_e32 vcc, 0, v[4:5]
	s_and_saveexec_b64 s[4:5], vcc
	s_cbranch_execz .LBB0_612
	v_lshlrev_b32_e32 v2, 4, v7
	v_sub_u32_e32 v10, v6, v2
	v_mul_lo_u32 v2, v7, s23
	v_lshl_add_u32 v2, v10, 4, v2
	ds_read_b128 v[6:9], v2
	s_mov_b32 s1, s95
	v_lshl_add_u64 v[2:3], v[4:5], 0, s[0:1]
	v_lshlrev_b32_e32 v4, 3, v10
	v_ashrrev_i32_e32 v5, 31, v4
	v_lshl_add_u64 v[2:3], v[4:5], 1, v[2:3]
	s_waitcnt lgkmcnt(0)
	global_store_dwordx4 v[2:3], v[6:9], off
	v_mov_b64_e32 v[2:3], s[40:41]
	s_load_dwordx2 s[100:101], s[40:41], 0x140
	s_waitcnt lgkmcnt(0)
	v_mov_b32_e32 v2, s100
	v_mov_b32_e32 v3, s101
.LBB0_612:
	s_or_b64 exec, exec, s[4:5]
	v_add_u32_e32 v6, 0x200, v0
	v_ashrrev_i32_e32 v4, 31, v6
	v_lshrrev_b32_e32 v4, 28, v4
	v_add_u32_e32 v4, v6, v4
	v_ashrrev_i32_e32 v7, 4, v4
	v_lshlrev_b32_e32 v5, 1, v7
	v_ashrrev_i32_e32 v4, 10, v4
	v_and_b32_e32 v5, 0x7e, v5
	v_add3_u32 v4, v4, s19, v5
	v_ashrrev_i32_e32 v5, 31, v4
	v_lshlrev_b64 v[4:5], 16, v[4:5]
	s_waitcnt lgkmcnt(0)
	v_lshl_add_u64 v[4:5], v[2:3], 0, v[4:5]
	v_lshl_add_u64 v[4:5], v[4:5], 0, s[94:95]
	v_cmp_ne_u64_e32 vcc, 0, v[4:5]
	s_and_saveexec_b64 s[4:5], vcc
	s_cbranch_execz .LBB0_614
	v_lshlrev_b32_e32 v2, 4, v7
	v_sub_u32_e32 v10, v6, v2
	v_mul_lo_u32 v2, v7, s23
	v_lshl_add_u32 v2, v10, 4, v2
	ds_read_b128 v[6:9], v2
	s_mov_b32 s1, s95
	v_lshl_add_u64 v[2:3], v[4:5], 0, s[0:1]
	v_lshlrev_b32_e32 v4, 3, v10
	v_ashrrev_i32_e32 v5, 31, v4
	v_lshl_add_u64 v[2:3], v[4:5], 1, v[2:3]
	s_waitcnt lgkmcnt(0)
	global_store_dwordx4 v[2:3], v[6:9], off
	v_mov_b64_e32 v[2:3], s[40:41]
	s_load_dwordx2 s[100:101], s[40:41], 0x140
	s_waitcnt lgkmcnt(0)
	v_mov_b32_e32 v2, s100
	v_mov_b32_e32 v3, s101
.LBB0_614:
	s_or_b64 exec, exec, s[4:5]
	v_add_u32_e32 v6, 0x300, v0
	v_ashrrev_i32_e32 v4, 31, v6
	v_lshrrev_b32_e32 v4, 28, v4
	v_add_u32_e32 v4, v6, v4
	v_ashrrev_i32_e32 v7, 4, v4
	v_lshlrev_b32_e32 v5, 1, v7
	v_ashrrev_i32_e32 v4, 10, v4
	v_and_b32_e32 v5, 0x7e, v5
	v_add3_u32 v4, v4, s19, v5
	v_ashrrev_i32_e32 v5, 31, v4
	v_lshlrev_b64 v[4:5], 16, v[4:5]
	s_waitcnt lgkmcnt(0)
	v_lshl_add_u64 v[4:5], v[2:3], 0, v[4:5]
	v_lshl_add_u64 v[4:5], v[4:5], 0, s[94:95]
	v_cmp_ne_u64_e32 vcc, 0, v[4:5]
	s_and_saveexec_b64 s[4:5], vcc
	s_cbranch_execz .LBB0_616
	v_lshlrev_b32_e32 v2, 4, v7
	v_sub_u32_e32 v10, v6, v2
	v_mul_lo_u32 v2, v7, s23
	v_lshl_add_u32 v2, v10, 4, v2
	ds_read_b128 v[6:9], v2
	s_mov_b32 s1, s95
	v_lshl_add_u64 v[2:3], v[4:5], 0, s[0:1]
	v_lshlrev_b32_e32 v4, 3, v10
	v_ashrrev_i32_e32 v5, 31, v4
	v_lshl_add_u64 v[2:3], v[4:5], 1, v[2:3]
	s_waitcnt lgkmcnt(0)
	global_store_dwordx4 v[2:3], v[6:9], off
	v_mov_b64_e32 v[2:3], s[40:41]
	s_load_dwordx2 s[100:101], s[40:41], 0x140
	s_waitcnt lgkmcnt(0)
	v_mov_b32_e32 v2, s100
	v_mov_b32_e32 v3, s101
; template <int NT, class VF, class RP>
; __device__ __forceinline__ void epi_staged_bf16(f32x4 (&acc)[4][NT], int r0, int c0, unsigned char* smem, VF vf, RP rowptr) {
;     ...
; #pragma unroll
;   for (int i = 0; i < CPR / 2; ++i) {
;     const int c = t + 256 * i, row = c / CPR, ch = c % CPR;
;     u16* d = rowptr(row);
;     if (d) *(u32x4*)(d + ch * 8) = *(const u32x4*)(Ts + row * PITCH + ch * 8);
;   }
; __device__ __forceinline__ void phase_mix_a(const Params& p, int l, bool last, unsigned char* smem) {
;     ...
;         auto rp = [&](int m) -> u16* { const int rip = m >> 6, k2 = m & 63; return p.PF + ((size_t)((b * 64 + k2) * 2 + rip) * 128 + n1) * 256 + nh * 128; };
.LBB0_616:
	s_or_b64 exec, exec, s[4:5]
	v_add_u32_e32 v6, 0x400, v0
	v_ashrrev_i32_e32 v4, 31, v6
	v_lshrrev_b32_e32 v4, 28, v4
	v_add_u32_e32 v4, v6, v4
	v_ashrrev_i32_e32 v7, 4, v4
	v_lshlrev_b32_e32 v5, 1, v7
	v_ashrrev_i32_e32 v4, 10, v4
	v_and_b32_e32 v5, 0x7e, v5
	v_add3_u32 v4, v4, s19, v5
	v_ashrrev_i32_e32 v5, 31, v4
	v_lshlrev_b64 v[4:5], 16, v[4:5]
	s_waitcnt lgkmcnt(0)
	v_lshl_add_u64 v[4:5], v[2:3], 0, v[4:5]
	v_lshl_add_u64 v[4:5], v[4:5], 0, s[94:95]
	v_cmp_ne_u64_e32 vcc, 0, v[4:5]
	s_and_saveexec_b64 s[4:5], vcc
	s_cbranch_execz .LBB0_618
	v_lshlrev_b32_e32 v2, 4, v7
	v_sub_u32_e32 v10, v6, v2
	v_mul_lo_u32 v2, v7, s23
	v_lshl_add_u32 v2, v10, 4, v2
	ds_read_b128 v[6:9], v2
	s_mov_b32 s1, s95
	v_lshl_add_u64 v[2:3], v[4:5], 0, s[0:1]
	v_lshlrev_b32_e32 v4, 3, v10
	v_ashrrev_i32_e32 v5, 31, v4
	v_lshl_add_u64 v[2:3], v[4:5], 1, v[2:3]
	s_waitcnt lgkmcnt(0)
	global_store_dwordx4 v[2:3], v[6:9], off
	v_mov_b64_e32 v[2:3], s[40:41]
	s_load_dwordx2 s[100:101], s[40:41], 0x140
	s_waitcnt lgkmcnt(0)
	v_mov_b32_e32 v2, s100
	v_mov_b32_e32 v3, s101
.LBB0_618:
	s_or_b64 exec, exec, s[4:5]
	v_add_u32_e32 v6, 0x500, v0
	v_ashrrev_i32_e32 v4, 31, v6
	v_lshrrev_b32_e32 v4, 28, v4
	v_add_u32_e32 v4, v6, v4
	v_ashrrev_i32_e32 v7, 4, v4
	v_lshlrev_b32_e32 v5, 1, v7
	v_ashrrev_i32_e32 v4, 10, v4
	v_and_b32_e32 v5, 0x7e, v5
	v_add3_u32 v4, v4, s19, v5
	v_ashrrev_i32_e32 v5, 31, v4
	v_lshlrev_b64 v[4:5], 16, v[4:5]
	s_waitcnt lgkmcnt(0)
	v_lshl_add_u64 v[4:5], v[2:3], 0, v[4:5]
	v_lshl_add_u64 v[4:5], v[4:5], 0, s[94:95]
	v_cmp_ne_u64_e32 vcc, 0, v[4:5]
	s_and_saveexec_b64 s[4:5], vcc
	s_cbranch_execz .LBB0_620
	v_lshlrev_b32_e32 v2, 4, v7
	v_sub_u32_e32 v10, v6, v2
	v_mul_lo_u32 v2, v7, s23
	v_lshl_add_u32 v2, v10, 4, v2
	ds_read_b128 v[6:9], v2
	s_mov_b32 s1, s95
	v_lshl_add_u64 v[2:3], v[4:5], 0, s[0:1]
	v_lshlrev_b32_e32 v4, 3, v10
	v_ashrrev_i32_e32 v5, 31, v4
	v_lshl_add_u64 v[2:3], v[4:5], 1, v[2:3]
	s_waitcnt lgkmcnt(0)
	global_store_dwordx4 v[2:3], v[6:9], off
	v_mov_b64_e32 v[2:3], s[40:41]
	s_load_dwordx2 s[100:101], s[40:41], 0x140
	s_waitcnt lgkmcnt(0)
	v_mov_b32_e32 v2, s100
	v_mov_b32_e32 v3, s101
.LBB0_620:
	s_or_b64 exec, exec, s[4:5]
	v_add_u32_e32 v6, 0x600, v0
	v_ashrrev_i32_e32 v4, 31, v6
	v_lshrrev_b32_e32 v4, 28, v4
	v_add_u32_e32 v4, v6, v4
	v_ashrrev_i32_e32 v7, 4, v4
	v_lshlrev_b32_e32 v5, 1, v7
	v_ashrrev_i32_e32 v4, 10, v4
	v_and_b32_e32 v5, 0x7e, v5
	v_add3_u32 v4, v4, s19, v5
	v_ashrrev_i32_e32 v5, 31, v4
	v_lshlrev_b64 v[4:5], 16, v[4:5]
	s_waitcnt lgkmcnt(0)
	v_lshl_add_u64 v[4:5], v[2:3], 0, v[4:5]
	v_lshl_add_u64 v[4:5], v[4:5], 0, s[94:95]
	v_cmp_ne_u64_e32 vcc, 0, v[4:5]
	s_and_saveexec_b64 s[4:5], vcc
	s_cbranch_execz .LBB0_622
	v_lshlrev_b32_e32 v2, 4, v7
	v_sub_u32_e32 v10, v6, v2
	v_mul_lo_u32 v2, v7, s23
	v_lshl_add_u32 v2, v10, 4, v2
	ds_read_b128 v[6:9], v2
	s_mov_b32 s1, s95
	v_lshl_add_u64 v[2:3], v[4:5], 0, s[0:1]
	v_lshlrev_b32_e32 v4, 3, v10
	v_ashrrev_i32_e32 v5, 31, v4
	v_lshl_add_u64 v[2:3], v[4:5], 1, v[2:3]
	s_waitcnt lgkmcnt(0)
	global_store_dwordx4 v[2:3], v[6:9], off
	v_mov_b64_e32 v[2:3], s[40:41]
	s_load_dwordx2 s[100:101], s[40:41], 0x140
	s_waitcnt lgkmcnt(0)
	v_mov_b32_e32 v2, s100
	v_mov_b32_e32 v3, s101
.LBB0_622:
	s_or_b64 exec, exec, s[4:5]
	v_add_u32_e32 v0, 0x700, v0
	v_ashrrev_i32_e32 v4, 31, v0
	v_lshrrev_b32_e32 v4, 28, v4
	v_add_u32_e32 v5, v0, v4
	v_ashrrev_i32_e32 v4, 4, v5
	v_lshlrev_b32_e32 v6, 1, v4
	v_ashrrev_i32_e32 v5, 10, v5
	v_and_b32_e32 v6, 0x7e, v6
	v_add3_u32 v6, v5, s19, v6
	v_ashrrev_i32_e32 v7, 31, v6
	v_lshlrev_b64 v[6:7], 16, v[6:7]
	s_waitcnt lgkmcnt(0)
	v_lshl_add_u64 v[2:3], v[2:3], 0, v[6:7]
	v_lshl_add_u64 v[2:3], v[2:3], 0, s[94:95]
	v_cmp_ne_u64_e32 vcc, 0, v[2:3]
	s_and_saveexec_b64 s[4:5], vcc
	s_cbranch_execz .LBB0_607
	v_lshlrev_b32_e32 v5, 4, v4
	v_sub_u32_e32 v0, v0, v5
	v_mul_lo_u32 v4, v4, s23
	v_lshl_add_u32 v4, v0, 4, v4
	ds_read_b128 v[4:7], v4
	s_mov_b32 s1, s95
	v_lshlrev_b32_e32 v8, 3, v0
	v_lshl_add_u64 v[2:3], v[2:3], 0, s[0:1]
	v_ashrrev_i32_e32 v9, 31, v8
	v_lshl_add_u64 v[2:3], v[8:9], 1, v[2:3]
	s_waitcnt lgkmcnt(0)
	global_store_dwordx4 v[2:3], v[4:7], off
	s_branch .LBB0_607

; __device__ __forceinline__ int tid_() { int t = threadIdx.x; asm volatile("" : "+v"(t)); return t; }
; __device__ __forceinline__ int bid_() { int b = blockIdx.x; asm volatile("" : "+s"(b)); return b; }
; __device__ __forceinline__ void phase_mix_b(const Params& p, int l, bool last, unsigned char* smem) {
;     ...
;   const int tt = tid_(), lane = tt & 63, wid = tt >> 6;
;   const int gw = bid_() * 4 + wid, nw = gridDim.x * 4;
;   const float QSCALE = 0.07216878364870322f * 1.4426950408889634f;
;   for (int row = gw; row < TT; row += nw) {
;     const bool lat = row < T_LAT;
;     const int b = row_batch(row), pos = row_pos(row);
;     float cs = 1.f, sn = 0.f;
;     if (lat) {
;       const int n = row & (SEQ - 1);
;       const int r = lane, sub = r & 31, i = sub & 15;
;       const float ps = (r < 32) ? (float)(n >> 6) : (float)(n & 63);
;       const float fr = __builtin_amdgcn_exp2f(-(float)i * 0.83048202372184058696f);
;       const float ang = ps * fr;
;       sn = __sinf(ang);
;       cs = __cosf(ang);
;     }
;     const bool hi = ((lane & 31) >= 16);
.LBB0_686:
	s_waitcnt vmcnt(0)
	s_mov_b64 s[0:1], exec
	s_load_dwordx4 s[40:43], s[64:65], 0x70
	s_load_dwordx2 s[46:47], s[64:65], 0x120
	s_load_dwordx4 s[48:51], s[64:65], 0x148
	s_load_dwordx2 s[52:53], s[64:65], 0x160
	s_load_dwordx2 s[56:57], s[64:65], 0x168
	v_and_b32_e32 v2, 63, v187
	v_lshrrev_b32_e32 v3, 6, v187
	v_and_b32_e32 v4, 15, v2
	v_lshrrev_b32_e32 v5, 4, v2
	v_readfirstlane_b32 s8, v3
	v_readlane_b32 s9, v254, 47
	v_lshlrev_b32_e32 v6, 4, v4
	v_lshlrev_b32_e32 v7, 3, v4
	v_mul_u32_u24_e32 v8, 0x180, v5
	v_add_u32_e32 v150, v8, v6
	v_add_u32_e32 v151, v8, v7
	v_add_u32_e32 v151, 0x100, v151
	v_lshl_add_u32 v152, v5, 8, v6
	v_mov_b32_e32 v153, v7
	v_mul_u32_u24_e32 v9, 0x318000, v5
	v_add_u32_e32 v154, v9, v6
	v_add_u32_e32 v155, v9, v7
	v_add_u32_e32 v155, 0x100, v155
	v_and_b32_e32 v10, 3, v4
	v_lshlrev_b32_e32 v10, 2, v10
	v_bfe_u32 v11, v4, 3, 1
	v_bfe_u32 v12, v4, 2, 1
	v_cmp_eq_u32_e64 s[38:39], 0, v11
	v_add_u32_e32 v13, 0, v10
	v_cvt_f32_u32_e32 v13, v13
	v_mul_f32_e32 v13, 0xbf549a78, v13
	v_exp_f32_e32 v13, v13
	s_nop 0
	v_cndmask_b32_e64 v180, 0, v13, s[38:39]
	v_cndmask_b32_e64 v184, v13, 0, s[38:39]
	v_add_u32_e32 v13, 1, v10
	v_cvt_f32_u32_e32 v13, v13
	v_mul_f32_e32 v13, 0xbf549a78, v13
	v_exp_f32_e32 v13, v13
	s_nop 0
	v_cndmask_b32_e64 v181, 0, v13, s[38:39]
	v_cndmask_b32_e64 v185, v13, 0, s[38:39]
	v_add_u32_e32 v13, 2, v10
	v_cvt_f32_u32_e32 v13, v13
	v_mul_f32_e32 v13, 0xbf549a78, v13
	v_exp_f32_e32 v13, v13
	s_nop 0
	v_cndmask_b32_e64 v182, 0, v13, s[38:39]
	v_cndmask_b32_e64 v188, v13, 0, s[38:39]
	v_add_u32_e32 v13, 3, v10
	v_cvt_f32_u32_e32 v13, v13
	v_mul_f32_e32 v13, 0xbf549a78, v13
	v_exp_f32_e32 v13, v13
	s_nop 0
	v_cndmask_b32_e64 v183, 0, v13, s[38:39]
	v_cndmask_b32_e64 v189, v13, 0, s[38:39]
	v_cmp_eq_u32_e64 s[38:39], 0, v12
	v_mov_b32_e32 v13, 0x3e22f983
	s_nop 1
	v_cndmask_b32_e64 v190, v13, -v13, s[38:39]
	s_waitcnt lgkmcnt(0)
	s_nop 3
	s_mul_i32 s18, s36, 0x300
	s_add_u32 s40, s40, s18
	s_addc_u32 s41, s41, 0
	s_add_u32 s42, s42, s18
	s_addc_u32 s43, s43, 0
	v_lshlrev_b32_e32 v13, 5, v4
	global_load_dwordx4 v[156:159], v13, s[40:41]
	global_load_dwordx4 v[160:163], v13, s[40:41] offset:16
	global_load_dwordx4 v[164:167], v6, s[40:41] offset:512
	global_load_dwordx4 v[168:171], v13, s[42:43]
	global_load_dwordx4 v[172:175], v13, s[42:43] offset:16
	global_load_dwordx4 v[176:179], v6, s[42:43] offset:512
	s_lshl_b32 s94, s2, 2
	s_add_i32 s94, s94, s8
	s_cmp_lt_u32 s94, 0x4200
	s_cbranch_scc0 .Lmb_done
	s_cmp_lt_u32 s94, 0x4000
	s_cbranch_scc0 .Lmb_ctxrow0
	s_lshr_b32 s32, s94, 13
	s_and_b32 s35, s94, 0x1fff
	s_add_i32 s38, s35, 0x100
	s_lshr_b32 s39, s35, 6
	s_and_b32 s35, s35, 63
	s_mov_b32 s59, 1
	s_mov_b32 s60, 1
	s_branch .Lmb_rowgo0

; __device__ __forceinline__ float bf2f(u16 b) { return __uint_as_float(((unsigned)b) << 16); }
; __device__ __forceinline__ void phase_mix_b(const Params& p, int l, bool last, unsigned char* smem) {
;     ...
;   for (int row = gw; row < TT; row += nw) {
;     const bool lat = row < T_LAT;
;     const int b = row_batch(row), pos = row_pos(row);
;     float cs = 1.f, sn = 0.f;
;     if (lat) {
;       const int n = row & (SEQ - 1);
;       const int r = lane, sub = r & 31, i = sub & 15;
;       const float ps = (r < 32) ? (float)(n >> 6) : (float)(n & 63);
;       const float fr = __builtin_amdgcn_exp2f(-(float)i * 0.83048202372184058696f);
;       const float ang = ps * fr;
;       sn = __sinf(ang);
;       cs = __cosf(ang);
;     }
;     const bool hi = ((lane & 31) >= 16);
;     if (lat || !last) {
; #pragma unroll
;       for (int h = 0; h < 4; ++h) {
;         const u16* q = p.QR + (size_t)row * 768 + h * 192;
;         float v0 = bf2f(q[lane]), v1 = bf2f(q[lane + 64]), v2 = bf2f(q[lane + 128]);
;     ...
;       const float kr = bf2f(p.PX[(size_t)row * 1024 + 896 + lane]);
; #pragma unroll
;       for (int h = 0; h < 4; ++h) {
;         const u16* kk = p.KN + (size_t)row * 512 + h * 128;
;         float v0 = bf2f(kk[lane]), v1 = bf2f(kk[lane + 64]), v2 = kr;
.Lmb_rowgo0:
	s_lshl_b32 s32, s32, 2
	s_mul_i32 s32, s32, 0x2100
	s_add_i32 s32, s32, s38
	s_mul_i32 s32, s32, 0x180
	s_add_u32 s88, s52, s32
	s_addc_u32 s89, s53, 0
	s_add_u32 s100, s56, s32
	s_addc_u32 s101, s57, 0
	s_lshl_b32 s32, s94, 10
	s_add_u32 s4, s50, s32
	s_addc_u32 s5, s51, 0
	global_load_dwordx4 v[8:11], v152, s[4:5]
	s_lshl_b32 s32, s94, 11
	s_add_u32 s4, s46, s32
	s_addc_u32 s5, s47, 0
	global_load_dwordx2 v[12:13], v153, s[4:5] offset:1792
	s_cmp_eq_u32 s60, 0
	s_cbranch_scc1 .Lmb_noqload0
	s_mul_i32 s32, s94, 0x600
	s_add_u32 s4, s48, s32
	s_addc_u32 s5, s49, 0
	global_load_dwordx4 v[2:5], v150, s[4:5]
	global_load_dwordx2 v[6:7], v151, s[4:5]
.Lmb_noqload0:
	s_waitcnt vmcnt(0)
	s_branch .Lmb_enter
.Lmb_row:
	s_waitcnt vmcnt(2)
.Lmb_enter:
	v_lshlrev_b32_e32 v26, 16, v8
	v_and_b32_e32 v27, 0xffff0000, v8
	v_lshlrev_b32_e32 v28, 16, v9
	v_and_b32_e32 v29, 0xffff0000, v9
	v_lshlrev_b32_e32 v30, 16, v10
	v_and_b32_e32 v31, 0xffff0000, v10
	v_lshlrev_b32_e32 v32, 16, v11
	v_and_b32_e32 v33, 0xffff0000, v11
	v_lshlrev_b32_e32 v34, 16, v12
	v_and_b32_e32 v35, 0xffff0000, v12
	v_lshlrev_b32_e32 v36, 16, v13
	v_and_b32_e32 v37, 0xffff0000, v13
	s_cmp_eq_u32 s60, 0
	s_cbranch_scc1 .Lmb_noq0
	v_lshlrev_b32_e32 v14, 16, v2
	v_and_b32_e32 v15, 0xffff0000, v2
	v_lshlrev_b32_e32 v16, 16, v3
	v_and_b32_e32 v17, 0xffff0000, v3
	v_lshlrev_b32_e32 v18, 16, v4
	v_and_b32_e32 v19, 0xffff0000, v4
	v_lshlrev_b32_e32 v20, 16, v5
	v_and_b32_e32 v21, 0xffff0000, v5
	v_lshlrev_b32_e32 v22, 16, v6
	v_and_b32_e32 v23, 0xffff0000, v6
	v_lshlrev_b32_e32 v24, 16, v7
	v_and_b32_e32 v25, 0xffff0000, v7

; __device__ __forceinline__ float bf2f(u16 b) { return __uint_as_float(((unsigned)b) << 16); }
; __device__ __forceinline__ void phase_mix_b(const Params& p, int l, bool last, unsigned char* smem) {
;     ...
;   for (int row = gw; row < TT; row += nw) {
;     const bool lat = row < T_LAT;
;     const int b = row_batch(row), pos = row_pos(row);
;     ...
;     {
;       const float kr = bf2f(p.PX[(size_t)row * 1024 + 896 + lane]);
; #pragma unroll
;       for (int h = 0; h < 4; ++h) {
;         const u16* kk = p.KN + (size_t)row * 512 + h * 128;
;         float v0 = bf2f(kk[lane]), v1 = bf2f(kk[lane + 64]), v2 = kr;
;         const float ss = wave_sum(v0 * v0 + v1 * v1 + v2 * v2);
.Lmb_norope_a:
	s_mov_b32 s40, s59
	s_mov_b32 s41, s60
	s_mov_b64 s[98:99], s[88:89]
	s_mov_b64 s[18:19], s[100:101]
	s_add_i32 s94, s94, s9
	s_mov_b32 s8, 0
	s_cmp_lt_u32 s94, 0x4200
	s_cbranch_scc0 .Lmb_nonext
	s_mov_b32 s8, 1
	s_cmp_lt_u32 s94, 0x4000
	s_cbranch_scc0 .Lmb_ctxrow1
	s_lshr_b32 s32, s94, 13
	s_and_b32 s35, s94, 0x1fff
	s_add_i32 s38, s35, 0x100
	s_lshr_b32 s39, s35, 6
	s_and_b32 s35, s35, 63
	s_mov_b32 s59, 1
	s_mov_b32 s60, 1
	s_branch .Lmb_rowgo1

; __device__ __forceinline__ float bf2f(u16 b) { return __uint_as_float(((unsigned)b) << 16); }
; __device__ __forceinline__ void phase_mix_b(const Params& p, int l, bool last, unsigned char* smem) {
;     ...
;         const u16* q = p.QR + (size_t)row * 768 + h * 192;
;         float v0 = bf2f(q[lane]), v1 = bf2f(q[lane + 64]), v2 = bf2f(q[lane + 128]);
;         const float ss = wave_sum(v0 * v0 + v1 * v1 + v2 * v2);
;         const float rstd = rsqrtf(ss * (1.f / 192.f) + 1e-6f);
;     ...
;     {
;       const float kr = bf2f(p.PX[(size_t)row * 1024 + 896 + lane]);
; #pragma unroll
;       for (int h = 0; h < 4; ++h) {
;         const u16* kk = p.KN + (size_t)row * 512 + h * 128;
;         float v0 = bf2f(kk[lane]), v1 = bf2f(kk[lane + 64]), v2 = kr;
;         const float ss = wave_sum(v0 * v0 + v1 * v1 + v2 * v2);
;         const float rstd = rsqrtf(ss * (1.f / 192.f) + 1e-6f);
;         const float* kn = p.k_norm + l * 192;
;         v0 *= rstd * kn[lane]; v1 *= rstd * kn[lane + 64]; v2 *= rstd * kn[lane + 128];
;         if (lat) {
;           const float xp = __shfl_xor(v2, 16);
;           v2 = hi ? (xp * sn + v2 * cs) : (v2 * cs - xp * sn);
;         }
.Lmb_noqload1:
.Lmb_nonext:
	v_mul_f32_e32 v39, v26, v26
	v_fmac_f32_e32 v39, v27, v27
	v_fmac_f32_e32 v39, v28, v28
	v_fmac_f32_e32 v39, v29, v29
	v_fmac_f32_e32 v39, v30, v30
	v_fmac_f32_e32 v39, v31, v31
	v_fmac_f32_e32 v39, v32, v32
	v_fmac_f32_e32 v39, v33, v33
	v_fmac_f32_e32 v39, v34, v34
	v_fmac_f32_e32 v39, v35, v35
	v_fmac_f32_e32 v39, v36, v36
	v_fmac_f32_e32 v39, v37, v37
	s_cmp_eq_u32 s41, 0
	s_cbranch_scc1 .Lmb_noq1
	v_mul_f32_e32 v38, v14, v14
	v_fmac_f32_e32 v38, v15, v15
	v_fmac_f32_e32 v38, v16, v16
	v_fmac_f32_e32 v38, v17, v17
	v_fmac_f32_e32 v38, v18, v18
	v_fmac_f32_e32 v38, v19, v19
	v_fmac_f32_e32 v38, v20, v20
	v_fmac_f32_e32 v38, v21, v21
	v_fmac_f32_e32 v38, v22, v22
	v_fmac_f32_e32 v38, v23, v23
	v_fmac_f32_e32 v38, v24, v24
	v_fmac_f32_e32 v38, v25, v25
.Lmb_noq1:
	s_nop 1
	v_add_f32_dpp v39, v39, v39 quad_perm:[1,0,3,2] row_mask:0xf bank_mask:0xf
	v_add_f32_dpp v38, v38, v38 quad_perm:[1,0,3,2] row_mask:0xf bank_mask:0xf
	s_nop 1
	v_add_f32_dpp v39, v39, v39 quad_perm:[2,3,0,1] row_mask:0xf bank_mask:0xf
	v_add_f32_dpp v38, v38, v38 quad_perm:[2,3,0,1] row_mask:0xf bank_mask:0xf
	s_nop 1
	v_add_f32_dpp v39, v39, v39 row_half_mirror row_mask:0xf bank_mask:0xf
	v_add_f32_dpp v38, v38, v38 row_half_mirror row_mask:0xf bank_mask:0xf
	s_nop 1
	v_add_f32_dpp v39, v39, v39 row_mirror row_mask:0xf bank_mask:0xf
	v_add_f32_dpp v38, v38, v38 row_mirror row_mask:0xf bank_mask:0xf
	v_fmamk_f32 v39, v39, 0x3baaaaab, v224
	v_rsq_f32_e32 v39, v39
	v_fmamk_f32 v38, v38, 0x3baaaaab, v224
	v_rsq_f32_e32 v38, v38
	s_nop 0
	v_mul_f32_e32 v210, v168, v39
	v_mul_f32_e32 v26, v210, v26
	v_mul_f32_e32 v210, v169, v39
	v_mul_f32_e32 v27, v210, v27
	v_mul_f32_e32 v210, v170, v39
	v_mul_f32_e32 v28, v210, v28
	v_mul_f32_e32 v210, v171, v39
	v_mul_f32_e32 v29, v210, v29
	v_mul_f32_e32 v210, v172, v39
	v_mul_f32_e32 v30, v210, v30
	v_mul_f32_e32 v210, v173, v39
	v_mul_f32_e32 v31, v210, v31
	v_mul_f32_e32 v210, v174, v39
	v_mul_f32_e32 v32, v210, v32
	v_mul_f32_e32 v210, v175, v39
	v_mul_f32_e32 v33, v210, v33
	v_mul_f32_e32 v210, v176, v39
	v_mul_f32_e32 v34, v210, v34
	v_mul_f32_e32 v210, v177, v39
	v_mul_f32_e32 v35, v210, v35
	v_mul_f32_e32 v210, v178, v39
	v_mul_f32_e32 v36, v210, v36
	v_mul_f32_e32 v210, v179, v39
	v_mul_f32_e32 v37, v210, v37
	s_cmp_eq_u32 s40, 0
	s_cbranch_scc1 .Lmb_kplain
	v_mul_f32_e32 v206, v34, v191
	v_mul_f32_e32 v207, v35, v192
	v_mul_f32_e32 v208, v36, v193
	v_mul_f32_e32 v209, v37, v194
	v_fmac_f32_dpp v206, v34, v195 row_shl:4 row_mask:0xf bank_mask:0x5
	v_fmac_f32_dpp v206, v34, v195 row_shr:4 row_mask:0xf bank_mask:0xa
	v_fmac_f32_dpp v207, v35, v196 row_shl:4 row_mask:0xf bank_mask:0x5
	v_fmac_f32_dpp v207, v35, v196 row_shr:4 row_mask:0xf bank_mask:0xa
	v_fmac_f32_dpp v208, v36, v197 row_shl:4 row_mask:0xf bank_mask:0x5
	v_fmac_f32_dpp v208, v36, v197 row_shr:4 row_mask:0xf bank_mask:0xa
	v_fmac_f32_dpp v209, v37, v198 row_shl:4 row_mask:0xf bank_mask:0x5
	v_fmac_f32_dpp v209, v37, v198 row_shr:4 row_mask:0xf bank_mask:0xa
	s_branch .Lmb_kpack

; __device__ __forceinline__ u16 f2bf(float f) { return (u16)(pack2(f, 0.f) & 0xffffu); }
; __device__ __forceinline__ void phase_mix_b(const Params& p, int l, bool last, unsigned char* smem) {
;     ...
;         const float rstd = rsqrtf(ss * (1.f / 192.f) + 1e-6f);
;         const float* qn = p.q_norm + l * 192;
;         v0 *= rstd * qn[lane]; v1 *= rstd * qn[lane + 64]; v2 *= rstd * qn[lane + 128];
;         if (lat) {
;           const float xp = __shfl_xor(v2, 16);
;           v2 = hi ? (xp * sn + v2 * cs) : (v2 * cs - xp * sn);
;     ...
;         u16* o = p.Kb + ((size_t)(b * 4 + h) * NPOS + pos) * 192;
;         o[lane] = f2bf(v0); o[lane + 64] = f2bf(v1); o[lane + 128] = f2bf(v2);
.Lmb_kpack:
	v_cvt_pk_bf16_f32 v230, v26, v27
	v_cvt_pk_bf16_f32 v231, v28, v29
	v_cvt_pk_bf16_f32 v232, v30, v31
	v_cvt_pk_bf16_f32 v233, v32, v33
	v_cvt_pk_bf16_f32 v234, v206, v207
	v_cvt_pk_bf16_f32 v235, v208, v209
	global_store_dwordx4 v154, v[230:233], s[18:19]
	global_store_dwordx2 v155, v[234:235], s[18:19]
	s_cmp_eq_u32 s41, 0
	s_cbranch_scc1 .Lmb_next
	v_mul_f32_e32 v210, v156, v38
	v_mul_f32_e32 v14, v210, v14
	v_mul_f32_e32 v210, v157, v38
	v_mul_f32_e32 v15, v210, v15
	v_mul_f32_e32 v210, v158, v38
	v_mul_f32_e32 v16, v210, v16
	v_mul_f32_e32 v210, v159, v38
	v_mul_f32_e32 v17, v210, v17
	v_mul_f32_e32 v210, v160, v38
	v_mul_f32_e32 v18, v210, v18
	v_mul_f32_e32 v210, v161, v38
	v_mul_f32_e32 v19, v210, v19
	v_mul_f32_e32 v210, v162, v38
	v_mul_f32_e32 v20, v210, v20
	v_mul_f32_e32 v210, v163, v38
	v_mul_f32_e32 v21, v210, v21
	v_mul_f32_e32 v210, v164, v38
	v_mul_f32_e32 v22, v210, v22
	v_mul_f32_e32 v210, v165, v38
	v_mul_f32_e32 v23, v210, v23
	v_mul_f32_e32 v210, v166, v38
	v_mul_f32_e32 v24, v210, v24
	v_mul_f32_e32 v210, v167, v38
	v_mul_f32_e32 v25, v210, v25
	s_cmp_eq_u32 s40, 0
	s_cbranch_scc1 .Lmb_qplain
	v_mul_f32_e32 v202, v22, v191
	v_mul_f32_e32 v203, v23, v192
	v_mul_f32_e32 v204, v24, v193
	v_mul_f32_e32 v205, v25, v194
	v_fmac_f32_dpp v202, v22, v195 row_shl:4 row_mask:0xf bank_mask:0x5
	v_fmac_f32_dpp v202, v22, v195 row_shr:4 row_mask:0xf bank_mask:0xa
	v_fmac_f32_dpp v203, v23, v196 row_shl:4 row_mask:0xf bank_mask:0x5
	v_fmac_f32_dpp v203, v23, v196 row_shr:4 row_mask:0xf bank_mask:0xa
	v_fmac_f32_dpp v204, v24, v197 row_shl:4 row_mask:0xf bank_mask:0x5
	v_fmac_f32_dpp v204, v24, v197 row_shr:4 row_mask:0xf bank_mask:0xa
	v_fmac_f32_dpp v205, v25, v198 row_shl:4 row_mask:0xf bank_mask:0x5
	v_fmac_f32_dpp v205, v25, v198 row_shr:4 row_mask:0xf bank_mask:0xa
	s_branch .Lmb_qpack

; __device__ __forceinline__ u16 f2bf(float f) { return (u16)(pack2(f, 0.f) & 0xffffu); }
; __device__ __forceinline__ void phase_mix_b(const Params& p, int l, bool last, unsigned char* smem) {
;     ...
;   for (int row = gw; row < TT; row += nw) {
;     ...
;         u16* o = p.Qall + ((size_t)(b * 4 + h) * NPOS + pos) * 192;
;         o[lane] = f2bf(v0 * QSCALE); o[lane + 64] = f2bf(v1 * QSCALE); o[lane + 128] = f2bf(v2 * QSCALE);
.Lmb_qpack:
	v_mul_f32_e32 v14, 0x3dd53b94, v14
	v_mul_f32_e32 v15, 0x3dd53b94, v15
	v_mul_f32_e32 v16, 0x3dd53b94, v16
	v_mul_f32_e32 v17, 0x3dd53b94, v17
	v_mul_f32_e32 v18, 0x3dd53b94, v18
	v_mul_f32_e32 v19, 0x3dd53b94, v19
	v_mul_f32_e32 v20, 0x3dd53b94, v20
	v_mul_f32_e32 v21, 0x3dd53b94, v21
	v_mul_f32_e32 v202, 0x3dd53b94, v202
	v_mul_f32_e32 v203, 0x3dd53b94, v203
	v_mul_f32_e32 v204, 0x3dd53b94, v204
	v_mul_f32_e32 v205, 0x3dd53b94, v205
	v_cvt_pk_bf16_f32 v216, v14, v15
	v_cvt_pk_bf16_f32 v217, v16, v17
	v_cvt_pk_bf16_f32 v218, v18, v19
	v_cvt_pk_bf16_f32 v219, v20, v21
	v_cvt_pk_bf16_f32 v220, v202, v203
	v_cvt_pk_bf16_f32 v221, v204, v205
	global_store_dwordx4 v154, v[216:219], s[98:99]
	global_store_dwordx2 v155, v[220:221], s[98:99]
.Lmb_next:
	s_cmp_lg_u32 s8, 0
	s_cbranch_scc1 .Lmb_row

; __device__ __forceinline__ void phase_topk(const Params& p, bool last, unsigned char* smem) {
;     ...
;     unsigned ngt, neq;
;     unsigned og = block_incl_scan(cgt, wsum, lane, wid, ngt) - cgt;
;     unsigned oe = block_incl_scan(ceq, wsum, lane, wid, neq) - ceq;
;     int* idx = p.IDXG + (size_t)inst * 1024;
;     float* gt = p.GATE + (size_t)inst * 1024;
;     int* inv = p.INV + (size_t)rowbase * 16 + (inst & 15);
.LBB0_1026:
	ds_bpermute_b32 v2, v17, v13
	s_waitcnt lgkmcnt(0)
	s_barrier
	v_cndmask_b32_e64 v2, v2, 0, s[38:39]
	v_add_u32_e32 v2, v2, v13
	ds_bpermute_b32 v3, v18, v2
	s_waitcnt lgkmcnt(0)
	v_cndmask_b32_e64 v3, v3, 0, s[40:41]
	v_add_u32_e32 v2, v3, v2
	ds_bpermute_b32 v3, v19, v2
	s_waitcnt lgkmcnt(0)
	v_cndmask_b32_e64 v3, v3, 0, s[42:43]
	v_add_u32_e32 v2, v3, v2
	ds_bpermute_b32 v3, v20, v2
	s_waitcnt lgkmcnt(0)
	v_cndmask_b32_e64 v3, v3, 0, s[44:45]
	v_add_u32_e32 v2, v3, v2
	ds_bpermute_b32 v3, v21, v2
	s_waitcnt lgkmcnt(0)
	v_cndmask_b32_e64 v3, v3, 0, s[46:47]
	v_add_u32_e32 v2, v3, v2
	ds_bpermute_b32 v3, v22, v2
	s_waitcnt lgkmcnt(0)
	v_cndmask_b32_e64 v3, v3, 0, s[48:49]
	v_add_u32_e32 v15, v3, v2
	s_and_saveexec_b64 s[8:9], s[50:51]
	ds_write_b32 v23, v15 offset:33792
	s_or_b64 exec, exec, s[8:9]
	ds_bpermute_b32 v2, v17, v0
	s_waitcnt lgkmcnt(0)
	s_barrier
	v_cndmask_b32_e64 v2, v2, 0, s[38:39]
	v_add_u32_e32 v2, v2, v0
	ds_bpermute_b32 v3, v18, v2
	s_waitcnt lgkmcnt(0)
	v_cndmask_b32_e64 v3, v3, 0, s[40:41]
	v_add_u32_e32 v2, v3, v2
	ds_bpermute_b32 v3, v19, v2
	s_waitcnt lgkmcnt(0)
	v_cndmask_b32_e64 v3, v3, 0, s[42:43]
	v_add_u32_e32 v2, v3, v2
	ds_bpermute_b32 v3, v20, v2
	s_waitcnt lgkmcnt(0)
	v_cndmask_b32_e64 v3, v3, 0, s[44:45]
	v_add_u32_e32 v2, v3, v2
	ds_bpermute_b32 v3, v21, v2
	s_waitcnt lgkmcnt(0)
	v_cndmask_b32_e64 v3, v3, 0, s[46:47]
	v_add_u32_e32 v14, v3, v2
	ds_bpermute_b32 v27, v22, v14
	ds_read_b128 v[2:5], v1 offset:33792
	s_waitcnt lgkmcnt(0)
	s_barrier
	v_cndmask_b32_e64 v27, v27, 0, s[48:49]
	v_add_u32_e32 v14, v27, v14
	s_and_saveexec_b64 s[8:9], s[50:51]
	ds_write_b32 v23, v14 offset:33792
	s_or_b64 exec, exec, s[8:9]
	v_add_u32_e32 v27, v3, v2
	v_add_u32_e32 v27, v27, v4
	v_add_u32_e32 v27, v27, v5
	v_cndmask_b32_e64 v2, 0, v2, s[52:53]
	v_sub_u32_e32 v5, v15, v13
	v_cndmask_b32_e64 v3, 0, v3, s[54:55]
	v_cndmask_b32_e64 v4, 0, v4, s[56:57]
	v_add_u32_e32 v2, v5, v2
	v_add3_u32 v13, v2, v3, v4
	s_waitcnt lgkmcnt(0)
	s_barrier
	ds_read_b96 v[2:4], v1 offset:33792
	v_sub_u32_e32 v0, v14, v0
	s_ashr_i32 s87, s86, 31
	s_lshl_b64 s[8:9], s[86:87], 12
	s_ashr_i32 s59, s58, 31
	s_waitcnt lgkmcnt(0)
	v_cndmask_b32_e64 v2, 0, v2, s[52:53]
	v_cndmask_b32_e64 v3, 0, v3, s[54:55]
	v_cndmask_b32_e64 v4, 0, v4, s[56:57]
	v_add_u32_e32 v0, v0, v2
	v_add3_u32 v28, v0, v3, v4
	v_mov_b64_e32 v[4:5], s[0:1]
	global_load_dwordx4 v[30:33], v[4:5], off offset:408
	s_waitcnt vmcnt(0) lgkmcnt(0)
	v_lshl_add_u64 v[2:3], v[30:31], 0, s[8:9]
	s_load_dwordx2 s[100:101], s[0:1], 0x180
	s_waitcnt lgkmcnt(0)
	v_mov_b32_e32 v4, s100
	v_mov_b32_e32 v5, s101
	s_waitcnt lgkmcnt(0)
	v_lshl_add_u64 v[4:5], v[4:5], 0, s[8:9]
	s_lshl_b64 s[8:9], s[58:59], 6
	v_lshl_add_u64 v[14:15], v[32:33], 0, s[8:9]
	s_and_b32 s8, s86, 15
	s_lshl_b32 s94, s8, 2
	v_lshl_add_u64 v[14:15], v[14:15], 0, s[94:95]
	s_branch .LBB0_1032

; template <int NT, bool BKN, bool MASK = false, bool ROWSS = false, class Epi> ...
;     ...
;   for (int kt = 0; kt < nk - 2; kt += 2) {
;     GEMM_COMPUTE(0);
;     GEMM_STORE(ra1, rb1, 1);
;     GEMM_LOAD(ra1, rb1, kt + 3);
;     __syncthreads();
;     GEMM_COMPUTE(1);
;     GEMM_STORE(ra0, rb0, 0);
;     GEMM_LOAD(ra0, rb0, (kt + 4 < nkm1 ? kt + 4 : nkm1));
;     __syncthreads();
;   }
.LBB0_1162:
	ds_read_b128 v[158:161], v169
	ds_read_b128 v[172:175], v168 offset:16384
	ds_read_b128 v[176:179], v169 offset:2048
	ds_read_b128 v[180:183], v168 offset:18432
	ds_read_b128 v[188:191], v168 offset:20480
	ds_read_b128 v[192:195], v168 offset:22528
	s_add_i32 s0, s0, 2
	s_waitcnt lgkmcnt(0)
	v_mfma_f32_16x16x32_bf16 v[78:81], v[158:161], v[172:175], v[78:81]
	s_min_u32 s1, s0, 11
	s_lshl_b32 s94, s1, 7
	s_cmp_lt_u32 s0, 12
	s_waitcnt lgkmcnt(2)
	v_mfma_f32_16x16x32_bf16 v[74:77], v[158:161], v[180:183], v[74:77]
	s_waitcnt lgkmcnt(1)
	v_mfma_f32_16x16x32_bf16 v[66:69], v[158:161], v[188:191], v[66:69]
	s_waitcnt lgkmcnt(0)
	v_mfma_f32_16x16x32_bf16 v[70:73], v[158:161], v[192:195], v[70:73]
	v_mfma_f32_16x16x32_bf16 v[90:93], v[176:179], v[172:175], v[90:93]
	v_mfma_f32_16x16x32_bf16 v[86:89], v[176:179], v[180:183], v[86:89]
	v_mfma_f32_16x16x32_bf16 v[82:85], v[176:179], v[188:191], v[82:85]
	v_mfma_f32_16x16x32_bf16 v[114:117], v[176:179], v[192:195], v[114:117]
	ds_read_b128 v[158:161], v169 offset:4096
	ds_read_b128 v[176:179], v169 offset:6144
	s_waitcnt lgkmcnt(0)
	v_mfma_f32_16x16x32_bf16 v[102:105], v[158:161], v[172:175], v[102:105]
	v_mfma_f32_16x16x32_bf16 v[110:113], v[158:161], v[180:183], v[110:113]
	v_mfma_f32_16x16x32_bf16 v[106:109], v[158:161], v[188:191], v[106:109]
	v_mfma_f32_16x16x32_bf16 v[98:101], v[158:161], v[192:195], v[98:101]
	ds_read_b128 v[158:161], v167
	s_waitcnt lgkmcnt(1)
	v_mfma_f32_16x16x32_bf16 v[94:97], v[176:179], v[172:175], v[94:97]
	v_mfma_f32_16x16x32_bf16 v[126:129], v[176:179], v[180:183], v[126:129]
	v_mfma_f32_16x16x32_bf16 v[122:125], v[176:179], v[188:191], v[122:125]
	v_mfma_f32_16x16x32_bf16 v[118:121], v[176:179], v[192:195], v[118:121]
	ds_read_b128 v[172:175], v166 offset:16384
	ds_read_b128 v[176:179], v167 offset:2048
	ds_read_b128 v[180:183], v166 offset:18432
	ds_read_b128 v[188:191], v166 offset:20480
	ds_read_b128 v[192:195], v166 offset:22528
	ds_read_b128 v[196:199], v167 offset:4096
	ds_read_b128 v[200:203], v167 offset:6144
	s_waitcnt vmcnt(0)
	ds_write_b128 v170, v[14:17] offset:32768
	ds_write_b128 v170, v[10:13] offset:36864
	ds_write_b128 v170, v[6:9] offset:40960
	ds_write_b128 v170, v[18:21] offset:45056
	ds_write_b128 v170, v[2:5] offset:49152
	ds_write_b128 v170, v[30:33] offset:53248
	ds_write_b128 v170, v[22:25] offset:57344
	ds_write_b128 v170, v[26:29] offset:61440
	v_lshl_add_u64 v[2:3], v[156:157], 0, v[0:1]
	v_lshl_add_u64 v[4:5], v[154:155], 0, v[0:1]
	v_lshl_add_u64 v[6:7], v[152:153], 0, v[0:1]
	v_lshl_add_u64 v[18:19], v[150:151], 0, v[0:1]
	v_lshl_add_u64 v[22:23], v[148:149], 0, v[0:1]
	v_lshl_add_u64 v[24:25], v[146:147], 0, v[0:1]
	global_load_dwordx4 v[14:17], v[2:3], off
	global_load_dwordx4 v[10:13], v[4:5], off
	s_nop 0
	global_load_dwordx4 v[6:9], v[6:7], off
	s_nop 0
	global_load_dwordx4 v[18:21], v[18:19], off
	s_nop 0
	global_load_dwordx4 v[2:5], v[22:23], off
	v_add_co_u32_e32 v22, vcc, s15, v24
	s_waitcnt lgkmcnt(0)
	v_mfma_f32_16x16x32_bf16 v[78:81], v[158:161], v[172:175], v[78:81]
	v_addc_co_u32_e32 v23, vcc, 0, v25, vcc
	v_add_co_u32_e32 v26, vcc, s16, v24
	v_mfma_f32_16x16x32_bf16 v[74:77], v[158:161], v[180:183], v[74:77]
	s_nop 0
	v_addc_co_u32_e32 v27, vcc, 0, v25, vcc
	v_add_co_u32_e32 v28, vcc, s17, v24
	v_mfma_f32_16x16x32_bf16 v[66:69], v[158:161], v[188:191], v[66:69]
	s_nop 0
	v_addc_co_u32_e32 v29, vcc, 0, v25, vcc
	global_load_dwordx4 v[30:33], v[22:23], off offset:384
	s_nop 0
	global_load_dwordx4 v[22:25], v[26:27], off offset:384
	s_nop 0
	global_load_dwordx4 v[26:29], v[28:29], off offset:384
	v_mfma_f32_16x16x32_bf16 v[70:73], v[158:161], v[192:195], v[70:73]
	s_waitcnt lgkmcnt(0)
	s_barrier
	ds_read_b128 v[158:161], v169 offset:32768
	v_mfma_f32_16x16x32_bf16 v[90:93], v[176:179], v[172:175], v[90:93]
	v_lshl_add_u64 v[146:147], v[146:147], 0, s[6:7]
	v_lshl_add_u64 v[148:149], v[148:149], 0, s[6:7]
	v_lshl_add_u64 v[150:151], v[150:151], 0, s[6:7]
	v_mfma_f32_16x16x32_bf16 v[86:89], v[176:179], v[180:183], v[86:89]
	v_lshl_add_u64 v[152:153], v[152:153], 0, s[6:7]
	v_lshl_add_u64 v[154:155], v[154:155], 0, s[6:7]
	v_lshl_add_u64 v[156:157], v[156:157], 0, s[6:7]
	v_mfma_f32_16x16x32_bf16 v[82:85], v[176:179], v[188:191], v[82:85]
	v_mfma_f32_16x16x32_bf16 v[114:117], v[176:179], v[192:195], v[114:117]
	v_mfma_f32_16x16x32_bf16 v[102:105], v[196:199], v[172:175], v[102:105]
	v_mfma_f32_16x16x32_bf16 v[110:113], v[196:199], v[180:183], v[110:113]
	v_mfma_f32_16x16x32_bf16 v[106:109], v[196:199], v[188:191], v[106:109]
	v_mfma_f32_16x16x32_bf16 v[98:101], v[196:199], v[192:195], v[98:101]
	v_mfma_f32_16x16x32_bf16 v[94:97], v[200:203], v[172:175], v[94:97]
	v_mfma_f32_16x16x32_bf16 v[126:129], v[200:203], v[180:183], v[126:129]
	ds_read_b128 v[172:175], v168 offset:49152
	ds_read_b128 v[176:179], v169 offset:34816
	ds_read_b128 v[180:183], v168 offset:51200
	v_mfma_f32_16x16x32_bf16 v[122:125], v[200:203], v[188:191], v[122:125]
	v_mfma_f32_16x16x32_bf16 v[118:121], v[200:203], v[192:195], v[118:121]
	ds_read_b128 v[188:191], v168 offset:53248
	ds_read_b128 v[192:195], v168 offset:55296
	s_waitcnt lgkmcnt(0)
	v_mfma_f32_16x16x32_bf16 v[78:81], v[158:161], v[172:175], v[78:81]
	v_mfma_f32_16x16x32_bf16 v[74:77], v[158:161], v[180:183], v[74:77]
	v_mfma_f32_16x16x32_bf16 v[66:69], v[158:161], v[188:191], v[66:69]
	v_mfma_f32_16x16x32_bf16 v[70:73], v[158:161], v[192:195], v[70:73]
	v_mfma_f32_16x16x32_bf16 v[90:93], v[176:179], v[172:175], v[90:93]
	v_mfma_f32_16x16x32_bf16 v[86:89], v[176:179], v[180:183], v[86:89]
	v_mfma_f32_16x16x32_bf16 v[82:85], v[176:179], v[188:191], v[82:85]
	v_mfma_f32_16x16x32_bf16 v[114:117], v[176:179], v[192:195], v[114:117]
	ds_read_b128 v[158:161], v169 offset:36864
	ds_read_b128 v[176:179], v169 offset:38912
	s_waitcnt lgkmcnt(0)
; template <int NT, bool BKN, bool MASK = false, bool ROWSS = false, class Epi> ...
;     ...
;     GEMM_COMPUTE(1);
;     GEMM_STORE(ra0, rb0, 0);
;     GEMM_LOAD(ra0, rb0, (kt + 4 < nkm1 ? kt + 4 : nkm1));
;     __syncthreads();
;   }
;   GEMM_COMPUTE(0);
;   GEMM_STORE(ra1, rb1, 1);
;   __syncthreads();
;   GEMM_COMPUTE(1);
	v_mfma_f32_16x16x32_bf16 v[102:105], v[158:161], v[172:175], v[102:105]
	v_mfma_f32_16x16x32_bf16 v[110:113], v[158:161], v[180:183], v[110:113]
	v_mfma_f32_16x16x32_bf16 v[106:109], v[158:161], v[188:191], v[106:109]
	v_mfma_f32_16x16x32_bf16 v[98:101], v[158:161], v[192:195], v[98:101]
	ds_read_b128 v[158:161], v167 offset:32768
	v_mfma_f32_16x16x32_bf16 v[94:97], v[176:179], v[172:175], v[94:97]
	v_mfma_f32_16x16x32_bf16 v[126:129], v[176:179], v[180:183], v[126:129]
	v_mfma_f32_16x16x32_bf16 v[122:125], v[176:179], v[188:191], v[122:125]
	v_mfma_f32_16x16x32_bf16 v[118:121], v[176:179], v[192:195], v[118:121]
	ds_read_b128 v[172:175], v166 offset:49152
	ds_read_b128 v[176:179], v167 offset:34816
	ds_read_b128 v[180:183], v166 offset:51200
	ds_read_b128 v[188:191], v166 offset:53248
	ds_read_b128 v[192:195], v166 offset:55296
	s_waitcnt lgkmcnt(0)
	v_mfma_f32_16x16x32_bf16 v[78:81], v[158:161], v[172:175], v[78:81]
	v_mfma_f32_16x16x32_bf16 v[74:77], v[158:161], v[180:183], v[74:77]
	v_mfma_f32_16x16x32_bf16 v[66:69], v[158:161], v[188:191], v[66:69]
	v_mfma_f32_16x16x32_bf16 v[70:73], v[158:161], v[192:195], v[70:73]
	ds_read_b128 v[158:161], v167 offset:36864
	ds_read_b128 v[196:199], v167 offset:38912
	ds_write_b128 v170, v[34:37]
	ds_write_b128 v170, v[38:41] offset:4096
	ds_write_b128 v170, v[42:45] offset:8192
	ds_write_b128 v170, v[46:49] offset:12288
	ds_write_b128 v170, v[50:53] offset:16384
	ds_write_b128 v170, v[58:61] offset:20480
	ds_write_b128 v170, v[54:57] offset:24576
	ds_write_b128 v170, v[62:65] offset:28672
	v_lshl_add_u64 v[34:35], v[134:135], 0, s[94:95]
	v_lshl_add_u64 v[38:39], v[132:133], 0, s[94:95]
	v_lshl_add_u64 v[42:43], v[130:131], 0, s[94:95]
	v_lshl_add_u64 v[46:47], v[136:137], 0, s[94:95]
	v_lshl_add_u64 v[50:51], v[138:139], 0, s[94:95]
	v_lshl_add_u64 v[54:55], v[140:141], 0, s[94:95]
	v_lshl_add_u64 v[56:57], v[142:143], 0, s[94:95]
	v_lshl_add_u64 v[62:63], v[144:145], 0, s[94:95]
	global_load_dwordx4 v[34:37], v[34:35], off offset:512
	s_nop 0
	global_load_dwordx4 v[38:41], v[38:39], off offset:512
	s_nop 0
	global_load_dwordx4 v[42:45], v[42:43], off offset:512
	s_nop 0
	global_load_dwordx4 v[46:49], v[46:47], off offset:512
	s_nop 0
	global_load_dwordx4 v[50:53], v[50:51], off offset:512
	s_nop 0
	global_load_dwordx4 v[58:61], v[54:55], off offset:512
	s_nop 0
	global_load_dwordx4 v[54:57], v[56:57], off offset:512
	v_mfma_f32_16x16x32_bf16 v[90:93], v[176:179], v[172:175], v[90:93]
	global_load_dwordx4 v[62:65], v[62:63], off offset:512
	s_waitcnt lgkmcnt(0)
	s_barrier
	v_mfma_f32_16x16x32_bf16 v[86:89], v[176:179], v[180:183], v[86:89]
	v_mfma_f32_16x16x32_bf16 v[82:85], v[176:179], v[188:191], v[82:85]
	v_mfma_f32_16x16x32_bf16 v[114:117], v[176:179], v[192:195], v[114:117]
	v_mfma_f32_16x16x32_bf16 v[102:105], v[158:161], v[172:175], v[102:105]
	v_mfma_f32_16x16x32_bf16 v[110:113], v[158:161], v[180:183], v[110:113]
	v_mfma_f32_16x16x32_bf16 v[106:109], v[158:161], v[188:191], v[106:109]
	v_mfma_f32_16x16x32_bf16 v[98:101], v[158:161], v[192:195], v[98:101]
	v_mfma_f32_16x16x32_bf16 v[94:97], v[196:199], v[172:175], v[94:97]
	v_mfma_f32_16x16x32_bf16 v[126:129], v[196:199], v[180:183], v[126:129]
	v_mfma_f32_16x16x32_bf16 v[122:125], v[196:199], v[188:191], v[122:125]
	v_mfma_f32_16x16x32_bf16 v[118:121], v[196:199], v[192:195], v[118:121]
	s_cbranch_scc1 .LBB0_1162
	s_waitcnt vmcnt(0)
	ds_read_b128 v[34:37], v169
	ds_read_b128 v[38:41], v169 offset:2048
	ds_read_b128 v[42:45], v169 offset:4096
	ds_read_b128 v[46:49], v169 offset:6144
	ds_read_b128 v[50:53], v168 offset:16384
	ds_read_b128 v[54:57], v168 offset:18432
	ds_read_b128 v[58:61], v168 offset:20480
	ds_read_b128 v[62:65], v168 offset:22528
	v_lshlrev_b32_e32 v0, 6, v164
	s_waitcnt lgkmcnt(3)
	v_mfma_f32_16x16x32_bf16 v[78:81], v[34:37], v[50:53], v[78:81]
	v_lshl_or_b32 v0, v165, 2, v0
	v_mul_lo_u32 v0, v0, s96
	s_waitcnt lgkmcnt(2)
	v_mfma_f32_16x16x32_bf16 v[74:77], v[34:37], v[54:57], v[74:77]
	s_waitcnt lgkmcnt(1)
	v_mfma_f32_16x16x32_bf16 v[66:69], v[34:37], v[58:61], v[66:69]
	s_waitcnt lgkmcnt(0)
	v_mfma_f32_16x16x32_bf16 v[34:37], v[34:37], v[62:65], v[70:73]
	v_mfma_f32_16x16x32_bf16 v[70:73], v[38:41], v[50:53], v[90:93]
	v_mfma_f32_16x16x32_bf16 v[86:89], v[38:41], v[54:57], v[86:89]
	v_mfma_f32_16x16x32_bf16 v[82:85], v[38:41], v[58:61], v[82:85]
	v_mfma_f32_16x16x32_bf16 v[38:41], v[38:41], v[62:65], v[114:117]
	v_mfma_f32_16x16x32_bf16 v[90:93], v[42:45], v[50:53], v[102:105]
	v_mfma_f32_16x16x32_bf16 v[102:105], v[42:45], v[54:57], v[110:113]
	v_mfma_f32_16x16x32_bf16 v[106:109], v[42:45], v[58:61], v[106:109]
	v_mfma_f32_16x16x32_bf16 v[42:45], v[42:45], v[62:65], v[98:101]
	v_mfma_f32_16x16x32_bf16 v[50:53], v[46:49], v[50:53], v[94:97]
	v_mfma_f32_16x16x32_bf16 v[54:57], v[46:49], v[54:57], v[126:129]
	v_mfma_f32_16x16x32_bf16 v[58:61], v[46:49], v[58:61], v[122:125]
	v_mfma_f32_16x16x32_bf16 v[46:49], v[46:49], v[62:65], v[118:121]
	ds_read_b128 v[62:65], v167
	ds_read_b128 v[94:97], v167 offset:2048
	ds_read_b128 v[98:101], v167 offset:4096
	ds_read_b128 v[110:113], v167 offset:6144
	ds_read_b128 v[114:117], v166 offset:16384
	ds_read_b128 v[118:121], v166 offset:18432
	ds_read_b128 v[122:125], v166 offset:20480
	ds_read_b128 v[126:129], v166 offset:22528
	ds_write_b128 v170, v[14:17] offset:32768
	ds_write_b128 v170, v[10:13] offset:36864
	ds_write_b128 v170, v[6:9] offset:40960
	ds_write_b128 v170, v[18:21] offset:45056
	ds_write_b128 v170, v[2:5] offset:49152
	ds_write_b128 v170, v[30:33] offset:53248
	ds_write_b128 v170, v[22:25] offset:57344
	ds_write_b128 v170, v[26:29] offset:61440
	s_waitcnt lgkmcnt(0)
	v_mfma_f32_16x16x32_bf16 v[78:81], v[62:65], v[114:117], v[78:81]
	s_barrier
; __device__ __forceinline__ u16 f2bf(float f) { return (u16)(pack2(f, 0.f) & 0xffffu); }
; __device__ __forceinline__ int tid_() { int t = threadIdx.x; asm volatile("" : "+v"(t)); return t; }
; __device__ __forceinline__ float silu_f(float x) { return x / (1.f + __expf(-x)); }
; template <int NT, bool BKN, bool MASK = false, bool ROWSS = false, class Epi> ...
;     ...
;   GEMM_COMPUTE(1);
; __device__ __forceinline__ void phase_moe_up(const Params& p, int l, bool last, unsigned char* smem) {
;     ...
;     auto epi = [&](f32x4(&acc)[4][4], int r0, int c0) {
;       u16* Ts = (u16*)smem;
;       const int t2 = tid_();
;       __syncthreads();
; #pragma unroll
;       for (int mi = 0; mi < 4; ++mi)
; #pragma unroll
;         for (int n2 = 0; n2 < 2; ++n2)
; #pragma unroll
;           for (int j = 0; j < 4; ++j) {
;             const int m = r0 + mi * 16 + j;
;             const int fl = (c0 >> 6) * 32 + n2 * 16 + (c0 & 15);
;             Ts[m * 72 + fl] = f2bf(silu_f(acc[mi][2 * n2][j]) * acc[mi][2 * n2 + 1][j]);
;           }
	ds_read_b128 v[2:5], v169 offset:32768
	ds_read_b128 v[6:9], v169 offset:34816
	ds_read_b128 v[10:13], v169 offset:36864
	ds_read_b128 v[14:17], v169 offset:38912
	ds_read_b128 v[18:21], v168 offset:49152
	ds_read_b128 v[22:25], v168 offset:51200
	ds_read_b128 v[26:29], v168 offset:53248
	ds_read_b128 v[30:33], v168 offset:55296
	v_mfma_f32_16x16x32_bf16 v[74:77], v[62:65], v[118:121], v[74:77]
	v_mfma_f32_16x16x32_bf16 v[66:69], v[62:65], v[122:125], v[66:69]
	v_mfma_f32_16x16x32_bf16 v[34:37], v[62:65], v[126:129], v[34:37]
	v_mfma_f32_16x16x32_bf16 v[62:65], v[94:97], v[114:117], v[70:73]
	v_mfma_f32_16x16x32_bf16 v[70:73], v[94:97], v[118:121], v[86:89]
	v_mfma_f32_16x16x32_bf16 v[86:89], v[98:101], v[114:117], v[90:93]
	v_mfma_f32_16x16x32_bf16 v[90:93], v[98:101], v[118:121], v[102:105]
	v_mfma_f32_16x16x32_bf16 v[50:53], v[110:113], v[114:117], v[50:53]
	v_mfma_f32_16x16x32_bf16 v[54:57], v[110:113], v[118:121], v[54:57]
	v_mfma_f32_16x16x32_bf16 v[58:61], v[110:113], v[122:125], v[58:61]
	v_mfma_f32_16x16x32_bf16 v[46:49], v[110:113], v[126:129], v[46:49]
	s_waitcnt lgkmcnt(3)
	v_mfma_f32_16x16x32_bf16 v[78:81], v[2:5], v[18:21], v[78:81]
	v_mfma_f32_16x16x32_bf16 v[82:85], v[94:97], v[122:125], v[82:85]
	v_mfma_f32_16x16x32_bf16 v[38:41], v[94:97], v[126:129], v[38:41]
	v_mfma_f32_16x16x32_bf16 v[94:97], v[98:101], v[122:125], v[106:109]
	v_mfma_f32_16x16x32_bf16 v[42:45], v[98:101], v[126:129], v[42:45]
	s_waitcnt lgkmcnt(2)
	v_mfma_f32_16x16x32_bf16 v[74:77], v[2:5], v[22:25], v[74:77]
	s_waitcnt lgkmcnt(1)
	v_mfma_f32_16x16x32_bf16 v[66:69], v[2:5], v[26:29], v[66:69]
	s_waitcnt lgkmcnt(0)
	v_mfma_f32_16x16x32_bf16 v[2:5], v[2:5], v[30:33], v[34:37]
	v_mfma_f32_16x16x32_bf16 v[34:37], v[6:9], v[18:21], v[62:65]
	v_mfma_f32_16x16x32_bf16 v[70:73], v[6:9], v[22:25], v[70:73]
	v_mfma_f32_16x16x32_bf16 v[86:89], v[10:13], v[18:21], v[86:89]
	v_mfma_f32_16x16x32_bf16 v[90:93], v[10:13], v[22:25], v[90:93]
	v_mfma_f32_16x16x32_bf16 v[98:101], v[14:17], v[18:21], v[50:53]
	v_mfma_f32_16x16x32_bf16 v[102:105], v[14:17], v[22:25], v[54:57]
	v_mfma_f32_16x16x32_bf16 v[106:109], v[14:17], v[26:29], v[58:61]
	v_mfma_f32_16x16x32_bf16 v[110:113], v[14:17], v[30:33], v[46:49]
	ds_read_b128 v[14:17], v167 offset:32768
	ds_read_b128 v[18:21], v167 offset:34816
	ds_read_b128 v[22:25], v167 offset:36864
	ds_read_b128 v[114:117], v167 offset:38912
	ds_read_b128 v[118:121], v166 offset:49152
	ds_read_b128 v[122:125], v166 offset:51200
	ds_read_b128 v[126:129], v166 offset:53248
	ds_read_b128 v[130:133], v166 offset:55296
	s_waitcnt lgkmcnt(3)
	v_mfma_f32_16x16x32_bf16 v[58:61], v[14:17], v[118:121], v[78:81]
	s_waitcnt lgkmcnt(1)
	v_mfma_f32_16x16x32_bf16 v[50:53], v[14:17], v[126:129], v[66:69]
	v_mfma_f32_16x16x32_bf16 v[46:49], v[18:21], v[122:125], v[70:73]
	s_nop 4
	v_mul_f32_e32 v68, 0xbfb8aa3b, v58
	v_exp_f32_e32 v68, v68
	v_lshlrev_b32_e32 v67, 5, v163
	v_mfma_f32_16x16x32_bf16 v[62:65], v[14:17], v[122:125], v[74:77]
	v_and_or_b32 v67, v67, 32, v162
	v_add_f32_e32 v68, 1.0, v68
	v_div_scale_f32 v69, s[0:1], v68, v68, v58
	v_rcp_f32_e32 v70, v69
	v_mov_b32_e32 v66, v187
	v_lshl_add_u32 v0, v67, 1, v0
	v_fma_f32 v71, -v69, v70, 1.0
	v_fmac_f32_e32 v70, v71, v70
	v_div_scale_f32 v71, vcc, v58, v68, v58
	v_mul_f32_e32 v72, v71, v70
	v_fma_f32 v73, -v69, v72, v71
	v_fmac_f32_e32 v72, v73, v70
	v_fma_f32 v69, -v69, v72, v71
	v_div_fmas_f32 v69, v69, v70, v72
	v_div_fixup_f32 v58, v69, v68, v58
	v_mul_f32_e32 v58, v62, v58
	v_cvt_pk_bf16_f32 v58, v58, s0
	s_waitcnt lgkmcnt(0)
	s_barrier
	ds_write_b16 v0, v58
	v_mul_f32_e32 v58, 0xbfb8aa3b, v59
	v_exp_f32_e32 v58, v58
	v_mfma_f32_16x16x32_bf16 v[54:57], v[14:17], v[130:133], v[2:5]
	v_add_f32_e32 v58, 1.0, v58
	v_div_scale_f32 v62, s[0:1], v58, v58, v59
	v_rcp_f32_e32 v67, v62
	v_mfma_f32_16x16x32_bf16 v[94:97], v[10:13], v[26:29], v[94:97]
	v_fma_f32 v68, -v62, v67, 1.0
	v_fmac_f32_e32 v67, v68, v67
	v_div_scale_f32 v68, vcc, v59, v58, v59
	v_mul_f32_e32 v69, v68, v67
	v_fma_f32 v70, -v62, v69, v68
	v_fmac_f32_e32 v69, v70, v67
	v_fma_f32 v62, -v62, v69, v68
	v_div_fmas_f32 v62, v62, v67, v69
	v_div_fixup_f32 v58, v62, v58, v59
	v_mul_f32_e32 v58, v63, v58
	v_cvt_pk_bf16_f32 v58, v58, s0
	ds_write_b16 v0, v58 offset:144
	v_mul_f32_e32 v58, 0xbfb8aa3b, v60
	v_exp_f32_e32 v58, v58
	v_mfma_f32_16x16x32_bf16 v[10:13], v[10:13], v[30:33], v[42:45]
	v_add_f32_e32 v58, 1.0, v58
	v_div_scale_f32 v59, s[0:1], v58, v58, v60
	v_rcp_f32_e32 v62, v59
	v_mfma_f32_16x16x32_bf16 v[42:45], v[18:21], v[118:121], v[34:37]
	v_fma_f32 v63, -v59, v62, 1.0
	v_fmac_f32_e32 v62, v63, v62
	v_div_scale_f32 v63, vcc, v60, v58, v60
	v_mul_f32_e32 v67, v63, v62
	v_fma_f32 v68, -v59, v67, v63
	v_fmac_f32_e32 v67, v68, v62
	v_fma_f32 v59, -v59, v67, v63
	v_div_fmas_f32 v59, v59, v62, v67
	v_div_fixup_f32 v58, v59, v58, v60
	v_mul_f32_e32 v58, v64, v58
	v_cvt_pk_bf16_f32 v58, v58, s0
	ds_write_b16 v0, v58 offset:288
	v_mul_f32_e32 v58, 0xbfb8aa3b, v61
	v_exp_f32_e32 v58, v58
	v_mfma_f32_16x16x32_bf16 v[82:85], v[6:9], v[26:29], v[82:85]
	v_add_f32_e32 v58, 1.0, v58
	v_div_scale_f32 v59, s[0:1], v58, v58, v61
	v_rcp_f32_e32 v60, v59
	v_mfma_f32_16x16x32_bf16 v[34:37], v[18:21], v[126:129], v[82:85]
	v_fma_f32 v62, -v59, v60, 1.0
	v_fmac_f32_e32 v60, v62, v60
	v_div_scale_f32 v62, vcc, v61, v58, v61
	v_mul_f32_e32 v63, v62, v60
	v_fma_f32 v64, -v59, v63, v62
	v_fmac_f32_e32 v63, v64, v60
	v_fma_f32 v59, -v59, v63, v62
	v_div_fmas_f32 v59, v59, v60, v63
	v_div_fixup_f32 v58, v59, v58, v61
	v_mul_f32_e32 v58, v65, v58
	v_cvt_pk_bf16_f32 v58, v58, s0
	ds_write_b16 v0, v58 offset:432
	v_mul_f32_e32 v58, 0xbfb8aa3b, v50
; __device__ __forceinline__ u16 f2bf(float f) { return (u16)(pack2(f, 0.f) & 0xffffu); }
; __device__ __forceinline__ float silu_f(float x) { return x / (1.f + __expf(-x)); }
; __device__ __forceinline__ void phase_moe_up(const Params& p, int l, bool last, unsigned char* smem) {
;     ...
; #pragma unroll
;       for (int mi = 0; mi < 4; ++mi)
; #pragma unroll
;         for (int n2 = 0; n2 < 2; ++n2)
; #pragma unroll
;           for (int j = 0; j < 4; ++j) {
;             const int m = r0 + mi * 16 + j;
;             const int fl = (c0 >> 6) * 32 + n2 * 16 + (c0 & 15);
;             Ts[m * 72 + fl] = f2bf(silu_f(acc[mi][2 * n2][j]) * acc[mi][2 * n2 + 1][j]);
;           }
	v_exp_f32_e32 v58, v58
	v_mfma_f32_16x16x32_bf16 v[6:9], v[6:9], v[30:33], v[38:41]
	v_add_f32_e32 v58, 1.0, v58
	v_div_scale_f32 v59, s[0:1], v58, v58, v50
	v_rcp_f32_e32 v60, v59
	v_mfma_f32_16x16x32_bf16 v[38:41], v[18:21], v[130:133], v[6:9]
	v_fma_f32 v61, -v59, v60, 1.0
	v_fmac_f32_e32 v60, v61, v60
	v_div_scale_f32 v61, vcc, v50, v58, v50
	v_mul_f32_e32 v62, v61, v60
	v_fma_f32 v63, -v59, v62, v61
	v_fmac_f32_e32 v62, v63, v60
	v_fma_f32 v59, -v59, v62, v61
	v_div_fmas_f32 v59, v59, v60, v62
	v_div_fixup_f32 v50, v59, v58, v50
	v_mul_f32_e32 v50, v54, v50
	v_cvt_pk_bf16_f32 v50, v50, s0
	ds_write_b16 v0, v50 offset:32
	v_mul_f32_e32 v50, 0xbfb8aa3b, v51
	v_exp_f32_e32 v50, v50
	v_mfma_f32_16x16x32_bf16 v[26:29], v[22:25], v[118:121], v[86:89]
	v_add_f32_e32 v50, 1.0, v50
	v_div_scale_f32 v54, s[0:1], v50, v50, v51
	v_rcp_f32_e32 v58, v54
	v_mfma_f32_16x16x32_bf16 v[30:33], v[22:25], v[122:125], v[90:93]
	v_fma_f32 v59, -v54, v58, 1.0
	v_fmac_f32_e32 v58, v59, v58
	v_div_scale_f32 v59, vcc, v51, v50, v51
	v_mul_f32_e32 v60, v59, v58
	v_fma_f32 v61, -v54, v60, v59
	v_fmac_f32_e32 v60, v61, v58
	v_fma_f32 v54, -v54, v60, v59
	v_div_fmas_f32 v54, v54, v58, v60
	v_div_fixup_f32 v50, v54, v50, v51
	v_mul_f32_e32 v50, v55, v50
	v_cvt_pk_bf16_f32 v50, v50, s0
	ds_write_b16 v0, v50 offset:176
	v_mul_f32_e32 v50, 0xbfb8aa3b, v52
	v_exp_f32_e32 v50, v50
	v_mfma_f32_16x16x32_bf16 v[18:21], v[22:25], v[126:129], v[94:97]
	v_add_f32_e32 v50, 1.0, v50
	v_div_scale_f32 v51, s[0:1], v50, v50, v52
	v_rcp_f32_e32 v54, v51
	v_mfma_f32_16x16x32_bf16 v[22:25], v[22:25], v[130:133], v[10:13]
	v_fma_f32 v55, -v51, v54, 1.0
	v_fmac_f32_e32 v54, v55, v54
	v_div_scale_f32 v55, vcc, v52, v50, v52
	v_mul_f32_e32 v58, v55, v54
	v_fma_f32 v59, -v51, v58, v55
	v_fmac_f32_e32 v58, v59, v54
	v_fma_f32 v51, -v51, v58, v55
	v_div_fmas_f32 v51, v51, v54, v58
	v_div_fixup_f32 v50, v51, v50, v52
	v_mul_f32_e32 v50, v56, v50
	v_cvt_pk_bf16_f32 v50, v50, s0
	ds_write_b16 v0, v50 offset:320
	v_mul_f32_e32 v50, 0xbfb8aa3b, v53
	v_exp_f32_e32 v50, v50
	v_mfma_f32_16x16x32_bf16 v[10:13], v[114:117], v[118:121], v[98:101]
	v_add_f32_e32 v50, 1.0, v50
	v_div_scale_f32 v51, s[0:1], v50, v50, v53
	v_rcp_f32_e32 v52, v51
	v_mfma_f32_16x16x32_bf16 v[14:17], v[114:117], v[122:125], v[102:105]
	v_fma_f32 v54, -v51, v52, 1.0
	v_fmac_f32_e32 v52, v54, v52
	v_div_scale_f32 v54, vcc, v53, v50, v53
	v_mul_f32_e32 v55, v54, v52
	v_fma_f32 v56, -v51, v55, v54
	v_fmac_f32_e32 v55, v56, v52
	v_fma_f32 v51, -v51, v55, v54
	v_div_fmas_f32 v51, v51, v52, v55
	v_div_fixup_f32 v50, v51, v50, v53
	v_mul_f32_e32 v50, v57, v50
	v_cvt_pk_bf16_f32 v50, v50, s0
	ds_write_b16 v0, v50 offset:464
	v_mul_f32_e32 v50, 0xbfb8aa3b, v42
	v_exp_f32_e32 v50, v50
	v_mfma_f32_16x16x32_bf16 v[2:5], v[114:117], v[126:129], v[106:109]
	v_add_f32_e32 v50, 1.0, v50
	v_div_scale_f32 v51, s[0:1], v50, v50, v42
	v_rcp_f32_e32 v52, v51
	v_mfma_f32_16x16x32_bf16 v[6:9], v[114:117], v[130:133], v[110:113]
	v_fma_f32 v53, -v51, v52, 1.0
	v_fmac_f32_e32 v52, v53, v52
	v_div_scale_f32 v53, vcc, v42, v50, v42
	v_mul_f32_e32 v54, v53, v52
	v_fma_f32 v55, -v51, v54, v53
	v_fmac_f32_e32 v54, v55, v52
	v_fma_f32 v51, -v51, v54, v53
	v_div_fmas_f32 v51, v51, v52, v54
	v_div_fixup_f32 v42, v51, v50, v42
	v_mul_f32_e32 v42, v46, v42
	v_cvt_pk_bf16_f32 v42, v42, s0
	ds_write_b16 v0, v42 offset:2304
	v_mul_f32_e32 v42, 0xbfb8aa3b, v43
	v_exp_f32_e32 v42, v42
	s_nop 0
	v_add_f32_e32 v42, 1.0, v42
	v_div_scale_f32 v46, s[0:1], v42, v42, v43
	v_rcp_f32_e32 v50, v46
	s_nop 0
	v_fma_f32 v51, -v46, v50, 1.0
	v_fmac_f32_e32 v50, v51, v50
	v_div_scale_f32 v51, vcc, v43, v42, v43
	v_mul_f32_e32 v52, v51, v50
	v_fma_f32 v53, -v46, v52, v51
	v_fmac_f32_e32 v52, v53, v50
	v_fma_f32 v46, -v46, v52, v51
	v_div_fmas_f32 v46, v46, v50, v52
	v_div_fixup_f32 v42, v46, v42, v43
	v_mul_f32_e32 v42, v47, v42
	v_cvt_pk_bf16_f32 v42, v42, s0
	ds_write_b16 v0, v42 offset:2448
	v_mul_f32_e32 v42, 0xbfb8aa3b, v44
	v_exp_f32_e32 v42, v42
	s_nop 0
	v_add_f32_e32 v42, 1.0, v42
	v_div_scale_f32 v43, s[0:1], v42, v42, v44
	v_rcp_f32_e32 v46, v43
	s_nop 0
	v_fma_f32 v47, -v43, v46, 1.0
	v_fmac_f32_e32 v46, v47, v46
	v_div_scale_f32 v47, vcc, v44, v42, v44
	v_mul_f32_e32 v50, v47, v46
	v_fma_f32 v51, -v43, v50, v47
	v_fmac_f32_e32 v50, v51, v46
	v_fma_f32 v43, -v43, v50, v47
	v_div_fmas_f32 v43, v43, v46, v50
	v_div_fixup_f32 v42, v43, v42, v44
	v_mul_f32_e32 v42, v48, v42
	v_cvt_pk_bf16_f32 v42, v42, s0
	ds_write_b16 v0, v42 offset:2592
	v_mul_f32_e32 v42, 0xbfb8aa3b, v45
	v_exp_f32_e32 v42, v42
	s_nop 0
	v_add_f32_e32 v42, 1.0, v42
	v_div_scale_f32 v43, s[0:1], v42, v42, v45
	v_rcp_f32_e32 v44, v43
	s_nop 0
	v_fma_f32 v46, -v43, v44, 1.0
	v_fmac_f32_e32 v44, v46, v44
	v_div_scale_f32 v46, vcc, v45, v42, v45
	v_mul_f32_e32 v47, v46, v44
	v_fma_f32 v48, -v43, v47, v46
	v_fmac_f32_e32 v47, v48, v44
	v_fma_f32 v43, -v43, v47, v46
	v_div_fmas_f32 v43, v43, v44, v47
	v_div_fixup_f32 v42, v43, v42, v45
	v_mul_f32_e32 v42, v49, v42
	v_cvt_pk_bf16_f32 v42, v42, s0
	ds_write_b16 v0, v42 offset:2736
	v_mul_f32_e32 v42, 0xbfb8aa3b, v34
	v_exp_f32_e32 v42, v42
	s_nop 0
	v_add_f32_e32 v42, 1.0, v42
	v_div_scale_f32 v43, s[0:1], v42, v42, v34
	v_rcp_f32_e32 v44, v43
	s_nop 0
	v_fma_f32 v45, -v43, v44, 1.0
	v_fmac_f32_e32 v44, v45, v44
	v_div_scale_f32 v45, vcc, v34, v42, v34
	v_mul_f32_e32 v46, v45, v44
	v_fma_f32 v47, -v43, v46, v45
	v_fmac_f32_e32 v46, v47, v44
	v_fma_f32 v43, -v43, v46, v45
	v_div_fmas_f32 v43, v43, v44, v46
	v_div_fixup_f32 v34, v43, v42, v34
	v_mul_f32_e32 v34, v38, v34
	v_cvt_pk_bf16_f32 v34, v34, s0
	ds_write_b16 v0, v34 offset:2336
	v_mul_f32_e32 v34, 0xbfb8aa3b, v35
; __device__ __forceinline__ u16 f2bf(float f) { return (u16)(pack2(f, 0.f) & 0xffffu); }
; __device__ __forceinline__ float silu_f(float x) { return x / (1.f + __expf(-x)); }
; __device__ __forceinline__ void phase_moe_up(const Params& p, int l, bool last, unsigned char* smem) {
;     ...
; #pragma unroll
;       for (int mi = 0; mi < 4; ++mi)
; #pragma unroll
;         for (int n2 = 0; n2 < 2; ++n2)
; #pragma unroll
;           for (int j = 0; j < 4; ++j) {
;             const int m = r0 + mi * 16 + j;
;             const int fl = (c0 >> 6) * 32 + n2 * 16 + (c0 & 15);
;             Ts[m * 72 + fl] = f2bf(silu_f(acc[mi][2 * n2][j]) * acc[mi][2 * n2 + 1][j]);
;           }
	v_exp_f32_e32 v34, v34
	s_nop 0
	v_add_f32_e32 v34, 1.0, v34
	v_div_scale_f32 v38, s[0:1], v34, v34, v35
	v_rcp_f32_e32 v42, v38
	s_nop 0
	v_fma_f32 v43, -v38, v42, 1.0
	v_fmac_f32_e32 v42, v43, v42
	v_div_scale_f32 v43, vcc, v35, v34, v35
	v_mul_f32_e32 v44, v43, v42
	v_fma_f32 v45, -v38, v44, v43
	v_fmac_f32_e32 v44, v45, v42
	v_fma_f32 v38, -v38, v44, v43
	v_div_fmas_f32 v38, v38, v42, v44
	v_div_fixup_f32 v34, v38, v34, v35
	v_mul_f32_e32 v34, v39, v34
	v_cvt_pk_bf16_f32 v34, v34, s0
	ds_write_b16 v0, v34 offset:2480
	v_mul_f32_e32 v34, 0xbfb8aa3b, v36
	v_exp_f32_e32 v34, v34
	s_nop 0
	v_add_f32_e32 v34, 1.0, v34
	v_div_scale_f32 v35, s[0:1], v34, v34, v36
	v_rcp_f32_e32 v38, v35
	s_nop 0
	v_fma_f32 v39, -v35, v38, 1.0
	v_fmac_f32_e32 v38, v39, v38
	v_div_scale_f32 v39, vcc, v36, v34, v36
	v_mul_f32_e32 v42, v39, v38
	v_fma_f32 v43, -v35, v42, v39
	v_fmac_f32_e32 v42, v43, v38
	v_fma_f32 v35, -v35, v42, v39
	v_div_fmas_f32 v35, v35, v38, v42
	v_div_fixup_f32 v34, v35, v34, v36
	v_mul_f32_e32 v34, v40, v34
	v_cvt_pk_bf16_f32 v34, v34, s0
	ds_write_b16 v0, v34 offset:2624
	v_mul_f32_e32 v34, 0xbfb8aa3b, v37
	v_exp_f32_e32 v34, v34
	s_nop 0
	v_add_f32_e32 v34, 1.0, v34
	v_div_scale_f32 v35, s[0:1], v34, v34, v37
	v_rcp_f32_e32 v36, v35
	s_nop 0
	v_fma_f32 v38, -v35, v36, 1.0
	v_fmac_f32_e32 v36, v38, v36
	v_div_scale_f32 v38, vcc, v37, v34, v37
	v_mul_f32_e32 v39, v38, v36
	v_fma_f32 v40, -v35, v39, v38
	v_fmac_f32_e32 v39, v40, v36
	v_fma_f32 v35, -v35, v39, v38
	v_div_fmas_f32 v35, v35, v36, v39
	v_div_fixup_f32 v34, v35, v34, v37
	v_mul_f32_e32 v34, v41, v34
	v_cvt_pk_bf16_f32 v34, v34, s0
	ds_write_b16 v0, v34 offset:2768
	v_mul_f32_e32 v34, 0xbfb8aa3b, v26
	v_exp_f32_e32 v34, v34
	s_nop 0
	v_add_f32_e32 v34, 1.0, v34
	v_div_scale_f32 v35, s[0:1], v34, v34, v26
	v_rcp_f32_e32 v36, v35
	s_nop 0
	v_fma_f32 v37, -v35, v36, 1.0
	v_fmac_f32_e32 v36, v37, v36
	v_div_scale_f32 v37, vcc, v26, v34, v26
	v_mul_f32_e32 v38, v37, v36
	v_fma_f32 v39, -v35, v38, v37
	v_fmac_f32_e32 v38, v39, v36
	v_fma_f32 v35, -v35, v38, v37
	v_div_fmas_f32 v35, v35, v36, v38
	v_div_fixup_f32 v26, v35, v34, v26
	v_mul_f32_e32 v26, v30, v26
	v_cvt_pk_bf16_f32 v26, v26, s0
	ds_write_b16 v0, v26 offset:4608
	v_mul_f32_e32 v26, 0xbfb8aa3b, v27
	v_exp_f32_e32 v26, v26
	s_nop 0
	v_add_f32_e32 v26, 1.0, v26
	v_div_scale_f32 v30, s[0:1], v26, v26, v27
	v_rcp_f32_e32 v34, v30
	s_nop 0
	v_fma_f32 v35, -v30, v34, 1.0
	v_fmac_f32_e32 v34, v35, v34
	v_div_scale_f32 v35, vcc, v27, v26, v27
	v_mul_f32_e32 v36, v35, v34
	v_fma_f32 v37, -v30, v36, v35
	v_fmac_f32_e32 v36, v37, v34
	v_fma_f32 v30, -v30, v36, v35
	v_div_fmas_f32 v30, v30, v34, v36
	v_div_fixup_f32 v26, v30, v26, v27
	v_mul_f32_e32 v26, v31, v26
	v_cvt_pk_bf16_f32 v26, v26, s0
	ds_write_b16 v0, v26 offset:4752
	v_mul_f32_e32 v26, 0xbfb8aa3b, v28
	v_exp_f32_e32 v26, v26
	s_nop 0
	v_add_f32_e32 v26, 1.0, v26
	v_div_scale_f32 v27, s[0:1], v26, v26, v28
	v_rcp_f32_e32 v30, v27
	s_nop 0
	v_fma_f32 v31, -v27, v30, 1.0
	v_fmac_f32_e32 v30, v31, v30
	v_div_scale_f32 v31, vcc, v28, v26, v28
	v_mul_f32_e32 v34, v31, v30
	v_fma_f32 v35, -v27, v34, v31
	v_fmac_f32_e32 v34, v35, v30
	v_fma_f32 v27, -v27, v34, v31
	v_div_fmas_f32 v27, v27, v30, v34
	v_div_fixup_f32 v26, v27, v26, v28
	v_mul_f32_e32 v26, v32, v26
	v_cvt_pk_bf16_f32 v26, v26, s0
	ds_write_b16 v0, v26 offset:4896
	v_mul_f32_e32 v26, 0xbfb8aa3b, v29
	v_exp_f32_e32 v26, v26
	s_nop 0
	v_add_f32_e32 v26, 1.0, v26
	v_div_scale_f32 v27, s[0:1], v26, v26, v29
	v_rcp_f32_e32 v28, v27
	s_nop 0
	v_fma_f32 v30, -v27, v28, 1.0
	v_fmac_f32_e32 v28, v30, v28
	v_div_scale_f32 v30, vcc, v29, v26, v29
	v_mul_f32_e32 v31, v30, v28
	v_fma_f32 v32, -v27, v31, v30
	v_fmac_f32_e32 v31, v32, v28
	v_fma_f32 v27, -v27, v31, v30
	v_div_fmas_f32 v27, v27, v28, v31
	v_div_fixup_f32 v26, v27, v26, v29
	v_mul_f32_e32 v26, v33, v26
	v_cvt_pk_bf16_f32 v26, v26, s0
	ds_write_b16 v0, v26 offset:5040
	v_mul_f32_e32 v26, 0xbfb8aa3b, v18
	v_exp_f32_e32 v26, v26
	s_nop 0
	v_add_f32_e32 v26, 1.0, v26
	v_div_scale_f32 v27, s[0:1], v26, v26, v18
	v_rcp_f32_e32 v28, v27
	s_nop 0
	v_fma_f32 v29, -v27, v28, 1.0
	v_fmac_f32_e32 v28, v29, v28
	v_div_scale_f32 v29, vcc, v18, v26, v18
	v_mul_f32_e32 v30, v29, v28
	v_fma_f32 v31, -v27, v30, v29
	v_fmac_f32_e32 v30, v31, v28
	v_fma_f32 v27, -v27, v30, v29
	v_div_fmas_f32 v27, v27, v28, v30
	v_div_fixup_f32 v18, v27, v26, v18
	v_mul_f32_e32 v18, v22, v18
	v_cvt_pk_bf16_f32 v18, v18, s0
	ds_write_b16 v0, v18 offset:4640
	v_mul_f32_e32 v18, 0xbfb8aa3b, v19
	v_exp_f32_e32 v18, v18
	s_nop 0
	v_add_f32_e32 v18, 1.0, v18
	v_div_scale_f32 v22, s[0:1], v18, v18, v19
	v_rcp_f32_e32 v26, v22
	s_nop 0
	v_fma_f32 v27, -v22, v26, 1.0
	v_fmac_f32_e32 v26, v27, v26
	v_div_scale_f32 v27, vcc, v19, v18, v19
	v_mul_f32_e32 v28, v27, v26
	v_fma_f32 v29, -v22, v28, v27
	v_fmac_f32_e32 v28, v29, v26
	v_fma_f32 v22, -v22, v28, v27
	v_div_fmas_f32 v22, v22, v26, v28
	v_div_fixup_f32 v18, v22, v18, v19
	v_mul_f32_e32 v18, v23, v18
	v_cvt_pk_bf16_f32 v18, v18, s0
	ds_write_b16 v0, v18 offset:4784
	v_mul_f32_e32 v18, 0xbfb8aa3b, v20
	v_exp_f32_e32 v18, v18
	s_nop 0
	v_add_f32_e32 v18, 1.0, v18
	v_div_scale_f32 v19, s[0:1], v18, v18, v20
	v_rcp_f32_e32 v22, v19
	s_nop 0
	v_fma_f32 v23, -v19, v22, 1.0
	v_fmac_f32_e32 v22, v23, v22
	v_div_scale_f32 v23, vcc, v20, v18, v20
	v_mul_f32_e32 v26, v23, v22
	v_fma_f32 v27, -v19, v26, v23
	v_fmac_f32_e32 v26, v27, v22
	v_fma_f32 v19, -v19, v26, v23
	v_div_fmas_f32 v19, v19, v22, v26
	v_div_fixup_f32 v18, v19, v18, v20
	v_mul_f32_e32 v18, v24, v18
	v_cvt_pk_bf16_f32 v18, v18, s0
	ds_write_b16 v0, v18 offset:4928
	v_mul_f32_e32 v18, 0xbfb8aa3b, v21
; __device__ __forceinline__ void phase_moe_up(const Params& p, int l, bool last, unsigned char* smem) {
;     ...
;       __syncthreads();
; #pragma unroll
;       for (int i = 0; i < 4; ++i) {
;         const int c = t2 + 256 * i, row = c >> 3, ch = c & 7;
;         if (row < mvalid) *(u32x4*)(p.HID + (size_t)(hid_row + row) * 512 + nt * 64 + ch * 8) = *(const u32x4*)(Ts + row * 72 + ch * 8);
	v_exp_f32_e32 v18, v18
	s_nop 0
	v_add_f32_e32 v18, 1.0, v18
	v_div_scale_f32 v19, s[0:1], v18, v18, v21
	v_rcp_f32_e32 v20, v19
	s_nop 0
	v_fma_f32 v22, -v19, v20, 1.0
	v_fmac_f32_e32 v20, v22, v20
	v_div_scale_f32 v22, vcc, v21, v18, v21
	v_mul_f32_e32 v23, v22, v20
	v_fma_f32 v24, -v19, v23, v22
	v_fmac_f32_e32 v23, v24, v20
	v_fma_f32 v19, -v19, v23, v22
	v_div_fmas_f32 v19, v19, v20, v23
	v_div_fixup_f32 v18, v19, v18, v21
	v_mul_f32_e32 v18, v25, v18
	v_cvt_pk_bf16_f32 v18, v18, s0
	ds_write_b16 v0, v18 offset:5072
	v_mul_f32_e32 v18, 0xbfb8aa3b, v10
	v_exp_f32_e32 v18, v18
	s_nop 0
	v_add_f32_e32 v18, 1.0, v18
	v_div_scale_f32 v19, s[0:1], v18, v18, v10
	v_rcp_f32_e32 v20, v19
	s_nop 0
	v_fma_f32 v21, -v19, v20, 1.0
	v_fmac_f32_e32 v20, v21, v20
	v_div_scale_f32 v21, vcc, v10, v18, v10
	v_mul_f32_e32 v22, v21, v20
	v_fma_f32 v23, -v19, v22, v21
	v_fmac_f32_e32 v22, v23, v20
	v_fma_f32 v19, -v19, v22, v21
	v_div_fmas_f32 v19, v19, v20, v22
	v_div_fixup_f32 v10, v19, v18, v10
	v_mul_f32_e32 v10, v14, v10
	v_cvt_pk_bf16_f32 v10, v10, s0
	ds_write_b16 v0, v10 offset:6912
	v_mul_f32_e32 v10, 0xbfb8aa3b, v11
	v_exp_f32_e32 v10, v10
	s_nop 0
	v_add_f32_e32 v10, 1.0, v10
	v_div_scale_f32 v14, s[0:1], v10, v10, v11
	v_rcp_f32_e32 v18, v14
	s_nop 0
	v_fma_f32 v19, -v14, v18, 1.0
	v_fmac_f32_e32 v18, v19, v18
	v_div_scale_f32 v19, vcc, v11, v10, v11
	v_mul_f32_e32 v20, v19, v18
	v_fma_f32 v21, -v14, v20, v19
	v_fmac_f32_e32 v20, v21, v18
	v_fma_f32 v14, -v14, v20, v19
	v_div_fmas_f32 v14, v14, v18, v20
	v_div_fixup_f32 v10, v14, v10, v11
	v_mul_f32_e32 v10, v15, v10
	v_cvt_pk_bf16_f32 v10, v10, s0
	ds_write_b16 v0, v10 offset:7056
	v_mul_f32_e32 v10, 0xbfb8aa3b, v12
	v_exp_f32_e32 v10, v10
	s_nop 0
	v_add_f32_e32 v10, 1.0, v10
	v_div_scale_f32 v11, s[0:1], v10, v10, v12
	v_rcp_f32_e32 v14, v11
	s_nop 0
	v_fma_f32 v15, -v11, v14, 1.0
	v_fmac_f32_e32 v14, v15, v14
	v_div_scale_f32 v15, vcc, v12, v10, v12
	v_mul_f32_e32 v18, v15, v14
	v_fma_f32 v19, -v11, v18, v15
	v_fmac_f32_e32 v18, v19, v14
	v_fma_f32 v11, -v11, v18, v15
	v_div_fmas_f32 v11, v11, v14, v18
	v_div_fixup_f32 v10, v11, v10, v12
	v_mul_f32_e32 v10, v16, v10
	v_cvt_pk_bf16_f32 v10, v10, s0
	ds_write_b16 v0, v10 offset:7200
	v_mul_f32_e32 v10, 0xbfb8aa3b, v13
	v_exp_f32_e32 v10, v10
	s_nop 0
	v_add_f32_e32 v10, 1.0, v10
	v_div_scale_f32 v11, s[0:1], v10, v10, v13
	v_rcp_f32_e32 v12, v11
	s_nop 0
	v_fma_f32 v14, -v11, v12, 1.0
	v_fmac_f32_e32 v12, v14, v12
	v_div_scale_f32 v14, vcc, v13, v10, v13
	v_mul_f32_e32 v15, v14, v12
	v_fma_f32 v16, -v11, v15, v14
	v_fmac_f32_e32 v15, v16, v12
	v_fma_f32 v11, -v11, v15, v14
	v_div_fmas_f32 v11, v11, v12, v15
	v_div_fixup_f32 v10, v11, v10, v13
	v_mul_f32_e32 v10, v17, v10
	v_cvt_pk_bf16_f32 v10, v10, s0
	ds_write_b16 v0, v10 offset:7344
	v_mul_f32_e32 v10, 0xbfb8aa3b, v2
	v_exp_f32_e32 v10, v10
	s_nop 0
	v_add_f32_e32 v10, 1.0, v10
	v_div_scale_f32 v11, s[0:1], v10, v10, v2
	v_rcp_f32_e32 v12, v11
	s_nop 0
	v_fma_f32 v13, -v11, v12, 1.0
	v_fmac_f32_e32 v12, v13, v12
	v_div_scale_f32 v13, vcc, v2, v10, v2
	v_mul_f32_e32 v14, v13, v12
	v_fma_f32 v15, -v11, v14, v13
	v_fmac_f32_e32 v14, v15, v12
	v_fma_f32 v11, -v11, v14, v13
	v_div_fmas_f32 v11, v11, v12, v14
	v_div_fixup_f32 v2, v11, v10, v2
	v_mul_f32_e32 v2, v6, v2
	v_cvt_pk_bf16_f32 v2, v2, s0
	ds_write_b16 v0, v2 offset:6944
	v_mul_f32_e32 v2, 0xbfb8aa3b, v3
	v_exp_f32_e32 v2, v2
	s_nop 0
	v_add_f32_e32 v2, 1.0, v2
	v_div_scale_f32 v6, s[0:1], v2, v2, v3
	v_rcp_f32_e32 v10, v6
	s_nop 0
	v_fma_f32 v11, -v6, v10, 1.0
	v_fmac_f32_e32 v10, v11, v10
	v_div_scale_f32 v11, vcc, v3, v2, v3
	v_mul_f32_e32 v12, v11, v10
	v_fma_f32 v13, -v6, v12, v11
	v_fmac_f32_e32 v12, v13, v10
	v_fma_f32 v6, -v6, v12, v11
	v_div_fmas_f32 v6, v6, v10, v12
	v_div_fixup_f32 v2, v6, v2, v3
	v_mul_f32_e32 v2, v7, v2
	v_cvt_pk_bf16_f32 v2, v2, s0
	ds_write_b16 v0, v2 offset:7088
	v_mul_f32_e32 v2, 0xbfb8aa3b, v4
	v_exp_f32_e32 v2, v2
	s_nop 0
	v_add_f32_e32 v2, 1.0, v2
	v_div_scale_f32 v3, s[0:1], v2, v2, v4
	v_rcp_f32_e32 v6, v3
	s_nop 0
	v_fma_f32 v7, -v3, v6, 1.0
	v_fmac_f32_e32 v6, v7, v6
	v_div_scale_f32 v7, vcc, v4, v2, v4
	v_mul_f32_e32 v10, v7, v6
	v_fma_f32 v11, -v3, v10, v7
	v_fmac_f32_e32 v10, v11, v6
	v_fma_f32 v3, -v3, v10, v7
	v_div_fmas_f32 v3, v3, v6, v10
	v_div_fixup_f32 v2, v3, v2, v4
	v_mul_f32_e32 v2, v8, v2
	v_cvt_pk_bf16_f32 v2, v2, s0
	ds_write_b16 v0, v2 offset:7232
	v_mul_f32_e32 v2, 0xbfb8aa3b, v5
	v_exp_f32_e32 v2, v2
	s_nop 0
	v_add_f32_e32 v2, 1.0, v2
	v_div_scale_f32 v3, s[0:1], v2, v2, v5
	v_rcp_f32_e32 v4, v3
	s_nop 0
	v_fma_f32 v6, -v3, v4, 1.0
	v_fmac_f32_e32 v4, v6, v4
	v_div_scale_f32 v6, vcc, v5, v2, v5
	v_mul_f32_e32 v7, v6, v4
	v_fma_f32 v8, -v3, v7, v6
	v_fmac_f32_e32 v7, v8, v4
	v_fma_f32 v3, -v3, v7, v6
	v_div_fmas_f32 v3, v3, v4, v7
	v_div_fixup_f32 v2, v3, v2, v5
	v_mul_f32_e32 v2, v9, v2
	v_cvt_pk_bf16_f32 v2, v2, s0
	ds_write_b16 v0, v2 offset:7376
	v_lshlrev_b32_e32 v0, 3, v66
	v_and_b32_e32 v0, 56, v0
	v_ashrrev_i32_e32 v3, 3, v66
	v_lshlrev_b32_e32 v2, 1, v0
	v_cmp_gt_i32_e32 vcc, s86, v3
	s_waitcnt lgkmcnt(0)
	s_barrier
	s_and_saveexec_b64 s[0:1], vcc
	s_cbranch_execz .LBB0_1165
	v_mov_b64_e32 v[4:5], s[4:5]
	s_load_dwordx2 s[100:101], s[4:5], 0x170
	s_waitcnt lgkmcnt(0)
	v_mov_b32_e32 v8, s100
	v_mov_b32_e32 v9, s101
	v_mad_u64_u32 v[4:5], s[8:9], v3, s96, v[2:3]
	v_add_u32_e32 v10, s82, v3
	ds_read_b128 v[4:7], v4
	v_ashrrev_i32_e32 v11, 31, v10
	v_lshlrev_b64 v[10:11], 10, v[10:11]
	s_lshl_b32 s94, s83, 7
	v_mov_b32_e32 v3, v1
	s_waitcnt lgkmcnt(0)
	v_lshl_add_u64 v[8:9], v[8:9], 0, v[10:11]
	v_lshl_add_u64 v[8:9], v[8:9], 0, s[94:95]
	v_lshl_add_u64 v[8:9], v[8:9], 0, v[2:3]
	global_store_dwordx4 v[8:9], v[4:7], off
; __device__ __forceinline__ void phase_moe_up(const Params& p, int l, bool last, unsigned char* smem) {
;     ...
;       __syncthreads();
; #pragma unroll
;       for (int i = 0; i < 4; ++i) {
;         const int c = t2 + 256 * i, row = c >> 3, ch = c & 7;
;         if (row < mvalid) *(u32x4*)(p.HID + (size_t)(hid_row + row) * 512 + nt * 64 + ch * 8) = *(const u32x4*)(Ts + row * 72 + ch * 8);
.LBB0_1165:
	s_or_b64 exec, exec, s[0:1]
	v_add_u32_e32 v3, 0x100, v66
	v_ashrrev_i32_e32 v3, 3, v3
	v_cmp_gt_i32_e32 vcc, s86, v3
	s_and_saveexec_b64 s[0:1], vcc
	s_cbranch_execz .LBB0_1167
	v_mov_b64_e32 v[4:5], s[4:5]
	s_load_dwordx2 s[100:101], s[4:5], 0x170
	s_waitcnt lgkmcnt(0)
	v_mov_b32_e32 v8, s100
	v_mov_b32_e32 v9, s101
	v_mad_u64_u32 v[4:5], s[8:9], v3, s96, v[2:3]
	v_add_u32_e32 v10, s82, v3
	ds_read_b128 v[4:7], v4
	v_ashrrev_i32_e32 v11, 31, v10
	v_lshlrev_b64 v[10:11], 10, v[10:11]
	s_lshl_b32 s94, s83, 7
	v_mov_b32_e32 v3, v1
	s_waitcnt lgkmcnt(0)
	v_lshl_add_u64 v[8:9], v[8:9], 0, v[10:11]
	v_lshl_add_u64 v[8:9], v[8:9], 0, s[94:95]
	v_lshl_add_u64 v[8:9], v[8:9], 0, v[2:3]
	global_store_dwordx4 v[8:9], v[4:7], off
.LBB0_1167:
	s_or_b64 exec, exec, s[0:1]
	v_add_u32_e32 v3, 0x200, v66
	v_ashrrev_i32_e32 v3, 3, v3
	v_cmp_gt_i32_e32 vcc, s86, v3
	s_and_saveexec_b64 s[0:1], vcc
	s_cbranch_execz .LBB0_1169
	v_mov_b64_e32 v[4:5], s[4:5]
	s_load_dwordx2 s[100:101], s[4:5], 0x170
	s_waitcnt lgkmcnt(0)
	v_mov_b32_e32 v8, s100
	v_mov_b32_e32 v9, s101
	v_mad_u64_u32 v[4:5], s[8:9], v3, s96, v[2:3]
	v_add_u32_e32 v10, s82, v3
	ds_read_b128 v[4:7], v4
	v_ashrrev_i32_e32 v11, 31, v10
	v_lshlrev_b64 v[10:11], 10, v[10:11]
	s_lshl_b32 s94, s83, 7
	v_mov_b32_e32 v3, v1
	s_waitcnt lgkmcnt(0)
	v_lshl_add_u64 v[8:9], v[8:9], 0, v[10:11]
	v_lshl_add_u64 v[8:9], v[8:9], 0, s[94:95]
	v_lshl_add_u64 v[2:3], v[8:9], 0, v[2:3]
	global_store_dwordx4 v[2:3], v[4:7], off

; __device__ __forceinline__ u16 f2bf(float f) { return (u16)(pack2(f, 0.f) & 0xffffu); }
; __device__ __forceinline__ float silu_f(float x) { return x / (1.f + __expf(-x)); }
; __device__ __forceinline__ void phase_moe_up(const Params& p, int l, bool last, unsigned char* smem) {
;     ...
; #pragma unroll
;       for (int mi = 0; mi < 4; ++mi)
; #pragma unroll
;         for (int n2 = 0; n2 < 2; ++n2)
; #pragma unroll
;           for (int j = 0; j < 4; ++j) {
;             const int m = r0 + mi * 16 + j;
;             const int fl = (c0 >> 6) * 32 + n2 * 16 + (c0 & 15);
;             Ts[m * 72 + fl] = f2bf(silu_f(acc[mi][2 * n2][j]) * acc[mi][2 * n2 + 1][j]);
;           }
.LBB0_1194:
	s_waitcnt lgkmcnt(4)
	v_mul_f32_e32 v66, 0xbfb8aa3b, v62
	v_exp_f32_e32 v68, v66
	v_lshl_or_b32 v0, v196, 2, v197
	v_lshlrev_b32_e32 v67, 5, v195
	v_and_or_b32 v67, v67, 32, v194
	v_add_f32_e32 v68, 1.0, v68
	v_div_scale_f32 v69, s[0:1], v68, v68, v62
	s_waitcnt lgkmcnt(3)
	v_rcp_f32_e32 v70, v69
	v_mul_lo_u32 v0, v0, s96
	v_mov_b32_e32 v66, v187
	v_lshl_add_u32 v0, v67, 1, v0
	v_fma_f32 v71, -v69, v70, 1.0
	v_fmac_f32_e32 v70, v71, v70
	v_div_scale_f32 v71, vcc, v62, v68, v62
	v_mul_f32_e32 v72, v71, v70
	v_fma_f32 v73, -v69, v72, v71
	v_fmac_f32_e32 v72, v73, v70
	v_fma_f32 v69, -v69, v72, v71
	v_div_fmas_f32 v69, v69, v70, v72
	v_mul_f32_e32 v70, 0xbfb8aa3b, v63
	v_exp_f32_e32 v70, v70
	v_div_fixup_f32 v62, v69, v68, v62
	v_mul_f32_e32 v58, v58, v62
	v_cvt_pk_bf16_f32 v58, v58, s0
	v_add_f32_e32 v62, 1.0, v70
	v_div_scale_f32 v68, s[0:1], v62, v62, v63
	v_rcp_f32_e32 v69, v68
	s_waitcnt lgkmcnt(0)
	s_barrier
	ds_write_b16 v0, v58
	v_fma_f32 v58, -v68, v69, 1.0
	v_fmac_f32_e32 v69, v58, v69
	v_div_scale_f32 v58, vcc, v63, v62, v63
	v_mul_f32_e32 v67, v58, v69
	v_fma_f32 v70, -v68, v67, v58
	v_fmac_f32_e32 v67, v70, v69
	v_fma_f32 v58, -v68, v67, v58
	v_mul_f32_e32 v68, 0xbfb8aa3b, v64
	v_exp_f32_e32 v68, v68
	v_div_fmas_f32 v58, v58, v69, v67
	v_div_fixup_f32 v58, v58, v62, v63
	v_mul_f32_e32 v58, v59, v58
	v_add_f32_e32 v62, 1.0, v68
	v_div_scale_f32 v63, s[0:1], v62, v62, v64
	v_rcp_f32_e32 v67, v63
	s_nop 0
	v_cvt_pk_bf16_f32 v58, v58, s0
	ds_write_b16 v0, v58 offset:144
	v_fma_f32 v58, -v63, v67, 1.0
	v_fmac_f32_e32 v67, v58, v67
	v_div_scale_f32 v58, vcc, v64, v62, v64
	v_mul_f32_e32 v59, v58, v67
	v_fma_f32 v68, -v63, v59, v58
	v_fmac_f32_e32 v59, v68, v67
	v_fma_f32 v58, -v63, v59, v58
	v_mul_f32_e32 v63, 0xbfb8aa3b, v65
	v_exp_f32_e32 v63, v63
	v_div_fmas_f32 v58, v58, v67, v59
	v_div_fixup_f32 v58, v58, v62, v64
	v_mul_f32_e32 v58, v60, v58
	v_add_f32_e32 v59, 1.0, v63
	v_div_scale_f32 v62, s[0:1], v59, v59, v65
	v_rcp_f32_e32 v63, v62
	s_nop 0
	v_cvt_pk_bf16_f32 v58, v58, s0
	ds_write_b16 v0, v58 offset:288
	v_fma_f32 v58, -v62, v63, 1.0
	v_fmac_f32_e32 v63, v58, v63
	v_div_scale_f32 v58, vcc, v65, v59, v65
	v_mul_f32_e32 v60, v58, v63
	v_fma_f32 v64, -v62, v60, v58
	v_fmac_f32_e32 v60, v64, v63
	v_fma_f32 v58, -v62, v60, v58
	v_mul_f32_e32 v62, 0xbfb8aa3b, v54
	v_exp_f32_e32 v62, v62
	v_div_fmas_f32 v58, v58, v63, v60
	v_div_fixup_f32 v58, v58, v59, v65
	v_mul_f32_e32 v58, v61, v58
	v_add_f32_e32 v59, 1.0, v62
	v_div_scale_f32 v60, s[0:1], v59, v59, v54
	v_rcp_f32_e32 v62, v60
	s_nop 0
	v_cvt_pk_bf16_f32 v58, v58, s0
	ds_write_b16 v0, v58 offset:432
	v_fma_f32 v58, -v60, v62, 1.0
	v_fmac_f32_e32 v62, v58, v62
	v_div_scale_f32 v58, vcc, v54, v59, v54
	v_mul_f32_e32 v61, v58, v62
	v_fma_f32 v63, -v60, v61, v58
	v_fmac_f32_e32 v61, v63, v62
	v_fma_f32 v58, -v60, v61, v58
	v_mul_f32_e32 v60, 0xbfb8aa3b, v55
	v_exp_f32_e32 v60, v60
	v_div_fmas_f32 v58, v58, v62, v61
	v_div_fixup_f32 v54, v58, v59, v54
	v_mul_f32_e32 v50, v50, v54
	v_add_f32_e32 v58, 1.0, v60
	v_div_scale_f32 v59, s[0:1], v58, v58, v55
	v_rcp_f32_e32 v60, v59
	s_nop 0
	v_cvt_pk_bf16_f32 v50, v50, s0
	ds_write_b16 v0, v50 offset:32
	v_fma_f32 v50, -v59, v60, 1.0
	v_fmac_f32_e32 v60, v50, v60
	v_div_scale_f32 v50, vcc, v55, v58, v55
	v_mul_f32_e32 v54, v50, v60
	v_fma_f32 v61, -v59, v54, v50
	v_fmac_f32_e32 v54, v61, v60
	v_fma_f32 v50, -v59, v54, v50
	v_mul_f32_e32 v59, 0xbfb8aa3b, v56
	v_exp_f32_e32 v59, v59
	v_div_fmas_f32 v50, v50, v60, v54
	v_div_fixup_f32 v50, v50, v58, v55
	v_mul_f32_e32 v50, v51, v50
	v_add_f32_e32 v54, 1.0, v59
	v_div_scale_f32 v55, s[0:1], v54, v54, v56
	v_rcp_f32_e32 v58, v55
	s_nop 0
	v_cvt_pk_bf16_f32 v50, v50, s0
	ds_write_b16 v0, v50 offset:176
	v_fma_f32 v50, -v55, v58, 1.0
	v_fmac_f32_e32 v58, v50, v58
	v_div_scale_f32 v50, vcc, v56, v54, v56
	v_mul_f32_e32 v51, v50, v58
	v_fma_f32 v59, -v55, v51, v50
	v_fmac_f32_e32 v51, v59, v58
	v_fma_f32 v50, -v55, v51, v50
	v_mul_f32_e32 v55, 0xbfb8aa3b, v57
	v_exp_f32_e32 v55, v55
	v_div_fmas_f32 v50, v50, v58, v51
	v_div_fixup_f32 v50, v50, v54, v56
	v_mul_f32_e32 v50, v52, v50
	v_add_f32_e32 v51, 1.0, v55
	v_div_scale_f32 v54, s[0:1], v51, v51, v57
	v_rcp_f32_e32 v55, v54
	s_nop 0
	v_cvt_pk_bf16_f32 v50, v50, s0
	ds_write_b16 v0, v50 offset:320
	v_fma_f32 v50, -v54, v55, 1.0
	v_fmac_f32_e32 v55, v50, v55
	v_div_scale_f32 v50, vcc, v57, v51, v57
	v_mul_f32_e32 v52, v50, v55
	v_fma_f32 v56, -v54, v52, v50
	v_fmac_f32_e32 v52, v56, v55
	v_fma_f32 v50, -v54, v52, v50
	v_mul_f32_e32 v54, 0xbfb8aa3b, v46
	v_exp_f32_e32 v54, v54
	v_div_fmas_f32 v50, v50, v55, v52
	v_div_fixup_f32 v50, v50, v51, v57
	v_mul_f32_e32 v50, v53, v50
	v_add_f32_e32 v51, 1.0, v54
	v_div_scale_f32 v52, s[0:1], v51, v51, v46
	v_rcp_f32_e32 v54, v52
	s_nop 0
	v_cvt_pk_bf16_f32 v50, v50, s0
	ds_write_b16 v0, v50 offset:464
	v_fma_f32 v50, -v52, v54, 1.0
	v_fmac_f32_e32 v54, v50, v54
	v_div_scale_f32 v50, vcc, v46, v51, v46
	v_mul_f32_e32 v53, v50, v54
	v_fma_f32 v55, -v52, v53, v50
	v_fmac_f32_e32 v53, v55, v54
	v_fma_f32 v50, -v52, v53, v50
	v_mul_f32_e32 v52, 0xbfb8aa3b, v47
	v_exp_f32_e32 v52, v52
	v_div_fmas_f32 v50, v50, v54, v53
	v_div_fixup_f32 v46, v50, v51, v46
	v_mul_f32_e32 v42, v42, v46
	v_add_f32_e32 v50, 1.0, v52
	v_div_scale_f32 v51, s[0:1], v50, v50, v47
	v_rcp_f32_e32 v52, v51
	s_nop 0
	v_cvt_pk_bf16_f32 v42, v42, s0
	ds_write_b16 v0, v42 offset:2304
	v_fma_f32 v42, -v51, v52, 1.0
	v_fmac_f32_e32 v52, v42, v52
	v_div_scale_f32 v42, vcc, v47, v50, v47
	v_mul_f32_e32 v46, v42, v52
	v_fma_f32 v53, -v51, v46, v42
	v_fmac_f32_e32 v46, v53, v52
	v_fma_f32 v42, -v51, v46, v42
	v_mul_f32_e32 v51, 0xbfb8aa3b, v48
; __device__ __forceinline__ u16 f2bf(float f) { return (u16)(pack2(f, 0.f) & 0xffffu); }
; __device__ __forceinline__ float silu_f(float x) { return x / (1.f + __expf(-x)); }
; __device__ __forceinline__ void phase_moe_up(const Params& p, int l, bool last, unsigned char* smem) {
;     ...
; #pragma unroll
;       for (int mi = 0; mi < 4; ++mi)
; #pragma unroll
;         for (int n2 = 0; n2 < 2; ++n2)
; #pragma unroll
;           for (int j = 0; j < 4; ++j) {
;             const int m = r0 + mi * 16 + j;
;             const int fl = (c0 >> 6) * 32 + n2 * 16 + (c0 & 15);
;             Ts[m * 72 + fl] = f2bf(silu_f(acc[mi][2 * n2][j]) * acc[mi][2 * n2 + 1][j]);
;           }
	v_exp_f32_e32 v51, v51
	v_div_fmas_f32 v42, v42, v52, v46
	v_div_fixup_f32 v42, v42, v50, v47
	v_mul_f32_e32 v42, v43, v42
	v_add_f32_e32 v46, 1.0, v51
	v_div_scale_f32 v47, s[0:1], v46, v46, v48
	v_rcp_f32_e32 v50, v47
	s_nop 0
	v_cvt_pk_bf16_f32 v42, v42, s0
	ds_write_b16 v0, v42 offset:2448
	v_fma_f32 v42, -v47, v50, 1.0
	v_fmac_f32_e32 v50, v42, v50
	v_div_scale_f32 v42, vcc, v48, v46, v48
	v_mul_f32_e32 v43, v42, v50
	v_fma_f32 v51, -v47, v43, v42
	v_fmac_f32_e32 v43, v51, v50
	v_fma_f32 v42, -v47, v43, v42
	v_mul_f32_e32 v47, 0xbfb8aa3b, v49
	v_exp_f32_e32 v47, v47
	v_div_fmas_f32 v42, v42, v50, v43
	v_div_fixup_f32 v42, v42, v46, v48
	v_mul_f32_e32 v42, v44, v42
	v_add_f32_e32 v43, 1.0, v47
	v_div_scale_f32 v46, s[0:1], v43, v43, v49
	v_rcp_f32_e32 v47, v46
	s_nop 0
	v_cvt_pk_bf16_f32 v42, v42, s0
	ds_write_b16 v0, v42 offset:2592
	v_fma_f32 v42, -v46, v47, 1.0
	v_fmac_f32_e32 v47, v42, v47
	v_div_scale_f32 v42, vcc, v49, v43, v49
	v_mul_f32_e32 v44, v42, v47
	v_fma_f32 v48, -v46, v44, v42
	v_fmac_f32_e32 v44, v48, v47
	v_fma_f32 v42, -v46, v44, v42
	v_mul_f32_e32 v46, 0xbfb8aa3b, v38
	v_exp_f32_e32 v46, v46
	v_div_fmas_f32 v42, v42, v47, v44
	v_div_fixup_f32 v42, v42, v43, v49
	v_mul_f32_e32 v42, v45, v42
	v_add_f32_e32 v43, 1.0, v46
	v_div_scale_f32 v44, s[0:1], v43, v43, v38
	v_rcp_f32_e32 v46, v44
	s_nop 0
	v_cvt_pk_bf16_f32 v42, v42, s0
	ds_write_b16 v0, v42 offset:2736
	v_fma_f32 v42, -v44, v46, 1.0
	v_fmac_f32_e32 v46, v42, v46
	v_div_scale_f32 v42, vcc, v38, v43, v38
	v_mul_f32_e32 v45, v42, v46
	v_fma_f32 v47, -v44, v45, v42
	v_fmac_f32_e32 v45, v47, v46
	v_fma_f32 v42, -v44, v45, v42
	v_mul_f32_e32 v44, 0xbfb8aa3b, v39
	v_exp_f32_e32 v44, v44
	v_div_fmas_f32 v42, v42, v46, v45
	v_div_fixup_f32 v38, v42, v43, v38
	v_mul_f32_e32 v34, v34, v38
	v_add_f32_e32 v42, 1.0, v44
	v_div_scale_f32 v43, s[0:1], v42, v42, v39
	v_rcp_f32_e32 v44, v43
	s_nop 0
	v_cvt_pk_bf16_f32 v34, v34, s0
	ds_write_b16 v0, v34 offset:2336
	v_fma_f32 v34, -v43, v44, 1.0
	v_fmac_f32_e32 v44, v34, v44
	v_div_scale_f32 v34, vcc, v39, v42, v39
	v_mul_f32_e32 v38, v34, v44
	v_fma_f32 v45, -v43, v38, v34
	v_fmac_f32_e32 v38, v45, v44
	v_fma_f32 v34, -v43, v38, v34
	v_mul_f32_e32 v43, 0xbfb8aa3b, v40
	v_exp_f32_e32 v43, v43
	v_div_fmas_f32 v34, v34, v44, v38
	v_div_fixup_f32 v34, v34, v42, v39
	v_mul_f32_e32 v34, v35, v34
	v_add_f32_e32 v38, 1.0, v43
	v_div_scale_f32 v39, s[0:1], v38, v38, v40
	v_rcp_f32_e32 v42, v39
	s_nop 0
	v_cvt_pk_bf16_f32 v34, v34, s0
	ds_write_b16 v0, v34 offset:2480
	v_fma_f32 v34, -v39, v42, 1.0
	v_fmac_f32_e32 v42, v34, v42
	v_div_scale_f32 v34, vcc, v40, v38, v40
	v_mul_f32_e32 v35, v34, v42
	v_fma_f32 v43, -v39, v35, v34
	v_fmac_f32_e32 v35, v43, v42
	v_fma_f32 v34, -v39, v35, v34
	v_mul_f32_e32 v39, 0xbfb8aa3b, v41
	v_exp_f32_e32 v39, v39
	v_div_fmas_f32 v34, v34, v42, v35
	v_div_fixup_f32 v34, v34, v38, v40
	v_mul_f32_e32 v34, v36, v34
	v_add_f32_e32 v35, 1.0, v39
	v_div_scale_f32 v38, s[0:1], v35, v35, v41
	v_rcp_f32_e32 v39, v38
	s_nop 0
	v_cvt_pk_bf16_f32 v34, v34, s0
	ds_write_b16 v0, v34 offset:2624
	v_fma_f32 v34, -v38, v39, 1.0
	v_fmac_f32_e32 v39, v34, v39
	v_div_scale_f32 v34, vcc, v41, v35, v41
	v_mul_f32_e32 v36, v34, v39
	v_fma_f32 v40, -v38, v36, v34
	v_fmac_f32_e32 v36, v40, v39
	v_fma_f32 v34, -v38, v36, v34
	v_mul_f32_e32 v38, 0xbfb8aa3b, v30
	v_exp_f32_e32 v38, v38
	v_div_fmas_f32 v34, v34, v39, v36
	v_div_fixup_f32 v34, v34, v35, v41
	v_mul_f32_e32 v34, v37, v34
	v_add_f32_e32 v35, 1.0, v38
	v_div_scale_f32 v36, s[0:1], v35, v35, v30
	v_rcp_f32_e32 v38, v36
	s_nop 0
	v_cvt_pk_bf16_f32 v34, v34, s0
	ds_write_b16 v0, v34 offset:2768
	v_fma_f32 v34, -v36, v38, 1.0
	v_fmac_f32_e32 v38, v34, v38
	v_div_scale_f32 v34, vcc, v30, v35, v30
	v_mul_f32_e32 v37, v34, v38
	v_fma_f32 v39, -v36, v37, v34
	v_fmac_f32_e32 v37, v39, v38
	v_fma_f32 v34, -v36, v37, v34
	v_mul_f32_e32 v36, 0xbfb8aa3b, v31
	v_exp_f32_e32 v36, v36
	v_div_fmas_f32 v34, v34, v38, v37
	v_div_fixup_f32 v30, v34, v35, v30
	v_mul_f32_e32 v26, v26, v30
	v_add_f32_e32 v34, 1.0, v36
	v_div_scale_f32 v35, s[0:1], v34, v34, v31
	v_rcp_f32_e32 v36, v35
	s_nop 0
	v_cvt_pk_bf16_f32 v26, v26, s0
	ds_write_b16 v0, v26 offset:4608
	v_fma_f32 v26, -v35, v36, 1.0
	v_fmac_f32_e32 v36, v26, v36
	v_div_scale_f32 v26, vcc, v31, v34, v31
	v_mul_f32_e32 v30, v26, v36
	v_fma_f32 v37, -v35, v30, v26
	v_fmac_f32_e32 v30, v37, v36
	v_fma_f32 v26, -v35, v30, v26
	v_mul_f32_e32 v35, 0xbfb8aa3b, v32
	v_exp_f32_e32 v35, v35
	v_div_fmas_f32 v26, v26, v36, v30
	v_div_fixup_f32 v26, v26, v34, v31
	v_mul_f32_e32 v26, v27, v26
	v_add_f32_e32 v30, 1.0, v35
	v_div_scale_f32 v31, s[0:1], v30, v30, v32
	v_rcp_f32_e32 v34, v31
	s_nop 0
	v_cvt_pk_bf16_f32 v26, v26, s0
	ds_write_b16 v0, v26 offset:4752
	v_fma_f32 v26, -v31, v34, 1.0
	v_fmac_f32_e32 v34, v26, v34
	v_div_scale_f32 v26, vcc, v32, v30, v32
	v_mul_f32_e32 v27, v26, v34
	v_fma_f32 v35, -v31, v27, v26
	v_fmac_f32_e32 v27, v35, v34
	v_fma_f32 v26, -v31, v27, v26
	v_mul_f32_e32 v31, 0xbfb8aa3b, v33
	v_exp_f32_e32 v31, v31
	v_div_fmas_f32 v26, v26, v34, v27
	v_div_fixup_f32 v26, v26, v30, v32
	v_mul_f32_e32 v26, v28, v26
	v_add_f32_e32 v27, 1.0, v31
	v_div_scale_f32 v30, s[0:1], v27, v27, v33
	v_rcp_f32_e32 v31, v30
	s_nop 0
	v_cvt_pk_bf16_f32 v26, v26, s0
	ds_write_b16 v0, v26 offset:4896
	v_fma_f32 v26, -v30, v31, 1.0
	v_fmac_f32_e32 v31, v26, v31
	v_div_scale_f32 v26, vcc, v33, v27, v33
	v_mul_f32_e32 v28, v26, v31
	v_fma_f32 v32, -v30, v28, v26
	v_fmac_f32_e32 v28, v32, v31
	v_fma_f32 v26, -v30, v28, v26
	v_mul_f32_e32 v30, 0xbfb8aa3b, v22
	v_exp_f32_e32 v30, v30
	v_div_fmas_f32 v26, v26, v31, v28
	v_div_fixup_f32 v26, v26, v27, v33
; __device__ __forceinline__ u16 f2bf(float f) { return (u16)(pack2(f, 0.f) & 0xffffu); }
; __device__ __forceinline__ float silu_f(float x) { return x / (1.f + __expf(-x)); }
; __device__ __forceinline__ void phase_moe_up(const Params& p, int l, bool last, unsigned char* smem) {
;     ...
; #pragma unroll
;       for (int mi = 0; mi < 4; ++mi)
; #pragma unroll
;         for (int n2 = 0; n2 < 2; ++n2)
; #pragma unroll
;           for (int j = 0; j < 4; ++j) {
;             const int m = r0 + mi * 16 + j;
;             const int fl = (c0 >> 6) * 32 + n2 * 16 + (c0 & 15);
;             Ts[m * 72 + fl] = f2bf(silu_f(acc[mi][2 * n2][j]) * acc[mi][2 * n2 + 1][j]);
;           }
;       __syncthreads();
	v_mul_f32_e32 v26, v29, v26
	v_add_f32_e32 v27, 1.0, v30
	v_div_scale_f32 v28, s[0:1], v27, v27, v22
	v_rcp_f32_e32 v30, v28
	s_nop 0
	v_cvt_pk_bf16_f32 v26, v26, s0
	ds_write_b16 v0, v26 offset:5040
	v_fma_f32 v26, -v28, v30, 1.0
	v_fmac_f32_e32 v30, v26, v30
	v_div_scale_f32 v26, vcc, v22, v27, v22
	v_mul_f32_e32 v29, v26, v30
	v_fma_f32 v31, -v28, v29, v26
	v_fmac_f32_e32 v29, v31, v30
	v_fma_f32 v26, -v28, v29, v26
	v_mul_f32_e32 v28, 0xbfb8aa3b, v23
	v_exp_f32_e32 v28, v28
	v_div_fmas_f32 v26, v26, v30, v29
	v_div_fixup_f32 v22, v26, v27, v22
	v_mul_f32_e32 v18, v18, v22
	v_add_f32_e32 v26, 1.0, v28
	v_div_scale_f32 v27, s[0:1], v26, v26, v23
	v_rcp_f32_e32 v28, v27
	s_nop 0
	v_cvt_pk_bf16_f32 v18, v18, s0
	ds_write_b16 v0, v18 offset:4640
	v_fma_f32 v18, -v27, v28, 1.0
	v_fmac_f32_e32 v28, v18, v28
	v_div_scale_f32 v18, vcc, v23, v26, v23
	v_mul_f32_e32 v22, v18, v28
	v_fma_f32 v29, -v27, v22, v18
	v_fmac_f32_e32 v22, v29, v28
	v_fma_f32 v18, -v27, v22, v18
	v_mul_f32_e32 v27, 0xbfb8aa3b, v24
	v_exp_f32_e32 v27, v27
	v_div_fmas_f32 v18, v18, v28, v22
	v_div_fixup_f32 v18, v18, v26, v23
	v_mul_f32_e32 v18, v19, v18
	v_add_f32_e32 v22, 1.0, v27
	v_div_scale_f32 v23, s[0:1], v22, v22, v24
	v_rcp_f32_e32 v26, v23
	s_nop 0
	v_cvt_pk_bf16_f32 v18, v18, s0
	ds_write_b16 v0, v18 offset:4784
	v_fma_f32 v18, -v23, v26, 1.0
	v_fmac_f32_e32 v26, v18, v26
	v_div_scale_f32 v18, vcc, v24, v22, v24
	v_mul_f32_e32 v19, v18, v26
	v_fma_f32 v27, -v23, v19, v18
	v_fmac_f32_e32 v19, v27, v26
	v_fma_f32 v18, -v23, v19, v18
	v_mul_f32_e32 v23, 0xbfb8aa3b, v25
	v_exp_f32_e32 v23, v23
	v_div_fmas_f32 v18, v18, v26, v19
	v_div_fixup_f32 v18, v18, v22, v24
	v_mul_f32_e32 v18, v20, v18
	v_add_f32_e32 v19, 1.0, v23
	v_div_scale_f32 v22, s[0:1], v19, v19, v25
	v_rcp_f32_e32 v23, v22
	s_nop 0
	v_cvt_pk_bf16_f32 v18, v18, s0
	ds_write_b16 v0, v18 offset:4928
	v_fma_f32 v18, -v22, v23, 1.0
	v_fmac_f32_e32 v23, v18, v23
	v_div_scale_f32 v18, vcc, v25, v19, v25
	v_mul_f32_e32 v20, v18, v23
	v_fma_f32 v24, -v22, v20, v18
	v_fmac_f32_e32 v20, v24, v23
	v_fma_f32 v18, -v22, v20, v18
	v_mul_f32_e32 v22, 0xbfb8aa3b, v14
	v_exp_f32_e32 v22, v22
	v_div_fmas_f32 v18, v18, v23, v20
	v_div_fixup_f32 v18, v18, v19, v25
	v_mul_f32_e32 v18, v21, v18
	v_add_f32_e32 v19, 1.0, v22
	v_div_scale_f32 v20, s[0:1], v19, v19, v14
	v_rcp_f32_e32 v22, v20
	s_nop 0
	v_cvt_pk_bf16_f32 v18, v18, s0
	ds_write_b16 v0, v18 offset:5072
	v_fma_f32 v18, -v20, v22, 1.0
	v_fmac_f32_e32 v22, v18, v22
	v_div_scale_f32 v18, vcc, v14, v19, v14
	v_mul_f32_e32 v21, v18, v22
	v_fma_f32 v23, -v20, v21, v18
	v_fmac_f32_e32 v21, v23, v22
	v_fma_f32 v18, -v20, v21, v18
	v_mul_f32_e32 v20, 0xbfb8aa3b, v15
	v_exp_f32_e32 v20, v20
	v_div_fmas_f32 v18, v18, v22, v21
	v_div_fixup_f32 v14, v18, v19, v14
	v_mul_f32_e32 v10, v10, v14
	v_add_f32_e32 v18, 1.0, v20
	v_div_scale_f32 v19, s[0:1], v18, v18, v15
	v_rcp_f32_e32 v20, v19
	s_nop 0
	v_cvt_pk_bf16_f32 v10, v10, s0
	ds_write_b16 v0, v10 offset:6912
	v_fma_f32 v10, -v19, v20, 1.0
	v_fmac_f32_e32 v20, v10, v20
	v_div_scale_f32 v10, vcc, v15, v18, v15
	v_mul_f32_e32 v14, v10, v20
	v_fma_f32 v21, -v19, v14, v10
	v_fmac_f32_e32 v14, v21, v20
	v_fma_f32 v10, -v19, v14, v10
	v_mul_f32_e32 v19, 0xbfb8aa3b, v16
	v_exp_f32_e32 v19, v19
	v_div_fmas_f32 v10, v10, v20, v14
	v_div_fixup_f32 v10, v10, v18, v15
	v_mul_f32_e32 v10, v11, v10
	v_add_f32_e32 v14, 1.0, v19
	v_div_scale_f32 v15, s[0:1], v14, v14, v16
	v_rcp_f32_e32 v18, v15
	s_nop 0
	v_cvt_pk_bf16_f32 v10, v10, s0
	ds_write_b16 v0, v10 offset:7056
	v_fma_f32 v10, -v15, v18, 1.0
	v_fmac_f32_e32 v18, v10, v18
	v_div_scale_f32 v10, vcc, v16, v14, v16
	v_mul_f32_e32 v11, v10, v18
	v_fma_f32 v19, -v15, v11, v10
	v_fmac_f32_e32 v11, v19, v18
	v_fma_f32 v10, -v15, v11, v10
	v_mul_f32_e32 v15, 0xbfb8aa3b, v17
	v_exp_f32_e32 v15, v15
	v_div_fmas_f32 v10, v10, v18, v11
	v_div_fixup_f32 v10, v10, v14, v16
	v_mul_f32_e32 v10, v12, v10
	v_add_f32_e32 v11, 1.0, v15
	v_div_scale_f32 v14, s[0:1], v11, v11, v17
	v_rcp_f32_e32 v15, v14
	s_nop 0
	v_cvt_pk_bf16_f32 v10, v10, s0
	ds_write_b16 v0, v10 offset:7200
	v_fma_f32 v10, -v14, v15, 1.0
	v_fmac_f32_e32 v15, v10, v15
	v_div_scale_f32 v10, vcc, v17, v11, v17
	v_mul_f32_e32 v12, v10, v15
	v_fma_f32 v16, -v14, v12, v10
	v_fmac_f32_e32 v12, v16, v15
	v_fma_f32 v10, -v14, v12, v10
	v_mul_f32_e32 v14, 0xbfb8aa3b, v6
	v_exp_f32_e32 v14, v14
	v_div_fmas_f32 v10, v10, v15, v12
	v_div_fixup_f32 v10, v10, v11, v17
	v_mul_f32_e32 v10, v13, v10
	v_add_f32_e32 v11, 1.0, v14
	v_div_scale_f32 v12, s[0:1], v11, v11, v6
	v_rcp_f32_e32 v14, v12
	s_nop 0
	v_cvt_pk_bf16_f32 v10, v10, s0
	ds_write_b16 v0, v10 offset:7344
	v_fma_f32 v10, -v12, v14, 1.0
	v_fmac_f32_e32 v14, v10, v14
	v_div_scale_f32 v10, vcc, v6, v11, v6
	v_mul_f32_e32 v13, v10, v14
	v_fma_f32 v15, -v12, v13, v10
	v_fmac_f32_e32 v13, v15, v14
	v_fma_f32 v10, -v12, v13, v10
	v_mul_f32_e32 v12, 0xbfb8aa3b, v7
	v_exp_f32_e32 v12, v12
	v_div_fmas_f32 v10, v10, v14, v13
	v_div_fixup_f32 v6, v10, v11, v6
	v_mul_f32_e32 v2, v2, v6
	v_add_f32_e32 v10, 1.0, v12
	v_div_scale_f32 v11, s[0:1], v10, v10, v7
	v_rcp_f32_e32 v12, v11
	s_nop 0
	v_cvt_pk_bf16_f32 v2, v2, s0
	ds_write_b16 v0, v2 offset:6944
	v_fma_f32 v2, -v11, v12, 1.0
	v_fmac_f32_e32 v12, v2, v12
	v_div_scale_f32 v2, vcc, v7, v10, v7
	v_mul_f32_e32 v6, v2, v12
	v_fma_f32 v13, -v11, v6, v2
	v_fmac_f32_e32 v6, v13, v12
	v_fma_f32 v2, -v11, v6, v2
	v_mul_f32_e32 v11, 0xbfb8aa3b, v8
	v_exp_f32_e32 v11, v11
	v_div_fmas_f32 v2, v2, v12, v6
	v_div_fixup_f32 v2, v2, v10, v7
	v_mul_f32_e32 v2, v3, v2
	v_add_f32_e32 v6, 1.0, v11
	v_div_scale_f32 v7, s[0:1], v6, v6, v8
	v_rcp_f32_e32 v10, v7
	s_nop 0
	v_cvt_pk_bf16_f32 v2, v2, s0
	ds_write_b16 v0, v2 offset:7088
	v_fma_f32 v2, -v7, v10, 1.0
	v_fmac_f32_e32 v10, v2, v10
	v_div_scale_f32 v2, vcc, v8, v6, v8
	v_mul_f32_e32 v3, v2, v10
	v_fma_f32 v11, -v7, v3, v2
	v_fmac_f32_e32 v3, v11, v10
	v_fma_f32 v2, -v7, v3, v2
	v_mul_f32_e32 v7, 0xbfb8aa3b, v9
	v_exp_f32_e32 v7, v7
	v_div_fmas_f32 v2, v2, v10, v3
	v_div_fixup_f32 v2, v2, v6, v8
	v_mul_f32_e32 v2, v4, v2
	v_add_f32_e32 v3, 1.0, v7
	v_div_scale_f32 v6, s[0:1], v3, v3, v9
	v_rcp_f32_e32 v7, v6
	s_nop 0
	v_cvt_pk_bf16_f32 v2, v2, s0
	ds_write_b16 v0, v2 offset:7232
	v_fma_f32 v2, -v6, v7, 1.0
	v_fmac_f32_e32 v7, v2, v7
	v_div_scale_f32 v2, vcc, v9, v3, v9
	v_mul_f32_e32 v4, v2, v7
	v_fma_f32 v8, -v6, v4, v2
	v_fmac_f32_e32 v4, v8, v7
	v_fma_f32 v2, -v6, v4, v2
	v_div_fmas_f32 v2, v2, v7, v4
	v_div_fixup_f32 v2, v2, v3, v9
	v_mul_f32_e32 v2, v5, v2
	v_cvt_pk_bf16_f32 v2, v2, s0
	ds_write_b16 v0, v2 offset:7376
	v_lshlrev_b32_e32 v0, 3, v66
	v_and_b32_e32 v0, 56, v0
	v_ashrrev_i32_e32 v3, 3, v66
	v_lshlrev_b32_e32 v2, 1, v0
	v_cmp_gt_i32_e32 vcc, s86, v3
	s_waitcnt lgkmcnt(0)
	s_barrier
; __device__ __forceinline__ void phase_moe_up(const Params& p, int l, bool last, unsigned char* smem) {
;     ...
;       __syncthreads();
; #pragma unroll
;       for (int i = 0; i < 4; ++i) {
;         const int c = t2 + 256 * i, row = c >> 3, ch = c & 7;
;         if (row < mvalid) *(u32x4*)(p.HID + (size_t)(hid_row + row) * 512 + nt * 64 + ch * 8) = *(const u32x4*)(Ts + row * 72 + ch * 8);
	s_and_saveexec_b64 s[0:1], vcc
	s_xor_b64 s[0:1], exec, s[0:1]
	s_cbranch_execz .LBB0_1196
	v_mov_b64_e32 v[4:5], s[4:5]
	s_load_dwordx2 s[100:101], s[4:5], 0x170
	s_waitcnt lgkmcnt(0)
	v_mov_b32_e32 v8, s100
	v_mov_b32_e32 v9, s101
	v_mad_u64_u32 v[4:5], s[40:41], v3, s96, v[2:3]
	v_add_u32_e32 v10, s82, v3
	ds_read_b128 v[4:7], v4
	v_ashrrev_i32_e32 v11, 31, v10
	v_lshlrev_b64 v[10:11], 10, v[10:11]
	s_lshl_b32 s94, s83, 7
	v_mov_b32_e32 v3, v1
	s_waitcnt lgkmcnt(0)
	v_lshl_add_u64 v[8:9], v[8:9], 0, v[10:11]
	v_lshl_add_u64 v[8:9], v[8:9], 0, s[94:95]
	v_lshl_add_u64 v[8:9], v[8:9], 0, v[2:3]
	global_store_dwordx4 v[8:9], v[4:7], off
.LBB0_1196:
	s_or_b64 exec, exec, s[0:1]
	v_add_u32_e32 v3, 0x100, v66
	v_ashrrev_i32_e32 v3, 3, v3
	v_cmp_gt_i32_e32 vcc, s86, v3
	s_and_saveexec_b64 s[0:1], vcc
	s_cbranch_execz .LBB0_1198
	v_mov_b64_e32 v[4:5], s[4:5]
	s_load_dwordx2 s[100:101], s[4:5], 0x170
	s_waitcnt lgkmcnt(0)
	v_mov_b32_e32 v8, s100
	v_mov_b32_e32 v9, s101
	v_mad_u64_u32 v[4:5], s[40:41], v3, s96, v[2:3]
	v_add_u32_e32 v10, s82, v3
	ds_read_b128 v[4:7], v4
	v_ashrrev_i32_e32 v11, 31, v10
	v_lshlrev_b64 v[10:11], 10, v[10:11]
	s_lshl_b32 s94, s83, 7
	v_mov_b32_e32 v3, v1
	s_waitcnt lgkmcnt(0)
	v_lshl_add_u64 v[8:9], v[8:9], 0, v[10:11]
	v_lshl_add_u64 v[8:9], v[8:9], 0, s[94:95]
	v_lshl_add_u64 v[8:9], v[8:9], 0, v[2:3]
	global_store_dwordx4 v[8:9], v[4:7], off
.LBB0_1198:
	s_or_b64 exec, exec, s[0:1]
	v_add_u32_e32 v3, 0x200, v66
	v_ashrrev_i32_e32 v3, 3, v3
	v_cmp_gt_i32_e32 vcc, s86, v3
	s_and_saveexec_b64 s[0:1], vcc
	s_cbranch_execz .LBB0_1200
	v_mov_b64_e32 v[4:5], s[4:5]
	s_load_dwordx2 s[100:101], s[4:5], 0x170
	s_waitcnt lgkmcnt(0)
	v_mov_b32_e32 v8, s100
	v_mov_b32_e32 v9, s101
	v_mad_u64_u32 v[4:5], s[40:41], v3, s96, v[2:3]
	v_add_u32_e32 v10, s82, v3
	ds_read_b128 v[4:7], v4
	v_ashrrev_i32_e32 v11, 31, v10
	v_lshlrev_b64 v[10:11], 10, v[10:11]
	s_lshl_b32 s94, s83, 7
	v_mov_b32_e32 v3, v1
	s_waitcnt lgkmcnt(0)
	v_lshl_add_u64 v[8:9], v[8:9], 0, v[10:11]
	v_lshl_add_u64 v[8:9], v[8:9], 0, s[94:95]
	v_lshl_add_u64 v[2:3], v[8:9], 0, v[2:3]
	global_store_dwordx4 v[2:3], v[4:7], off

; __device__ __forceinline__ void phase_moe_up(const Params& p, int l, bool last, unsigned char* smem) {
;     ...
;       __syncthreads();
; #pragma unroll
;       for (int i = 0; i < 4; ++i) {
;         const int c = t2 + 256 * i, row = c >> 3, ch = c & 7;
;         if (row < mvalid) *(u32x4*)(p.HID + (size_t)(hid_row + row) * 512 + nt * 64 + ch * 8) = *(const u32x4*)(Ts + row * 72 + ch * 8);
.LBB0_1202:
	v_mov_b64_e32 v[4:5], s[4:5]
	s_load_dwordx2 s[100:101], s[4:5], 0x170
	s_waitcnt lgkmcnt(0)
	v_mov_b32_e32 v6, s100
	v_mov_b32_e32 v7, s101
	v_mul_lo_u32 v3, v2, s96
	v_add_u32_e32 v8, s82, v2
	v_lshl_add_u32 v2, v0, 1, v3
	v_ashrrev_i32_e32 v9, 31, v8
	ds_read_b128 v[2:5], v2
	v_lshlrev_b64 v[8:9], 10, v[8:9]
	s_lshl_b32 s94, s83, 7
	s_waitcnt lgkmcnt(0)
	v_lshl_add_u64 v[6:7], v[6:7], 0, v[8:9]
	v_lshl_add_u64 v[6:7], v[6:7], 0, s[94:95]
	v_lshl_add_u64 v[6:7], v[0:1], 1, v[6:7]
	global_store_dwordx4 v[6:7], v[2:5], off
	s_branch .LBB0_1102
